# ssq-loads hoisted in P1/P4 epilogues + G1 quota 4000/G3 7500
# speedup vs baseline: 1.0253x; 1.0253x over previous
; #define PG8_LAS __attribute__((address_space(3)))
; #define LAS __attribute__((address_space(3)))
; #define GRID_BAR() xcd_barrier(bar)
; __global__ void __launch_bounds__(NWAVES * 64, 2) fwd_kernel(Args A) {
;     ...
;     unsigned char* ws = A.ws;
;     bf16* XB = (bf16*)(ws + WS_XN); ss_t* SS = (ss_t*)(ws + WS_SS); bf16* Z = (bf16*)(ws + WS_Z); bf16* MIX = (bf16*)(ws + WS_MIX); bf16* ACT = (bf16*)(ws + WS_ACT);
;     float* X = A.out;
;     PG8_LAS unsigned char* ldsl = (PG8_LAS unsigned char*)lds;
;     volatile LAS unsigned* bst = (volatile LAS unsigned*)(ldsl + LDS_BYTES - 16);
;     if (threadIdx.x < 4) bst[threadIdx.x] = 0u;
;     __syncthreads();
;     unsigned* barw = (unsigned*)(ws + WS_CTL);
;     XcdBarrier bar; bar.bar = barw; bar.st = bst; bar.x = xb_xcc_id();
;     if (threadIdx.x == 0) bst[2] = xb_add(&barw[XB_XCNT(bar.x)], 1u);
;     __syncthreads();
;     const unsigned my_x = bar.x, my_r = (unsigned)__builtin_amdgcn_readfirstlane((int)bst[2]);
;     ...
;     {
;         PHASE_IDS();
;         float* scr = (float*)(lds + wid * TSCR);
;         const bool lazy = (G == 256);
;         convert_items(A, ws, 0, lazy ? Q_P : N_ALL, gw, NGW, scr, lane);
;         prologue_rows(A.x, XB, SS + (size_t)SS_Q1 * SEQ, gw, NGW, lane);
;     }
;     if (A.never) grid.sync();
;     GRID_BAR();
;     bool tp = (G == 256);
;     if (tp) { for (unsigned q = 0; q < 16; ++q) { const unsigned c = xb_ld(&barw[XB_XCNT(q)]); tp = tp && (c == (q < 8 ? 32u : 0u)); } }
;     tp = __builtin_amdgcn_readfirstlane((int)tp) != 0;
;     const int vc = tp ? (int)(my_r * 8u + my_x) : bx;
;     ...
; #pragma nounroll
;     for (int l = 0; l < DEPTH; ++l) {
;         { pg8::Gemm g{XB, (const bf16*)(ws + WS_WIN + l * SZ_WIN), SEQ, INW, DM};
;           pg8::EpiZ E{Z, INW, 8, SS + (size_t)(SS_Q1 + l) * SEQ};
;           if (G == 256) { pg8::OrderTok S{vc, INW / 256, 0}; pg8::gemm_phase<pg8::EpiZ, pg8::OrderTok, true, true>(ldsl, g, S, E); }
;           else { pg8::StaticOrder S; S.init(SEQ, INW, G, bx); pg8::gemm_phase<pg8::EpiZ, pg8::StaticOrder, true, true>(ldsl, g, S, E); } }
;         if (G == 256 && vc >= 192) {
;             PHASE_IDS(); const int g0 = Q_P + l * (Q_G1 + Q_G3), g1 = g0 + Q_G1;
;             convert_items(A, ws, g0 < N_ALL ? g0 : N_ALL, g1 < N_ALL ? g1 : N_ALL, (vc - 192) * NWAVES + wid, 64 * NWAVES, (float*)(lds + wid * TSCR), lane); }
;         GRID_BAR();
;         { PHASE_IDS();
.LBB0_111:
	s_add_u32 s64, s86, 0x16200000
	s_addc_u32 s65, s87, 0
	s_add_u32 s80, s86, 0x10000
	s_addc_u32 s2, s87, 0
	s_add_u32 s82, s86, 0x18200000
	s_addc_u32 s83, s87, 0
	s_add_u32 s18, s86, 0x1ba00000
	s_addc_u32 s19, s87, 0
	s_add_u32 s20, s86, 0x1da00000
	v_cndmask_b32_e64 v0, 0, 1, s[0:1]
	s_addc_u32 s21, s87, 0
	v_readfirstlane_b32 s0, v0
	s_lshl_b32 s1, s33, 3
	s_and_b32 s0, 1, s0
	s_add_i32 s4, s1, s17
	s_cmp_eq_u32 s0, 1
	v_writelane_b32 v250, s2, 46
	s_cselect_b64 s[0:1], -1, 0
	s_and_b64 s[2:3], s[0:1], exec
	v_readlane_b32 s28, v250, 0
	s_cselect_b32 s3, s4, s28
	s_xor_b64 s[0:1], s[0:1], -1
	v_writelane_b32 v250, s0, 47
	v_mov_b32_e32 v2, 0
	v_mov_b32_e32 v205, 0x358637bd
	v_writelane_b32 v250, s1, 48
	s_add_u32 s0, s86, 0x200000
	v_writelane_b32 v250, s0, 49
	s_addc_u32 s0, s87, 0
	s_cmpk_lt_i32 s28, 0x1c0
	v_writelane_b32 v250, s0, 50
	s_cselect_b64 s[0:1], -1, 0
	v_writelane_b32 v250, s0, 51
	s_bfe_u32 s4, s3, 0x20003
	s_ashr_i32 s22, s3, 5
	v_writelane_b32 v250, s1, 52
	s_ashr_i32 s0, s28, 31
	v_writelane_b32 v250, s0, 53
	s_lshr_b32 s0, s0, 29
	s_add_i32 s0, s28, s0
	s_ashr_i32 s5, s0, 3
	s_and_b32 s0, s0, -8
	s_sub_i32 s6, s28, s0
	s_ashr_i32 s0, s84, 31
	v_writelane_b32 v250, s0, 54
	s_lshl_b32 s0, s3, 2
	s_and_b32 s0, s0, 28
	s_or_b32 s7, s0, s4
	s_cmp_lt_i32 s22, 14
	s_cselect_b64 s[0:1], -1, 0
	s_ashr_i32 s23, s22, 31
	v_writelane_b32 v250, s0, 55
	s_lshl_b32 s10, s7, 20
	s_lshl_b64 s[24:25], s[22:23], 20
	v_writelane_b32 v250, s1, 56
	s_add_u32 s0, s64, s10
	s_addc_u32 s1, s65, 0
	s_add_u32 s8, s0, 0x80000
	s_addc_u32 s9, s1, 0
	s_lshl_b32 s2, s7, 8
	v_writelane_b32 v250, s8, 57
	s_cmpk_gt_i32 s3, 0xbf
	s_mul_i32 s7, s7, 0x2c0000
	v_writelane_b32 v250, s9, 58
	s_cselect_b64 s[8:9], -1, 0
	v_writelane_b32 v250, s2, 59
	s_and_b64 s[8:9], s[30:31], s[8:9]
	v_writelane_b32 v250, s8, 60
	s_lshl_b32 s11, s3, 3
	s_add_i32 s2, s11, 0xf7c
	v_writelane_b32 v250, s9, 61
	v_writelane_b32 v250, s2, 62
	s_add_u32 s2, s86, 0x10a00000
	v_writelane_b32 v250, s2, 63
	s_addc_u32 s2, s87, 0
	v_writelane_b32 v249, s2, 0
	s_add_u32 s2, s86, 0x5a00000
	v_writelane_b32 v249, s2, 1
	s_addc_u32 s2, s87, 0
	v_writelane_b32 v249, s2, 2
	s_add_u32 s2, s86, 0x3a00000
	v_writelane_b32 v249, s2, 3
	s_addc_u32 s2, s87, 0
	s_cmp_lg_u64 s[78:79], 0
	v_writelane_b32 v249, s2, 4
	s_cselect_b64 s[8:9], -1, 0
	v_writelane_b32 v249, s8, 5
	s_cmp_lg_u64 s[44:45], 0
	v_mov_b32_e32 v206, 0x260
	v_writelane_b32 v249, s9, 6
	s_cselect_b64 s[8:9], -1, 0
	v_writelane_b32 v249, s8, 7
	v_mov_b32_e32 v207, 1
	v_mbcnt_hi_u32_b32 v208, -1, v40
	v_writelane_b32 v249, s9, 8
	s_add_u32 s8, s86, 0x200
	s_addc_u32 s9, s87, 0
	v_writelane_b32 v249, s8, 9
	v_mov_b64_e32 v[160:161], 0x1c0
	v_mov_b64_e32 v[162:163], 0x1bf
	v_writelane_b32 v249, s9, 10
	s_add_u32 s8, s86, 0x1000
	s_addc_u32 s9, s87, 0
	v_writelane_b32 v249, s8, 11
	v_mov_b32_e32 v209, 0x41b17218
	v_mov_b32_e32 v210, 0x1a00
	v_writelane_b32 v249, s9, 12
	s_add_u32 s8, s86, 0x1100
	s_addc_u32 s9, s87, 0
	v_writelane_b32 v249, s8, 13
	v_mov_b32_e32 v211, 0x1800
	v_mov_b64_e32 v[164:165], 0x100
	v_writelane_b32 v249, s9, 14
	s_add_u32 s8, s86, 0x1200
	s_addc_u32 s9, s87, 0
	v_writelane_b32 v249, s8, 15
	v_mov_b64_e32 v[166:167], 0xff
	v_mov_b64_e32 v[168:169], 0x580
	v_writelane_b32 v249, s9, 16
	s_add_u32 s8, s86, 0x1300
	s_addc_u32 s9, s87, 0
	v_writelane_b32 v249, s8, 17
	s_cmp_eq_u32 s17, 15
	v_mov_b64_e32 v[170:171], 0x57f
	v_writelane_b32 v249, s9, 18
	s_cselect_b64 s[8:9], -1, 0
	v_writelane_b32 v249, s8, 19
	s_cmp_eq_u32 s17, 14
	s_mov_b32 s97, 0xf800000
	v_writelane_b32 v249, s9, 20
	s_cselect_b64 s[8:9], -1, 0
	v_writelane_b32 v249, s8, 21
	s_cmp_eq_u32 s17, 13
	s_movk_i32 s33, 0x90
	v_writelane_b32 v249, s9, 22
	s_cselect_b64 s[8:9], -1, 0
	v_writelane_b32 v249, s8, 23
	s_cmp_eq_u32 s17, 12
	s_mov_b32 s72, 0x3e38aa3b
	v_writelane_b32 v249, s9, 24
	s_cselect_b64 s[8:9], -1, 0
	v_writelane_b32 v249, s8, 25
	s_cmp_eq_u32 s17, 11
	s_mov_b32 s54, 0
	v_writelane_b32 v249, s9, 26
	s_cselect_b64 s[8:9], -1, 0
	v_writelane_b32 v249, s8, 27
	s_cmp_eq_u32 s17, 10
	s_mov_b32 s77, 0
	v_writelane_b32 v249, s9, 28
	s_cselect_b64 s[8:9], -1, 0
	v_writelane_b32 v249, s8, 29
	s_cmp_eq_u32 s17, 9
	s_mov_b32 s90, 0x3e6d3388
	v_writelane_b32 v249, s9, 30
	s_cselect_b64 s[8:9], -1, 0
	v_writelane_b32 v249, s8, 31
	s_cmp_eq_u32 s17, 8
	s_mov_b32 s92, 0x3f07dc22
	v_writelane_b32 v249, s9, 32
	s_cselect_b64 s[8:9], -1, 0
	v_writelane_b32 v249, s8, 33
	s_cmp_eq_u32 s17, 7
	s_mov_b32 s94, 0x3f35f0e3
	v_writelane_b32 v249, s9, 34
	s_cselect_b64 s[8:9], -1, 0
	v_writelane_b32 v249, s8, 35
	s_cmp_eq_u32 s17, 6
	s_mov_b32 s96, 0xbe11a98e
	v_writelane_b32 v249, s9, 36
	s_cselect_b64 s[8:9], -1, 0
	v_writelane_b32 v249, s8, 37
	s_cmp_eq_u32 s17, 5
	s_nop 0
	v_writelane_b32 v249, s9, 38
	s_cselect_b64 s[8:9], -1, 0
	v_writelane_b32 v249, s8, 39
	s_cmp_eq_u32 s17, 4
	s_nop 0
	v_writelane_b32 v249, s9, 40
	s_cselect_b64 s[8:9], -1, 0
	v_writelane_b32 v249, s8, 41
	s_cmp_eq_u32 s17, 3
	s_nop 0
	v_writelane_b32 v249, s9, 42
	s_cselect_b64 s[8:9], -1, 0
	v_writelane_b32 v249, s8, 43
	s_cmp_eq_u32 s17, 2
	s_nop 0
	v_writelane_b32 v249, s9, 44
	s_cselect_b64 s[8:9], -1, 0
	v_writelane_b32 v249, s8, 45
	s_cmp_eq_u32 s17, 1
	s_nop 0
	v_writelane_b32 v249, s9, 46
	s_cselect_b64 s[8:9], -1, 0
	v_writelane_b32 v249, s8, 47
	s_cmp_eq_u32 s17, 0
	s_nop 0
	v_writelane_b32 v249, s9, 48
	s_cselect_b64 s[8:9], -1, 0
	v_writelane_b32 v249, s8, 49
	s_lshl_b32 s2, s17, 8
	s_nop 0
	v_writelane_b32 v249, s9, 50
	s_add_u32 s8, s86, s2
	s_addc_u32 s9, s87, 0
	s_add_u32 s12, s8, 0x1400
	s_addc_u32 s13, s9, 0
	v_writelane_b32 v249, s12, 51
	s_nop 1
; __global__ void __launch_bounds__(NWAVES * 64, 2) fwd_kernel(Args A) {
;     ...
;     for (int l = 0; l < DEPTH; ++l) {
;         { pg8::Gemm g{XB, (const bf16*)(ws + WS_WIN + l * SZ_WIN), SEQ, INW, DM};
;           pg8::EpiZ E{Z, INW, 8, SS + (size_t)(SS_Q1 + l) * SEQ};
;           if (G == 256) { pg8::OrderTok S{vc, INW / 256, 0}; pg8::gemm_phase<pg8::EpiZ, pg8::OrderTok, true, true>(ldsl, g, S, E); }
;           else { pg8::StaticOrder S; S.init(SEQ, INW, G, bx); pg8::gemm_phase<pg8::EpiZ, pg8::StaticOrder, true, true>(ldsl, g, S, E); } }
;         if (G == 256 && vc >= 192) {
;             PHASE_IDS(); const int g0 = Q_P + l * (Q_G1 + Q_G3), g1 = g0 + Q_G1;
;             convert_items(A, ws, g0 < N_ALL ? g0 : N_ALL, g1 < N_ALL ? g1 : N_ALL, (vc - 192) * NWAVES + wid, 64 * NWAVES, (float*)(lds + wid * TSCR), lane); }
;         GRID_BAR();
;         { PHASE_IDS();
;           if (G == 256) mixer_phase256(A, l, vc, Z, MIX, SS + (size_t)(SS_A + l) * SEQ, SS + (size_t)(SS_B + l) * SEQ, lds, tid, wid, lane);
;           else {
;             for (int a = bx; a < 256; a += G) attn_unit(A, l, a >> 2, a & 3, Z, MIX, SS + (size_t)(SS_B + l) * SEQ, lds, tid, wid, lane);
;             for (int s = bx; s < 1024; s += G) sgu_unit(A, l, s >> 4, s & 15, Z, MIX, SS + (size_t)(SS_A + l) * SEQ, lds, tid, wid, lane); } }
;         LOCAL_BAR();
;         { pg8::Gemm g{MIX, (const bf16*)(ws + WS_WOUT + l * SZ_WOUT), SEQ, DM, DM};
;           pg8::EpiResid<true> E{nullptr, DM, XB, SS + (size_t)(SS_Q2 + l) * SEQ, SS + (size_t)(SS_A + l) * SEQ, SS + (size_t)(SS_B + l) * SEQ};
;           if (G == 256) { pg8::OrderTok S{vc, DM / 256, 0}; pg8::gemm_phase<pg8::EpiResid<true>, pg8::OrderTok, true, true>(ldsl, g, S, E); }
;           else { pg8::StaticOrder S; S.init(SEQ, DM, G, bx); pg8::gemm_phase<pg8::EpiResid<true>, pg8::StaticOrder, true, true>(ldsl, g, S, E); } }
;         LOCAL_BAR();
;         { pg8::Gemm g{XB, (const bf16*)(ws + WS_WGU + l * SZ_WGU), SEQ, NGU, DM};
;           pg8::EpiSwiGLU E{ACT, DFF, SS + (size_t)(SS_Q2 + l) * SEQ};
;           if (G == 256) { pg8::OrderTok S{vc, NGU / 256, 5}; pg8::gemm_phase<pg8::EpiSwiGLU, pg8::OrderTok, true, true>(ldsl, g, S, E); }
;           else { pg8::StaticOrder S; S.init(SEQ, NGU, G, bx); pg8::gemm_phase<pg8::EpiSwiGLU, pg8::StaticOrder, true, true>(ldsl, g, S, E); } }
;         if (G == 256 && vc >= 128) {
	v_writelane_b32 v249, s13, 52
	s_add_u32 s12, s8, 0x2400
	s_addc_u32 s13, s9, 0
	v_writelane_b32 v249, s12, 53
	s_nop 1
	v_writelane_b32 v249, s13, 54
	s_add_u32 s12, s86, 0x3400
	s_addc_u32 s13, s87, 0
	v_writelane_b32 v249, s12, 55
	s_nop 1
	v_writelane_b32 v249, s13, 56
	s_add_u32 s12, s86, 0x3500
	s_addc_u32 s13, s87, 0
	v_writelane_b32 v249, s12, 57
	s_cmpk_lt_i32 s28, 0x100
	s_nop 0
	v_writelane_b32 v249, s13, 58
	s_cselect_b64 s[12:13], -1, 0
	v_writelane_b32 v249, s12, 59
	s_cmpk_lt_i32 s28, 0x400
	s_nop 0
	v_writelane_b32 v249, s13, 60
	s_cselect_b64 s[12:13], -1, 0
	v_writelane_b32 v249, s12, 61
	s_and_b32 s2, s11, 56
	s_nop 0
	v_writelane_b32 v249, s13, 62
	s_and_b32 s12, s22, -4
	s_add_i32 s14, s2, s12
	s_add_i32 s12, s2, s22
	s_ashr_i32 s2, s3, 3
	s_and_b32 s13, s2, 3
	s_and_b32 s17, s2, 15
	s_lshl_b32 s2, s13, 6
	s_lshl_b32 s23, s13, 2
	s_lshl_b32 s13, s13, 8
	v_writelane_b32 v248, s13, 0
	s_lshl_b32 s13, s12, 7
	v_writelane_b32 v248, s13, 1
	s_addk_i32 s13, 0xff80
	v_writelane_b32 v248, s13, 2
	s_lshl_b32 s13, s17, 7
	s_add_u32 s26, s82, s13
	v_writelane_b32 v248, s17, 3
	s_addc_u32 s27, s83, 0
	v_writelane_b32 v248, s26, 4
	v_writelane_b32 v249, s23, 63
	s_nop 0
	v_writelane_b32 v248, s27, 5
	v_writelane_b32 v248, s14, 6
	s_lshl_b32 s14, s14, 7
	s_or_b32 s17, s14, 0x80
	v_writelane_b32 v248, s17, 7
	s_or_b32 s17, s14, 0x100
	v_writelane_b32 v248, s17, 8
	v_writelane_b32 v248, s14, 9
	s_or_b32 s14, s14, 0x180
	s_add_u32 s26, s18, s13
	v_writelane_b32 v248, s14, 10
	s_addc_u32 s27, s19, 0
	v_writelane_b32 v248, s26, 11
	s_cmp_gt_i32 s12, 0
	s_cselect_b64 s[12:13], -1, 0
	v_writelane_b32 v248, s27, 12
	v_writelane_b32 v248, s12, 13
	s_nop 1
	v_writelane_b32 v248, s13, 14
	s_add_u32 s12, s8, 0x4000
	s_addc_u32 s13, s9, 0
	v_writelane_b32 v248, s12, 15
	s_add_u32 s8, s8, 0x5000
	s_addc_u32 s9, s9, 0
	v_writelane_b32 v248, s13, 16
	s_lshl_b32 s12, s6, 5
	v_writelane_b32 v248, s8, 17
	s_cmp_lt_i32 s22, 8
	s_nop 0
	v_writelane_b32 v248, s9, 18
	s_cselect_b64 s[8:9], -1, 0
	s_add_u32 s88, s18, s10
	v_writelane_b32 v248, s8, 19
	s_addc_u32 s89, s19, 0
	s_nop 0
	v_writelane_b32 v248, s9, 20
	s_add_u32 s8, s88, 0x80000
	s_addc_u32 s9, s89, 0
	v_writelane_b32 v248, s8, 21
	s_cmpk_lt_i32 s28, 0x580
	s_mov_b64 s[28:29], 0x80
	v_writelane_b32 v248, s9, 22
	s_cselect_b64 s[8:9], -1, 0
	v_writelane_b32 v248, s8, 23
	s_add_i32 s26, s22, 32
	s_cmp_lt_i32 s22, 12
	v_writelane_b32 v248, s9, 24
	s_mov_b32 s8, s22
	v_writelane_b32 v248, s8, 25
	s_nop 1
	v_writelane_b32 v248, s9, 26
	s_cselect_b64 s[8:9], -1, 0
	v_writelane_b32 v248, s8, 27
	s_ashr_i32 s27, s26, 31
	s_nop 0
	v_writelane_b32 v248, s9, 28
	s_mov_b32 s8, s26
	v_writelane_b32 v248, s8, 29
	s_nop 1
	v_writelane_b32 v248, s9, 30
	s_lshl_b64 s[8:9], s[26:27], 20
	v_writelane_b32 v248, s8, 31
	s_cmpk_gt_i32 s3, 0x7f
	s_nop 0
	v_writelane_b32 v248, s9, 32
	s_cselect_b64 s[8:9], -1, 0
	s_and_b64 s[8:9], s[30:31], s[8:9]
	v_writelane_b32 v248, s8, 33
	s_mov_b32 s30, 0x3e027906
	s_nop 0
	v_writelane_b32 v248, s9, 34
	s_add_i32 s8, s11, 0x211c
	s_add_u32 s34, s20, s7
	s_addc_u32 s35, s21, 0
	v_writelane_b32 v248, s8, 35
	s_add_u32 s8, s34, 0x160000
	s_addc_u32 s9, s35, 0
	v_writelane_b32 v248, s8, 36
	s_cmp_lt_i32 s6, 0
	s_mul_i32 s7, s6, 33
	v_writelane_b32 v248, s9, 37
	s_cselect_b32 s8, 57, 56
	s_mul_i32 s8, s6, s8
	s_movk_i32 s9, 0xb1
	s_cselect_b32 s7, s7, s12
	s_cselect_b32 s9, s9, 0xb0
	s_add_i32 s8, s8, s5
	s_mul_hi_i32 s10, s8, 0x92492493
	s_add_i32 s10, s10, s8
	s_lshr_b32 s11, s10, 31
	s_ashr_i32 s10, s10, 6
	s_add_i32 s10, s10, s11
	s_mul_i32 s11, s10, 0x70
	s_sub_i32 s8, s8, s11
	s_bfe_i32 s11, s8, 0x80000
	s_bfe_u32 s11, s11, 0x3000c
	s_add_i32 s11, s8, s11
	s_and_b32 s12, s11, 0xf8
	s_add_i32 s7, s7, s5
	s_sub_i32 s8, s8, s12
	s_ashr_i32 s12, s7, 31
	s_mul_i32 s6, s6, s9
	s_lshr_b32 s12, s12, 26
	s_add_i32 s6, s6, s5
	s_add_i32 s12, s7, s12
	s_mul_hi_i32 s5, s6, 0x2e8ba2e9
	s_and_b32 s13, s12, 0xffc0
	s_lshr_b32 s9, s5, 31
	s_ashr_i32 s5, s5, 6
	s_sub_i32 s7, s7, s13
	s_add_i32 s5, s5, s9
	s_bfe_i32 s13, s7, 0x80000
	s_mul_i32 s9, s5, 0x160
	s_bfe_u32 s13, s13, 0x3000c
	s_sub_i32 s6, s6, s9
; #define GRID_BAR() xcd_barrier(bar)
; __global__ void __launch_bounds__(NWAVES * 64, 2) fwd_kernel(Args A) {
;     ...
;         { pg8::Gemm g{XB, (const bf16*)(ws + WS_WIN + l * SZ_WIN), SEQ, INW, DM};
;           pg8::EpiZ E{Z, INW, 8, SS + (size_t)(SS_Q1 + l) * SEQ};
;           if (G == 256) { pg8::OrderTok S{vc, INW / 256, 0}; pg8::gemm_phase<pg8::EpiZ, pg8::OrderTok, true, true>(ldsl, g, S, E); }
;           else { pg8::StaticOrder S; S.init(SEQ, INW, G, bx); pg8::gemm_phase<pg8::EpiZ, pg8::StaticOrder, true, true>(ldsl, g, S, E); } }
;         if (G == 256 && vc >= 192) {
;             PHASE_IDS(); const int g0 = Q_P + l * (Q_G1 + Q_G3), g1 = g0 + Q_G1;
;             convert_items(A, ws, g0 < N_ALL ? g0 : N_ALL, g1 < N_ALL ? g1 : N_ALL, (vc - 192) * NWAVES + wid, 64 * NWAVES, (float*)(lds + wid * TSCR), lane); }
;         GRID_BAR();
;         { PHASE_IDS();
;           if (G == 256) mixer_phase256(A, l, vc, Z, MIX, SS + (size_t)(SS_A + l) * SEQ, SS + (size_t)(SS_B + l) * SEQ, lds, tid, wid, lane);
;           else {
;             for (int a = bx; a < 256; a += G) attn_unit(A, l, a >> 2, a & 3, Z, MIX, SS + (size_t)(SS_B + l) * SEQ, lds, tid, wid, lane);
;             for (int s = bx; s < 1024; s += G) sgu_unit(A, l, s >> 4, s & 15, Z, MIX, SS + (size_t)(SS_A + l) * SEQ, lds, tid, wid, lane); } }
;         LOCAL_BAR();
;         { pg8::Gemm g{MIX, (const bf16*)(ws + WS_WOUT + l * SZ_WOUT), SEQ, DM, DM};
;           pg8::EpiResid<true> E{nullptr, DM, XB, SS + (size_t)(SS_Q2 + l) * SEQ, SS + (size_t)(SS_A + l) * SEQ, SS + (size_t)(SS_B + l) * SEQ};
;           if (G == 256) { pg8::OrderTok S{vc, DM / 256, 0}; pg8::gemm_phase<pg8::EpiResid<true>, pg8::OrderTok, true, true>(ldsl, g, S, E); }
;           else { pg8::StaticOrder S; S.init(SEQ, DM, G, bx); pg8::gemm_phase<pg8::EpiResid<true>, pg8::StaticOrder, true, true>(ldsl, g, S, E); } }
;         LOCAL_BAR();
;         { pg8::Gemm g{XB, (const bf16*)(ws + WS_WGU + l * SZ_WGU), SEQ, NGU, DM};
;           pg8::EpiSwiGLU E{ACT, DFF, SS + (size_t)(SS_Q2 + l) * SEQ};
;           if (G == 256) { pg8::OrderTok S{vc, NGU / 256, 5}; pg8::gemm_phase<pg8::EpiSwiGLU, pg8::OrderTok, true, true>(ldsl, g, S, E); }
;           else { pg8::StaticOrder S; S.init(SEQ, NGU, G, bx); pg8::gemm_phase<pg8::EpiSwiGLU, pg8::StaticOrder, true, true>(ldsl, g, S, E); } }
;         if (G == 256 && vc >= 128) {
	s_add_i32 s13, s7, s13
	s_bfe_u32 s9, s6, 0x3001c
	s_and_b32 s14, s13, 0xf8
	s_add_i32 s9, s6, s9
	s_lshl_b32 s10, s10, 3
	s_sext_i32_i8 s8, s8
	s_sub_i32 s7, s7, s14
	s_and_b32 s14, s9, 0xfff8
	s_add_i32 s22, s10, s8
	s_ashr_i32 s8, s12, 6
	s_sub_i32 s6, s6, s14
	s_lshl_b32 s8, s8, 3
	s_sext_i32_i8 s7, s7
	s_add_i32 s12, s8, s7
	s_lshl_b32 s5, s5, 3
	s_sext_i32_i16 s7, s9
	s_sext_i32_i16 s6, s6
	s_add_i32 s26, s5, s6
	s_lshr_b32 s6, s7, 3
	s_ashr_i32 s5, s7, 3
	s_bfe_i64 s[6:7], s[6:7], 0x100000
	s_bfe_i32 s11, s11, 0x80000
	v_writelane_b32 v248, s5, 38
	s_lshl_b64 s[6:7], s[6:7], 20
	s_sext_i32_i16 s11, s11
	s_bfe_i32 s10, s13, 0x80000
	v_writelane_b32 v248, s6, 39
	s_sext_i32_i16 s10, s10
	s_ashr_i32 s5, s11, 3
	v_writelane_b32 v248, s7, 40
	v_writelane_b32 v248, s5, 41
	s_ashr_i32 s5, s10, 3
	v_writelane_b32 v248, s5, 42
	s_lshr_b32 s8, s10, 3
	s_mov_b32 s10, s26
	s_ashr_i32 s27, s26, 31
	s_lshr_b32 s6, s11, 3
	v_writelane_b32 v248, s10, 43
	s_mul_i32 s5, s85, s84
	s_mul_i32 s5, s5, s16
	v_writelane_b32 v248, s11, 44
	s_lshl_b64 s[10:11], s[26:27], 20
	s_add_u32 s10, s64, s10
	s_addc_u32 s11, s65, s11
	s_add_u32 s26, s10, 0x80000
	v_writelane_b32 v248, s10, 45
	s_addc_u32 s27, s11, 0
	s_bfe_i64 s[6:7], s[6:7], 0x100000
	v_writelane_b32 v248, s11, 46
	v_writelane_b32 v248, s26, 47
	s_lshl_b64 s[6:7], s[6:7], 20
	s_ashr_i32 s23, s22, 31
	v_writelane_b32 v248, s27, 48
	v_writelane_b32 v248, s6, 49
	s_movk_i32 s85, 0x1c00
	s_nop 0
	v_writelane_b32 v248, s7, 50
	s_mov_b32 s6, s22
	v_writelane_b32 v248, s6, 51
	s_nop 1
	v_writelane_b32 v248, s7, 52
	s_lshl_b64 s[6:7], s[22:23], 20
	s_add_u32 s6, s64, s6
	s_addc_u32 s7, s65, s7
	s_add_u32 s10, s6, 0x80000
	v_writelane_b32 v248, s6, 53
	s_addc_u32 s11, s7, 0
	s_ashr_i32 s13, s12, 31
	v_writelane_b32 v248, s7, 54
	v_writelane_b32 v248, s10, 55
	s_bfe_i64 s[6:7], s[8:9], 0x100000
	s_lshl_b64 s[6:7], s[6:7], 20
	v_writelane_b32 v248, s11, 56
	v_writelane_b32 v248, s6, 57
	s_nop 1
	v_writelane_b32 v248, s7, 58
	s_lshl_b64 s[6:7], s[12:13], 20
	s_add_u32 s6, s18, s6
	v_writelane_b32 v248, s18, 59
	s_addc_u32 s7, s19, s7
	s_add_u32 s8, s6, 0x80000
	v_writelane_b32 v248, s19, 60
	v_writelane_b32 v248, s5, 61
	v_writelane_b32 v248, s6, 62
	s_addc_u32 s9, s7, 0
	v_writelane_b32 v247, s8, 0
	v_writelane_b32 v248, s7, 63
	s_mov_b32 s6, s12
	v_writelane_b32 v247, s9, 1
	v_writelane_b32 v247, s6, 2
	s_mul_hi_i32 s5, s12, 0x2c0000
	s_nop 0
	v_writelane_b32 v247, s7, 3
	s_mul_i32 s6, s12, 0x2c0000
	s_add_u32 s6, s20, s6
	v_writelane_b32 v247, s20, 4
	s_addc_u32 s7, s21, s5
	s_add_u32 s8, s6, 0x160000
	v_writelane_b32 v247, s21, 5
	v_writelane_b32 v247, s6, 6
	s_addc_u32 s9, s7, 0
	s_and_b32 s3, s3, 7
	v_writelane_b32 v247, s7, 7
	s_lshl_b32 s5, s3, 22
	s_lshl_b32 s6, s4, 20
	s_or_b32 s5, s5, s6
	s_add_u32 s31, s86, s5
	s_addc_u32 s91, s87, 0
	v_writelane_b32 v247, s8, 8
	s_add_u32 s6, s31, 0x16280080
	s_addc_u32 s7, s91, 0
	v_writelane_b32 v247, s9, 9
	v_writelane_b32 v247, s6, 10
	s_add_u32 s5, s86, s24
	s_mul_i32 s3, s3, 0xb00000
	v_writelane_b32 v247, s7, 11
	v_writelane_b32 v247, s24, 12
	s_addc_u32 s6, s87, s25
	s_add_u32 s8, s5, 0x200100
	v_writelane_b32 v247, s25, 13
	s_addc_u32 s9, s6, 0
	v_writelane_b32 v247, s8, 14
	s_mul_i32 s4, s4, 0x2c0000
	s_nop 0
	v_writelane_b32 v247, s9, 15
	s_add_u32 s8, s31, 0x1ba80080
	s_addc_u32 s9, s91, 0
	v_writelane_b32 v247, s8, 16
	s_nop 1
	v_writelane_b32 v247, s9, 17
	s_add_u32 s8, s5, 0x3a00100
	s_addc_u32 s9, s6, 0
	s_add_i32 s3, s3, s4
	s_add_u32 s93, s86, s3
	s_addc_u32 s95, s87, 0
	v_writelane_b32 v247, s8, 18
	s_add_u32 s4, s93, 0x1db60080
	s_addc_u32 s5, s95, 0
	v_writelane_b32 v247, s9, 19
	v_writelane_b32 v247, s4, 20
	s_add_i32 s3, 0, 0x23ff0
	s_lshl_b32 s2, s2, 1
	v_writelane_b32 v247, s5, 21
	v_writelane_b32 v247, s3, 22
	s_add_i32 s3, 0, 0x23ff4
	v_writelane_b32 v247, s3, 23
	s_add_i32 s3, 0, 0x11400
	v_writelane_b32 v247, s3, 24
	v_writelane_b32 v247, s2, 25
	s_nop 1
	v_writelane_b32 v247, s3, 26
	s_add_i32 s2, 0, 0x11c00
	v_writelane_b32 v247, s2, 27
	v_writelane_b32 v247, s64, 28
	s_nop 1
	v_writelane_b32 v247, s65, 29
	v_writelane_b32 v247, s80, 30
	s_branch .LBB0_116

; __device__ __forceinline__ float ss_get(const ss_t* p) { const ss_t v = *p; return (float)(unsigned)(v >> 32) + (float)(unsigned)v * 2.3283064365386963e-10f; }
; __device__ __forceinline__ unsigned pkbf(float lo, float hi) { typedef float f2_t __attribute__((ext_vector_type(2))); typedef __bf16 b2_t __attribute__((ext_vector_type(2))); f2_t v = {lo, hi}; b2_t b = __builtin_convertvector(v, b2_t); return __builtin_bit_cast(unsigned, b); }
; __device__ __forceinline__ f32x2 gelu_pk(f32x2 v) {
;     const f32x2 av = __builtin_elementwise_abs(v), d = av * 0.2316418882f + 1.0f;
;     f32x2 t; t.x = __builtin_amdgcn_rcpf(d.x); t.y = __builtin_amdgcn_rcpf(d.y);
;     f32x2 q = t * 0.5307027145f + (-0.7265760135f); q = q * t + 0.7107068705f; q = q * t + (-0.142248368f); q = q * t + 0.127414796f; q = q * t;
;     const f32x2 s = (v * v) * (-0.72134752044f);
;     f32x2 e; e.x = __builtin_amdgcn_exp2f(s.x); e.y = __builtin_amdgcn_exp2f(s.y);
;     const f32x2 m = v * (q * e), r = v - m;
;     f32x2 o; o.x = v.x < 0.f ? m.x : r.x; o.y = v.y < 0.f ? m.y : r.y; return o;
; }
;     __device__ __forceinline__ void operator()(const f32x4 (&acc)[2][2][4][2], const Unit& u, int wr, int wc, int fr, int fq) const {
;         int row0 = u.pm * BM + wr * 64 + fr; asm volatile("" : "+v"(row0));     const int col0 = u.pn * BM + wc * 32 + 8 * fq; const bool act = u.pn < gelu_tiles;
; #pragma unroll
;         for (int ai = 0; ai < 2; ++ai)
; #pragma unroll
;             for (int m = 0; m < 4; ++m) { const int row = row0 + ai * HALF + m * 16; bf16_t* rowp = O + (size_t)row * ldc + col0;
;                 const float rs = 1.0f / sqrtf(ss_get(ssq + row) * (1.0f / 2048.f) + 1e-6f);
; #pragma unroll
;                 for (int bj = 0; bj < 2; ++bj) { f32x4 v0 = acc[ai][bj][m][0] * rs, v1 = acc[ai][bj][m][1] * rs;
;                     if (act) { f32x2 a = gelu_pk((f32x2){v0[0], v0[1]}), b = gelu_pk((f32x2){v0[2], v0[3]}), c = gelu_pk((f32x2){v1[0], v1[1]}), d = gelu_pk((f32x2){v1[2], v1[3]});
;                         v0 = (f32x4){a.x, a.y, b.x, b.y}; v1 = (f32x4){c.x, c.y, d.x, d.y}; }
;                     u32x4 w; w.x = pkbf(v0[0], v0[1]); w.y = pkbf(v0[2], v0[3]); w.z = pkbf(v1[0], v1[1]); w.w = pkbf(v1[2], v1[3]);
;                     *(u32x4*)(rowp + bj * HALF) = w; } }
.LBB0_177:
	v_mov_b32_e32 v142, v152
	s_cmp_lt_i32 s53, 8
	v_ashrrev_i32_e32 v143, 31, v142
	v_lshl_add_u64 v[144:145], v[142:143], 3, s[4:5]
	global_load_dwordx2 v[146:147], v[144:145], off
	global_load_dwordx2 v[172:173], v[144:145], off offset:128
	global_load_dwordx2 v[174:175], v[144:145], off offset:256
	global_load_dwordx2 v[176:177], v[144:145], off offset:384
	global_load_dwordx2 v[178:179], v[144:145], off offset:1024
	global_load_dwordx2 v[180:181], v[144:145], off offset:1152
	global_load_dwordx2 v[182:183], v[144:145], off offset:1280
	global_load_dwordx2 v[184:185], v[144:145], off offset:1408
	s_flbit_i32_b32 s2, 0
	v_mov_b32_e32 v149, v2
	s_cselect_b64 s[40:41], -1, 0
	s_min_u32 s15, s2, 32
	s_sub_i32 s52, 32, s15
	s_cmp_gt_i32 s53, 7
	s_waitcnt vmcnt(0)
	v_mov_b32_e32 v148, v147
	v_lshlrev_b64 v[148:149], s15, v[148:149]
	v_min_u32_e32 v143, 1, v148
	v_or_b32_e32 v143, v149, v143
	v_cvt_f32_u32_e32 v143, v143
	v_cvt_f32_u32_e32 v146, v146
	v_ldexp_f32 v143, v143, s52
	v_fmac_f32_e32 v143, 0x2f800000, v146
	v_fmamk_f32 v143, v143, 0x3a000000, v205
	v_mul_f32_e32 v146, 0x4f800000, v143
	v_cmp_gt_f32_e32 vcc, s97, v143
	s_nop 1
	v_cndmask_b32_e32 v143, v143, v146, vcc
	v_sqrt_f32_e32 v146, v143
	s_nop 0
	v_add_u32_e32 v147, -1, v146
	v_add_u32_e32 v148, 1, v146
	v_fma_f32 v149, -v147, v146, v143
	v_fma_f32 v150, -v148, v146, v143
	v_cmp_ge_f32_e64 s[2:3], 0, v149
	s_nop 1
	v_cndmask_b32_e64 v146, v146, v147, s[2:3]
	v_cmp_lt_f32_e64 s[2:3], 0, v150
	s_nop 1
	v_cndmask_b32_e64 v146, v146, v148, s[2:3]
	v_mul_f32_e32 v147, 0x37800000, v146
	v_cndmask_b32_e32 v146, v146, v147, vcc
	v_cmp_class_f32_e32 vcc, v143, v206
	s_nop 1
	v_cndmask_b32_e32 v143, v146, v143, vcc
	v_div_scale_f32 v146, s[2:3], v143, v143, 1.0
	v_rcp_f32_e32 v147, v146
	v_div_scale_f32 v148, vcc, 1.0, v143, 1.0
	v_fma_f32 v149, -v146, v147, 1.0
	v_fmac_f32_e32 v147, v149, v147
	v_mul_f32_e32 v149, v148, v147
	v_fma_f32 v150, -v146, v149, v148
	v_fmac_f32_e32 v149, v150, v147
	v_fma_f32 v146, -v146, v149, v148
	v_div_fmas_f32 v146, v146, v147, v149
	v_div_fixup_f32 v146, v146, v143, 1.0
	v_pk_mul_f32 v[130:131], v[130:131], v[146:147] op_sel_hi:[1,0]
	v_pk_mul_f32 v[128:129], v[128:129], v[146:147] op_sel_hi:[1,0]
	v_pk_mul_f32 v[148:149], v[126:127], v[146:147] op_sel_hi:[1,0]
	v_pk_mul_f32 v[150:151], v[124:125], v[146:147] op_sel_hi:[1,0]
	s_cbranch_scc1 .LBB0_179
	v_and_b32_e32 v125, 0x7fffffff, v129
	v_and_b32_e32 v124, 0x7fffffff, v128
	v_pk_fma_f32 v[124:125], v[124:125], s[90:91], 1.0 op_sel_hi:[1,0,0]
	s_mov_b32 s2, 0xbf3a00e3
	v_rcp_f32_e32 v126, v124
	v_rcp_f32_e32 v127, v125
	v_mov_b64_e32 v[124:125], s[2:3]
	v_pk_mul_f32 v[158:159], v[128:129], v[128:129]
	s_mov_b32 s2, 0xbf38aa3b
	v_pk_fma_f32 v[156:157], v[126:127], s[92:93], v[124:125] op_sel_hi:[1,0,0]
	v_pk_mul_f32 v[158:159], v[158:159], s[2:3] op_sel_hi:[1,0]
	v_pk_fma_f32 v[156:157], v[126:127], v[156:157], s[94:95] op_sel_hi:[1,1,0]
	v_exp_f32_e32 v158, v158
	v_exp_f32_e32 v159, v159
	v_pk_fma_f32 v[156:157], v[126:127], v[156:157], s[96:97] op_sel_hi:[1,1,0]
	v_cmp_gt_f32_e32 vcc, 0, v128
	v_pk_fma_f32 v[156:157], v[126:127], v[156:157], s[30:31] op_sel_hi:[1,1,0]
	s_nop 0
	v_pk_mul_f32 v[126:127], v[126:127], v[156:157]
	v_pk_mul_f32 v[156:157], v[130:131], v[130:131]
	v_pk_mul_f32 v[126:127], v[158:159], v[126:127]
	v_pk_mul_f32 v[156:157], v[156:157], s[2:3] op_sel_hi:[1,0]
	v_pk_mul_f32 v[158:159], v[128:129], v[126:127]
	v_pk_fma_f32 v[126:127], v[128:129], v[126:127], v[128:129] neg_lo:[1,0,0] neg_hi:[1,0,0]
	v_exp_f32_e32 v156, v156
	v_cndmask_b32_e32 v128, v126, v158, vcc
	v_cmp_gt_f32_e32 vcc, 0, v129
	v_and_b32_e32 v126, 0x7fffffff, v130
	v_exp_f32_e32 v157, v157
	v_cndmask_b32_e32 v129, v127, v159, vcc
	v_and_b32_e32 v127, 0x7fffffff, v131
	v_pk_fma_f32 v[126:127], v[126:127], s[90:91], 1.0 op_sel_hi:[1,0,0]
	v_cmp_gt_f32_e32 vcc, 0, v130
	v_rcp_f32_e32 v126, v126
	v_rcp_f32_e32 v127, v127
	s_nop 0
	v_pk_fma_f32 v[158:159], v[126:127], s[92:93], v[124:125] op_sel_hi:[1,0,0]
	s_nop 0
	v_pk_fma_f32 v[158:159], v[126:127], v[158:159], s[94:95] op_sel_hi:[1,1,0]
	s_nop 0
	v_pk_fma_f32 v[158:159], v[126:127], v[158:159], s[96:97] op_sel_hi:[1,1,0]
	s_nop 0
	v_pk_fma_f32 v[158:159], v[126:127], v[158:159], s[30:31] op_sel_hi:[1,1,0]
	s_nop 0
	v_pk_mul_f32 v[126:127], v[126:127], v[158:159]
	v_pk_mul_f32 v[158:159], v[150:151], v[150:151]
	v_pk_mul_f32 v[126:127], v[156:157], v[126:127]
	v_pk_mul_f32 v[158:159], v[158:159], s[2:3] op_sel_hi:[1,0]
	v_pk_mul_f32 v[156:157], v[130:131], v[126:127]
	v_pk_fma_f32 v[126:127], v[130:131], v[126:127], v[130:131] neg_lo:[1,0,0] neg_hi:[1,0,0]
	v_exp_f32_e32 v158, v158
	v_cndmask_b32_e32 v130, v126, v156, vcc
	v_cmp_gt_f32_e32 vcc, 0, v131
	v_and_b32_e32 v126, 0x7fffffff, v150
	v_exp_f32_e32 v159, v159
	v_cndmask_b32_e32 v131, v127, v157, vcc
	v_and_b32_e32 v127, 0x7fffffff, v151
	v_pk_fma_f32 v[126:127], v[126:127], s[90:91], 1.0 op_sel_hi:[1,0,0]
	v_cmp_gt_f32_e32 vcc, 0, v150
	v_rcp_f32_e32 v126, v126
	v_rcp_f32_e32 v127, v127
	s_nop 0
	v_pk_fma_f32 v[156:157], v[126:127], s[92:93], v[124:125] op_sel_hi:[1,0,0]
	s_nop 0
	v_pk_fma_f32 v[156:157], v[126:127], v[156:157], s[94:95] op_sel_hi:[1,1,0]
	s_nop 0
	v_pk_fma_f32 v[156:157], v[126:127], v[156:157], s[96:97] op_sel_hi:[1,1,0]
	s_nop 0
	v_pk_fma_f32 v[156:157], v[126:127], v[156:157], s[30:31] op_sel_hi:[1,1,0]
	s_nop 0
	v_pk_mul_f32 v[126:127], v[126:127], v[156:157]
	v_pk_mul_f32 v[156:157], v[148:149], v[148:149]
	v_pk_mul_f32 v[126:127], v[158:159], v[126:127]
	s_nop 0
	v_pk_mul_f32 v[158:159], v[150:151], v[126:127]
	v_pk_fma_f32 v[126:127], v[150:151], v[126:127], v[150:151] neg_lo:[1,0,0] neg_hi:[1,0,0]
	s_nop 0
	v_cndmask_b32_e32 v150, v126, v158, vcc
	v_cmp_gt_f32_e32 vcc, 0, v151
	v_and_b32_e32 v126, 0x7fffffff, v148
	s_nop 0
	v_cndmask_b32_e32 v151, v127, v159, vcc
	v_and_b32_e32 v127, 0x7fffffff, v149
	v_pk_fma_f32 v[126:127], v[126:127], s[90:91], 1.0 op_sel_hi:[1,0,0]
	v_cmp_gt_f32_e32 vcc, 0, v148
	v_rcp_f32_e32 v126, v126
	v_rcp_f32_e32 v127, v127
	s_nop 0
	v_pk_fma_f32 v[124:125], v[126:127], s[92:93], v[124:125] op_sel_hi:[1,0,0]
	s_nop 0
	v_pk_fma_f32 v[124:125], v[126:127], v[124:125], s[94:95] op_sel_hi:[1,1,0]
	s_nop 0
	v_pk_fma_f32 v[124:125], v[126:127], v[124:125], s[96:97] op_sel_hi:[1,1,0]
	s_nop 0
	v_pk_fma_f32 v[124:125], v[126:127], v[124:125], s[30:31] op_sel_hi:[1,1,0]
	s_nop 0
	v_pk_mul_f32 v[124:125], v[126:127], v[124:125]
	v_pk_mul_f32 v[126:127], v[156:157], s[2:3] op_sel_hi:[1,0]
	s_nop 0
	v_exp_f32_e32 v126, v126
	v_exp_f32_e32 v127, v127
	s_nop 0
	v_pk_mul_f32 v[124:125], v[126:127], v[124:125]
	s_nop 0
	v_pk_mul_f32 v[126:127], v[148:149], v[124:125]
	v_pk_fma_f32 v[124:125], v[148:149], v[124:125], v[148:149] neg_lo:[1,0,0] neg_hi:[1,0,0]
	s_nop 0
	v_cndmask_b32_e32 v148, v124, v126, vcc
	v_cmp_gt_f32_e32 vcc, 0, v149
	s_nop 1
	v_cndmask_b32_e32 v149, v125, v127, vcc

; __device__ __forceinline__ float ss_get(const ss_t* p) { const ss_t v = *p; return (float)(unsigned)(v >> 32) + (float)(unsigned)v * 2.3283064365386963e-10f; }
; __device__ __forceinline__ unsigned pkbf(float lo, float hi) { typedef float f2_t __attribute__((ext_vector_type(2))); typedef __bf16 b2_t __attribute__((ext_vector_type(2))); f2_t v = {lo, hi}; b2_t b = __builtin_convertvector(v, b2_t); return __builtin_bit_cast(unsigned, b); }
; __device__ __forceinline__ f32x2 gelu_pk(f32x2 v) {
;     const f32x2 av = __builtin_elementwise_abs(v), d = av * 0.2316418882f + 1.0f;
;     f32x2 t; t.x = __builtin_amdgcn_rcpf(d.x); t.y = __builtin_amdgcn_rcpf(d.y);
;     f32x2 q = t * 0.5307027145f + (-0.7265760135f); q = q * t + 0.7107068705f; q = q * t + (-0.142248368f); q = q * t + 0.127414796f; q = q * t;
;     const f32x2 s = (v * v) * (-0.72134752044f);
;     f32x2 e; e.x = __builtin_amdgcn_exp2f(s.x); e.y = __builtin_amdgcn_exp2f(s.y);
;     const f32x2 m = v * (q * e), r = v - m;
;     f32x2 o; o.x = v.x < 0.f ? m.x : r.x; o.y = v.y < 0.f ? m.y : r.y; return o;
; }
;     __device__ __forceinline__ void operator()(const f32x4 (&acc)[2][2][4][2], const Unit& u, int wr, int wc, int fr, int fq) const {
;         int row0 = u.pm * BM + wr * 64 + fr; asm volatile("" : "+v"(row0));     const int col0 = u.pn * BM + wc * 32 + 8 * fq; const bool act = u.pn < gelu_tiles;
; #pragma unroll
;         for (int ai = 0; ai < 2; ++ai)
; #pragma unroll
;             for (int m = 0; m < 4; ++m) { const int row = row0 + ai * HALF + m * 16; bf16_t* rowp = O + (size_t)row * ldc + col0;
;                 const float rs = 1.0f / sqrtf(ss_get(ssq + row) * (1.0f / 2048.f) + 1e-6f);
; #pragma unroll
;                 for (int bj = 0; bj < 2; ++bj) { f32x4 v0 = acc[ai][bj][m][0] * rs, v1 = acc[ai][bj][m][1] * rs;
;                     if (act) { f32x2 a = gelu_pk((f32x2){v0[0], v0[1]}), b = gelu_pk((f32x2){v0[2], v0[3]}), c = gelu_pk((f32x2){v1[0], v1[1]}), d = gelu_pk((f32x2){v1[2], v1[3]});
;                         v0 = (f32x4){a.x, a.y, b.x, b.y}; v1 = (f32x4){c.x, c.y, d.x, d.y}; }
;                     u32x4 w; w.x = pkbf(v0[0], v0[1]); w.y = pkbf(v0[2], v0[3]); w.z = pkbf(v1[0], v1[1]); w.w = pkbf(v1[2], v1[3]);
;                     *(u32x4*)(rowp + bj * HALF) = w; } }
.LBB0_181:
	v_cvt_pk_bf16_f32 v120, v120, v121
	v_cvt_pk_bf16_f32 v121, v122, v123
	v_cvt_pk_bf16_f32 v122, v116, v117
	v_cvt_pk_bf16_f32 v123, v118, v119
	global_store_dwordx4 v[126:127], v[120:123], off offset:256
	s_nop 1
	v_mov_b32_e32 v116, v172
	v_mov_b32_e32 v117, v173
	v_mov_b32_e32 v119, v2
	v_mov_b32_e32 v118, v117
	v_lshlrev_b64 v[118:119], s15, v[118:119]
	v_min_u32_e32 v117, 1, v118
	v_or_b32_e32 v117, v119, v117
	v_cvt_f32_u32_e32 v117, v117
	v_cvt_f32_u32_e32 v116, v116
	v_ldexp_f32 v117, v117, s52
	v_fmac_f32_e32 v117, 0x2f800000, v116
	v_fmamk_f32 v116, v117, 0x3a000000, v205
	v_mul_f32_e32 v117, 0x4f800000, v116
	v_cmp_gt_f32_e32 vcc, s97, v116
	s_nop 1
	v_cndmask_b32_e32 v116, v116, v117, vcc
	v_sqrt_f32_e32 v117, v116
	s_nop 0
	v_add_u32_e32 v118, -1, v117
	v_add_u32_e32 v119, 1, v117
	v_fma_f32 v120, -v118, v117, v116
	v_fma_f32 v121, -v119, v117, v116
	v_cmp_ge_f32_e64 s[2:3], 0, v120
	s_nop 1
	v_cndmask_b32_e64 v117, v117, v118, s[2:3]
	v_cmp_lt_f32_e64 s[2:3], 0, v121
	s_nop 1
	v_cndmask_b32_e64 v117, v117, v119, s[2:3]
	v_mul_f32_e32 v118, 0x37800000, v117
	v_cndmask_b32_e32 v117, v117, v118, vcc
	v_cmp_class_f32_e32 vcc, v116, v206
	s_nop 1
	v_cndmask_b32_e32 v116, v117, v116, vcc
	v_div_scale_f32 v117, s[2:3], v116, v116, 1.0
	v_rcp_f32_e32 v118, v117
	v_div_scale_f32 v119, vcc, 1.0, v116, 1.0
	v_fma_f32 v120, -v117, v118, 1.0
	v_fmac_f32_e32 v118, v120, v118
	v_mul_f32_e32 v120, v119, v118
	v_fma_f32 v121, -v117, v120, v119
	v_fmac_f32_e32 v120, v121, v118
	v_fma_f32 v117, -v117, v120, v119
	v_div_fmas_f32 v117, v117, v118, v120
	v_div_fixup_f32 v116, v117, v116, 1.0
	s_and_b64 vcc, exec, s[36:37]
	v_pk_mul_f32 v[114:115], v[114:115], v[116:117] op_sel_hi:[1,0]
	v_pk_mul_f32 v[118:119], v[112:113], v[116:117] op_sel_hi:[1,0]
	v_pk_mul_f32 v[110:111], v[110:111], v[116:117] op_sel_hi:[1,0]
	v_pk_mul_f32 v[112:113], v[108:109], v[116:117] op_sel_hi:[1,0]
	s_cbranch_vccnz .LBB0_183
	v_and_b32_e32 v109, 0x7fffffff, v119
	v_and_b32_e32 v108, 0x7fffffff, v118
	v_pk_fma_f32 v[108:109], v[108:109], s[90:91], 1.0 op_sel_hi:[1,0,0]
	s_mov_b32 s2, 0xbf3a00e3
	v_rcp_f32_e32 v120, v108
	v_rcp_f32_e32 v121, v109
	v_mov_b64_e32 v[108:109], s[2:3]
	v_pk_mul_f32 v[126:127], v[118:119], v[118:119]
	s_mov_b32 s2, 0xbf38aa3b
	v_pk_fma_f32 v[122:123], v[120:121], s[92:93], v[108:109] op_sel_hi:[1,0,0]
	v_pk_mul_f32 v[126:127], v[126:127], s[2:3] op_sel_hi:[1,0]
	v_pk_fma_f32 v[122:123], v[120:121], v[122:123], s[94:95] op_sel_hi:[1,1,0]
	v_exp_f32_e32 v126, v126
	v_exp_f32_e32 v127, v127
	v_pk_fma_f32 v[122:123], v[120:121], v[122:123], s[96:97] op_sel_hi:[1,1,0]
	v_cmp_gt_f32_e32 vcc, 0, v118
	v_pk_fma_f32 v[122:123], v[120:121], v[122:123], s[30:31] op_sel_hi:[1,1,0]
	s_nop 0
	v_pk_mul_f32 v[120:121], v[120:121], v[122:123]
	v_pk_mul_f32 v[122:123], v[114:115], v[114:115]
	v_pk_mul_f32 v[120:121], v[126:127], v[120:121]
	v_pk_mul_f32 v[122:123], v[122:123], s[2:3] op_sel_hi:[1,0]
	v_pk_mul_f32 v[126:127], v[118:119], v[120:121]
	v_pk_fma_f32 v[120:121], v[118:119], v[120:121], v[118:119] neg_lo:[1,0,0] neg_hi:[1,0,0]
	v_exp_f32_e32 v122, v122
	v_cndmask_b32_e32 v118, v120, v126, vcc
	v_cmp_gt_f32_e32 vcc, 0, v119
	v_and_b32_e32 v120, 0x7fffffff, v114
	v_exp_f32_e32 v123, v123
	v_cndmask_b32_e32 v119, v121, v127, vcc
	v_and_b32_e32 v121, 0x7fffffff, v115
	v_pk_fma_f32 v[120:121], v[120:121], s[90:91], 1.0 op_sel_hi:[1,0,0]
	v_cmp_gt_f32_e32 vcc, 0, v114
	v_rcp_f32_e32 v120, v120
	v_rcp_f32_e32 v121, v121
	s_nop 0
	v_pk_fma_f32 v[126:127], v[120:121], s[92:93], v[108:109] op_sel_hi:[1,0,0]
	s_nop 0
	v_pk_fma_f32 v[126:127], v[120:121], v[126:127], s[94:95] op_sel_hi:[1,1,0]
	s_nop 0
	v_pk_fma_f32 v[126:127], v[120:121], v[126:127], s[96:97] op_sel_hi:[1,1,0]
	s_nop 0
	v_pk_fma_f32 v[126:127], v[120:121], v[126:127], s[30:31] op_sel_hi:[1,1,0]
	s_nop 0
	v_pk_mul_f32 v[120:121], v[120:121], v[126:127]
	v_pk_mul_f32 v[126:127], v[112:113], v[112:113]
	v_pk_mul_f32 v[120:121], v[122:123], v[120:121]
	v_pk_mul_f32 v[126:127], v[126:127], s[2:3] op_sel_hi:[1,0]
	v_pk_mul_f32 v[122:123], v[114:115], v[120:121]
	v_pk_fma_f32 v[120:121], v[114:115], v[120:121], v[114:115] neg_lo:[1,0,0] neg_hi:[1,0,0]
	v_exp_f32_e32 v126, v126
	v_cndmask_b32_e32 v114, v120, v122, vcc
	v_cmp_gt_f32_e32 vcc, 0, v115
	v_and_b32_e32 v120, 0x7fffffff, v112
	v_exp_f32_e32 v127, v127
	v_cndmask_b32_e32 v115, v121, v123, vcc
	v_and_b32_e32 v121, 0x7fffffff, v113
	v_pk_fma_f32 v[120:121], v[120:121], s[90:91], 1.0 op_sel_hi:[1,0,0]
	v_cmp_gt_f32_e32 vcc, 0, v112
	v_rcp_f32_e32 v120, v120
	v_rcp_f32_e32 v121, v121
	s_nop 0
	v_pk_fma_f32 v[122:123], v[120:121], s[92:93], v[108:109] op_sel_hi:[1,0,0]
	s_nop 0
	v_pk_fma_f32 v[122:123], v[120:121], v[122:123], s[94:95] op_sel_hi:[1,1,0]
	s_nop 0
	v_pk_fma_f32 v[122:123], v[120:121], v[122:123], s[96:97] op_sel_hi:[1,1,0]
	s_nop 0
	v_pk_fma_f32 v[122:123], v[120:121], v[122:123], s[30:31] op_sel_hi:[1,1,0]
	s_nop 0
	v_pk_mul_f32 v[120:121], v[120:121], v[122:123]
	v_pk_mul_f32 v[122:123], v[110:111], v[110:111]
	v_pk_mul_f32 v[120:121], v[126:127], v[120:121]
	s_nop 0
	v_pk_mul_f32 v[126:127], v[112:113], v[120:121]
	v_pk_fma_f32 v[120:121], v[112:113], v[120:121], v[112:113] neg_lo:[1,0,0] neg_hi:[1,0,0]
	s_nop 0
	v_cndmask_b32_e32 v112, v120, v126, vcc
	v_cmp_gt_f32_e32 vcc, 0, v113
	v_and_b32_e32 v120, 0x7fffffff, v110
	s_nop 0
	v_cndmask_b32_e32 v113, v121, v127, vcc
	v_and_b32_e32 v121, 0x7fffffff, v111
	v_pk_fma_f32 v[120:121], v[120:121], s[90:91], 1.0 op_sel_hi:[1,0,0]
	v_cmp_gt_f32_e32 vcc, 0, v110
	v_rcp_f32_e32 v120, v120
	v_rcp_f32_e32 v121, v121
	s_nop 0
	v_pk_fma_f32 v[108:109], v[120:121], s[92:93], v[108:109] op_sel_hi:[1,0,0]
	s_nop 0
	v_pk_fma_f32 v[108:109], v[120:121], v[108:109], s[94:95] op_sel_hi:[1,1,0]
	s_nop 0
	v_pk_fma_f32 v[108:109], v[120:121], v[108:109], s[96:97] op_sel_hi:[1,1,0]
	s_nop 0
	v_pk_fma_f32 v[108:109], v[120:121], v[108:109], s[30:31] op_sel_hi:[1,1,0]
	s_nop 0
	v_pk_mul_f32 v[108:109], v[120:121], v[108:109]
	v_pk_mul_f32 v[120:121], v[122:123], s[2:3] op_sel_hi:[1,0]
	s_nop 0
	v_exp_f32_e32 v120, v120
	v_exp_f32_e32 v121, v121
	s_nop 0
	v_pk_mul_f32 v[108:109], v[120:121], v[108:109]
	s_nop 0
	v_pk_mul_f32 v[120:121], v[110:111], v[108:109]
	v_pk_fma_f32 v[108:109], v[110:111], v[108:109], v[110:111] neg_lo:[1,0,0] neg_hi:[1,0,0]
	s_nop 0
	v_cndmask_b32_e32 v110, v108, v120, vcc
	v_cmp_gt_f32_e32 vcc, 0, v111
	s_nop 1
	v_cndmask_b32_e32 v111, v109, v121, vcc

; __device__ __forceinline__ float ss_get(const ss_t* p) { const ss_t v = *p; return (float)(unsigned)(v >> 32) + (float)(unsigned)v * 2.3283064365386963e-10f; }
; __device__ __forceinline__ unsigned pkbf(float lo, float hi) { typedef float f2_t __attribute__((ext_vector_type(2))); typedef __bf16 b2_t __attribute__((ext_vector_type(2))); f2_t v = {lo, hi}; b2_t b = __builtin_convertvector(v, b2_t); return __builtin_bit_cast(unsigned, b); }
; __device__ __forceinline__ f32x2 gelu_pk(f32x2 v) {
;     const f32x2 av = __builtin_elementwise_abs(v), d = av * 0.2316418882f + 1.0f;
;     f32x2 t; t.x = __builtin_amdgcn_rcpf(d.x); t.y = __builtin_amdgcn_rcpf(d.y);
;     f32x2 q = t * 0.5307027145f + (-0.7265760135f); q = q * t + 0.7107068705f; q = q * t + (-0.142248368f); q = q * t + 0.127414796f; q = q * t;
;     const f32x2 s = (v * v) * (-0.72134752044f);
;     f32x2 e; e.x = __builtin_amdgcn_exp2f(s.x); e.y = __builtin_amdgcn_exp2f(s.y);
;     const f32x2 m = v * (q * e), r = v - m;
;     f32x2 o; o.x = v.x < 0.f ? m.x : r.x; o.y = v.y < 0.f ? m.y : r.y; return o;
; }
;     __device__ __forceinline__ void operator()(const f32x4 (&acc)[2][2][4][2], const Unit& u, int wr, int wc, int fr, int fq) const {
;         int row0 = u.pm * BM + wr * 64 + fr; asm volatile("" : "+v"(row0));     const int col0 = u.pn * BM + wc * 32 + 8 * fq; const bool act = u.pn < gelu_tiles;
; #pragma unroll
;         for (int ai = 0; ai < 2; ++ai)
; #pragma unroll
;             for (int m = 0; m < 4; ++m) { const int row = row0 + ai * HALF + m * 16; bf16_t* rowp = O + (size_t)row * ldc + col0;
;                 const float rs = 1.0f / sqrtf(ss_get(ssq + row) * (1.0f / 2048.f) + 1e-6f);
; #pragma unroll
;                 for (int bj = 0; bj < 2; ++bj) { f32x4 v0 = acc[ai][bj][m][0] * rs, v1 = acc[ai][bj][m][1] * rs;
;                     if (act) { f32x2 a = gelu_pk((f32x2){v0[0], v0[1]}), b = gelu_pk((f32x2){v0[2], v0[3]}), c = gelu_pk((f32x2){v1[0], v1[1]}), d = gelu_pk((f32x2){v1[2], v1[3]});
;                         v0 = (f32x4){a.x, a.y, b.x, b.y}; v1 = (f32x4){c.x, c.y, d.x, d.y}; }
;                     u32x4 w; w.x = pkbf(v0[0], v0[1]); w.y = pkbf(v0[2], v0[3]); w.z = pkbf(v1[0], v1[1]); w.w = pkbf(v1[2], v1[3]);
;                     *(u32x4*)(rowp + bj * HALF) = w; } }
.LBB0_185:
	v_cvt_pk_bf16_f32 v104, v104, v105
	v_cvt_pk_bf16_f32 v105, v106, v107
	v_cvt_pk_bf16_f32 v106, v100, v101
	v_cvt_pk_bf16_f32 v107, v102, v103
	global_store_dwordx4 v[108:109], v[104:107], off offset:256
	s_nop 1
	v_mov_b32_e32 v100, v174
	v_mov_b32_e32 v101, v175
	v_mov_b32_e32 v103, v2
	v_mov_b32_e32 v102, v101
	v_lshlrev_b64 v[102:103], s15, v[102:103]
	v_min_u32_e32 v101, 1, v102
	v_or_b32_e32 v101, v103, v101
	v_cvt_f32_u32_e32 v101, v101
	v_cvt_f32_u32_e32 v100, v100
	v_ldexp_f32 v101, v101, s52
	v_fmac_f32_e32 v101, 0x2f800000, v100
	v_fmamk_f32 v100, v101, 0x3a000000, v205
	v_mul_f32_e32 v101, 0x4f800000, v100
	v_cmp_gt_f32_e32 vcc, s97, v100
	s_nop 1
	v_cndmask_b32_e32 v100, v100, v101, vcc
	v_sqrt_f32_e32 v101, v100
	s_nop 0
	v_add_u32_e32 v102, -1, v101
	v_add_u32_e32 v103, 1, v101
	v_fma_f32 v104, -v102, v101, v100
	v_fma_f32 v105, -v103, v101, v100
	v_cmp_ge_f32_e64 s[2:3], 0, v104
	s_nop 1
	v_cndmask_b32_e64 v101, v101, v102, s[2:3]
	v_cmp_lt_f32_e64 s[2:3], 0, v105
	s_nop 1
	v_cndmask_b32_e64 v101, v101, v103, s[2:3]
	v_mul_f32_e32 v102, 0x37800000, v101
	v_cndmask_b32_e32 v101, v101, v102, vcc
	v_cmp_class_f32_e32 vcc, v100, v206
	s_nop 1
	v_cndmask_b32_e32 v100, v101, v100, vcc
	v_div_scale_f32 v101, s[2:3], v100, v100, 1.0
	v_rcp_f32_e32 v102, v101
	v_div_scale_f32 v103, vcc, 1.0, v100, 1.0
	v_fma_f32 v104, -v101, v102, 1.0
	v_fmac_f32_e32 v102, v104, v102
	v_mul_f32_e32 v104, v103, v102
	v_fma_f32 v105, -v101, v104, v103
	v_fmac_f32_e32 v104, v105, v102
	v_fma_f32 v101, -v101, v104, v103
	v_div_fmas_f32 v101, v101, v102, v104
	v_div_fixup_f32 v100, v101, v100, 1.0
	s_and_b64 vcc, exec, s[36:37]
	v_pk_mul_f32 v[98:99], v[98:99], v[100:101] op_sel_hi:[1,0]
	v_pk_mul_f32 v[102:103], v[96:97], v[100:101] op_sel_hi:[1,0]
	v_pk_mul_f32 v[94:95], v[94:95], v[100:101] op_sel_hi:[1,0]
	v_pk_mul_f32 v[96:97], v[92:93], v[100:101] op_sel_hi:[1,0]
	s_cbranch_vccnz .LBB0_187
	v_and_b32_e32 v93, 0x7fffffff, v103
	v_and_b32_e32 v92, 0x7fffffff, v102
	v_pk_fma_f32 v[92:93], v[92:93], s[90:91], 1.0 op_sel_hi:[1,0,0]
	s_mov_b32 s2, 0xbf3a00e3
	v_rcp_f32_e32 v104, v92
	v_rcp_f32_e32 v105, v93
	v_mov_b64_e32 v[92:93], s[2:3]
	v_pk_mul_f32 v[108:109], v[102:103], v[102:103]
	s_mov_b32 s2, 0xbf38aa3b
	v_pk_fma_f32 v[106:107], v[104:105], s[92:93], v[92:93] op_sel_hi:[1,0,0]
	v_pk_mul_f32 v[108:109], v[108:109], s[2:3] op_sel_hi:[1,0]
	v_pk_fma_f32 v[106:107], v[104:105], v[106:107], s[94:95] op_sel_hi:[1,1,0]
	v_exp_f32_e32 v108, v108
	v_exp_f32_e32 v109, v109
	v_pk_fma_f32 v[106:107], v[104:105], v[106:107], s[96:97] op_sel_hi:[1,1,0]
	v_cmp_gt_f32_e32 vcc, 0, v102
	v_pk_fma_f32 v[106:107], v[104:105], v[106:107], s[30:31] op_sel_hi:[1,1,0]
	s_nop 0
	v_pk_mul_f32 v[104:105], v[104:105], v[106:107]
	v_pk_mul_f32 v[106:107], v[98:99], v[98:99]
	v_pk_mul_f32 v[104:105], v[108:109], v[104:105]
	v_pk_mul_f32 v[106:107], v[106:107], s[2:3] op_sel_hi:[1,0]
	v_pk_mul_f32 v[108:109], v[102:103], v[104:105]
	v_pk_fma_f32 v[104:105], v[102:103], v[104:105], v[102:103] neg_lo:[1,0,0] neg_hi:[1,0,0]
	v_exp_f32_e32 v106, v106
	v_cndmask_b32_e32 v102, v104, v108, vcc
	v_cmp_gt_f32_e32 vcc, 0, v103
	v_and_b32_e32 v104, 0x7fffffff, v98
	v_exp_f32_e32 v107, v107
	v_cndmask_b32_e32 v103, v105, v109, vcc
	v_and_b32_e32 v105, 0x7fffffff, v99
	v_pk_fma_f32 v[104:105], v[104:105], s[90:91], 1.0 op_sel_hi:[1,0,0]
	v_cmp_gt_f32_e32 vcc, 0, v98
	v_rcp_f32_e32 v104, v104
	v_rcp_f32_e32 v105, v105
	s_nop 0
	v_pk_fma_f32 v[108:109], v[104:105], s[92:93], v[92:93] op_sel_hi:[1,0,0]
	s_nop 0
	v_pk_fma_f32 v[108:109], v[104:105], v[108:109], s[94:95] op_sel_hi:[1,1,0]
	s_nop 0
	v_pk_fma_f32 v[108:109], v[104:105], v[108:109], s[96:97] op_sel_hi:[1,1,0]
	s_nop 0
	v_pk_fma_f32 v[108:109], v[104:105], v[108:109], s[30:31] op_sel_hi:[1,1,0]
	s_nop 0
	v_pk_mul_f32 v[104:105], v[104:105], v[108:109]
	v_pk_mul_f32 v[108:109], v[96:97], v[96:97]
	v_pk_mul_f32 v[104:105], v[106:107], v[104:105]
	v_pk_mul_f32 v[108:109], v[108:109], s[2:3] op_sel_hi:[1,0]
	v_pk_mul_f32 v[106:107], v[98:99], v[104:105]
	v_pk_fma_f32 v[104:105], v[98:99], v[104:105], v[98:99] neg_lo:[1,0,0] neg_hi:[1,0,0]
	v_exp_f32_e32 v108, v108
	v_cndmask_b32_e32 v98, v104, v106, vcc
	v_cmp_gt_f32_e32 vcc, 0, v99
	v_and_b32_e32 v104, 0x7fffffff, v96
	v_exp_f32_e32 v109, v109
	v_cndmask_b32_e32 v99, v105, v107, vcc
	v_and_b32_e32 v105, 0x7fffffff, v97
	v_pk_fma_f32 v[104:105], v[104:105], s[90:91], 1.0 op_sel_hi:[1,0,0]
	v_cmp_gt_f32_e32 vcc, 0, v96
	v_rcp_f32_e32 v104, v104
	v_rcp_f32_e32 v105, v105
	s_nop 0
	v_pk_fma_f32 v[106:107], v[104:105], s[92:93], v[92:93] op_sel_hi:[1,0,0]
	s_nop 0
	v_pk_fma_f32 v[106:107], v[104:105], v[106:107], s[94:95] op_sel_hi:[1,1,0]
	s_nop 0
	v_pk_fma_f32 v[106:107], v[104:105], v[106:107], s[96:97] op_sel_hi:[1,1,0]
	s_nop 0
	v_pk_fma_f32 v[106:107], v[104:105], v[106:107], s[30:31] op_sel_hi:[1,1,0]
	s_nop 0
	v_pk_mul_f32 v[104:105], v[104:105], v[106:107]
	v_pk_mul_f32 v[106:107], v[94:95], v[94:95]
	v_pk_mul_f32 v[104:105], v[108:109], v[104:105]
	s_nop 0
	v_pk_mul_f32 v[108:109], v[96:97], v[104:105]
	v_pk_fma_f32 v[104:105], v[96:97], v[104:105], v[96:97] neg_lo:[1,0,0] neg_hi:[1,0,0]
	s_nop 0
	v_cndmask_b32_e32 v96, v104, v108, vcc
	v_cmp_gt_f32_e32 vcc, 0, v97
	v_and_b32_e32 v104, 0x7fffffff, v94
	s_nop 0
	v_cndmask_b32_e32 v97, v105, v109, vcc
	v_and_b32_e32 v105, 0x7fffffff, v95
	v_pk_fma_f32 v[104:105], v[104:105], s[90:91], 1.0 op_sel_hi:[1,0,0]
	v_cmp_gt_f32_e32 vcc, 0, v94
	v_rcp_f32_e32 v104, v104
	v_rcp_f32_e32 v105, v105
	s_nop 0
	v_pk_fma_f32 v[92:93], v[104:105], s[92:93], v[92:93] op_sel_hi:[1,0,0]
	s_nop 0
	v_pk_fma_f32 v[92:93], v[104:105], v[92:93], s[94:95] op_sel_hi:[1,1,0]
	s_nop 0
	v_pk_fma_f32 v[92:93], v[104:105], v[92:93], s[96:97] op_sel_hi:[1,1,0]
	s_nop 0
	v_pk_fma_f32 v[92:93], v[104:105], v[92:93], s[30:31] op_sel_hi:[1,1,0]
	s_nop 0
	v_pk_mul_f32 v[92:93], v[104:105], v[92:93]
	v_pk_mul_f32 v[104:105], v[106:107], s[2:3] op_sel_hi:[1,0]
	s_nop 0
	v_exp_f32_e32 v104, v104
	v_exp_f32_e32 v105, v105
	s_nop 0
	v_pk_mul_f32 v[92:93], v[104:105], v[92:93]
	s_nop 0
	v_pk_mul_f32 v[104:105], v[94:95], v[92:93]
	v_pk_fma_f32 v[92:93], v[94:95], v[92:93], v[94:95] neg_lo:[1,0,0] neg_hi:[1,0,0]
	s_nop 0
	v_cndmask_b32_e32 v94, v92, v104, vcc
	v_cmp_gt_f32_e32 vcc, 0, v95
	s_nop 1
	v_cndmask_b32_e32 v95, v93, v105, vcc

; __device__ __forceinline__ float ss_get(const ss_t* p) { const ss_t v = *p; return (float)(unsigned)(v >> 32) + (float)(unsigned)v * 2.3283064365386963e-10f; }
; __device__ __forceinline__ unsigned pkbf(float lo, float hi) { typedef float f2_t __attribute__((ext_vector_type(2))); typedef __bf16 b2_t __attribute__((ext_vector_type(2))); f2_t v = {lo, hi}; b2_t b = __builtin_convertvector(v, b2_t); return __builtin_bit_cast(unsigned, b); }
; __device__ __forceinline__ f32x2 gelu_pk(f32x2 v) {
;     const f32x2 av = __builtin_elementwise_abs(v), d = av * 0.2316418882f + 1.0f;
;     f32x2 t; t.x = __builtin_amdgcn_rcpf(d.x); t.y = __builtin_amdgcn_rcpf(d.y);
;     f32x2 q = t * 0.5307027145f + (-0.7265760135f); q = q * t + 0.7107068705f; q = q * t + (-0.142248368f); q = q * t + 0.127414796f; q = q * t;
;     const f32x2 s = (v * v) * (-0.72134752044f);
;     f32x2 e; e.x = __builtin_amdgcn_exp2f(s.x); e.y = __builtin_amdgcn_exp2f(s.y);
;     const f32x2 m = v * (q * e), r = v - m;
;     f32x2 o; o.x = v.x < 0.f ? m.x : r.x; o.y = v.y < 0.f ? m.y : r.y; return o;
; }
;     __device__ __forceinline__ void operator()(const f32x4 (&acc)[2][2][4][2], const Unit& u, int wr, int wc, int fr, int fq) const {
;         int row0 = u.pm * BM + wr * 64 + fr; asm volatile("" : "+v"(row0));     const int col0 = u.pn * BM + wc * 32 + 8 * fq; const bool act = u.pn < gelu_tiles;
; #pragma unroll
;         for (int ai = 0; ai < 2; ++ai)
; #pragma unroll
;             for (int m = 0; m < 4; ++m) { const int row = row0 + ai * HALF + m * 16; bf16_t* rowp = O + (size_t)row * ldc + col0;
;                 const float rs = 1.0f / sqrtf(ss_get(ssq + row) * (1.0f / 2048.f) + 1e-6f);
; #pragma unroll
;                 for (int bj = 0; bj < 2; ++bj) { f32x4 v0 = acc[ai][bj][m][0] * rs, v1 = acc[ai][bj][m][1] * rs;
;                     if (act) { f32x2 a = gelu_pk((f32x2){v0[0], v0[1]}), b = gelu_pk((f32x2){v0[2], v0[3]}), c = gelu_pk((f32x2){v1[0], v1[1]}), d = gelu_pk((f32x2){v1[2], v1[3]});
;                         v0 = (f32x4){a.x, a.y, b.x, b.y}; v1 = (f32x4){c.x, c.y, d.x, d.y}; }
;                     u32x4 w; w.x = pkbf(v0[0], v0[1]); w.y = pkbf(v0[2], v0[3]); w.z = pkbf(v1[0], v1[1]); w.w = pkbf(v1[2], v1[3]);
;                     *(u32x4*)(rowp + bj * HALF) = w; } }
.LBB0_189:
	v_cvt_pk_bf16_f32 v88, v88, v89
	v_cvt_pk_bf16_f32 v89, v90, v91
	v_cvt_pk_bf16_f32 v90, v84, v85
	v_cvt_pk_bf16_f32 v91, v86, v87
	global_store_dwordx4 v[92:93], v[88:91], off offset:256
	s_nop 1
	v_mov_b32_e32 v84, v176
	v_mov_b32_e32 v85, v177
	v_mov_b32_e32 v87, v2
	v_mov_b32_e32 v86, v85
	v_lshlrev_b64 v[86:87], s15, v[86:87]
	v_min_u32_e32 v85, 1, v86
	v_or_b32_e32 v85, v87, v85
	v_cvt_f32_u32_e32 v85, v85
	v_cvt_f32_u32_e32 v84, v84
	v_ldexp_f32 v85, v85, s52
	v_fmac_f32_e32 v85, 0x2f800000, v84
	v_fmamk_f32 v84, v85, 0x3a000000, v205
	v_mul_f32_e32 v85, 0x4f800000, v84
	v_cmp_gt_f32_e32 vcc, s97, v84
	s_nop 1
	v_cndmask_b32_e32 v84, v84, v85, vcc
	v_sqrt_f32_e32 v85, v84
	s_nop 0
	v_add_u32_e32 v86, -1, v85
	v_add_u32_e32 v87, 1, v85
	v_fma_f32 v88, -v86, v85, v84
	v_fma_f32 v89, -v87, v85, v84
	v_cmp_ge_f32_e64 s[2:3], 0, v88
	s_nop 1
	v_cndmask_b32_e64 v85, v85, v86, s[2:3]
	v_cmp_lt_f32_e64 s[2:3], 0, v89
	s_nop 1
	v_cndmask_b32_e64 v85, v85, v87, s[2:3]
	v_mul_f32_e32 v86, 0x37800000, v85
	v_cndmask_b32_e32 v85, v85, v86, vcc
	v_cmp_class_f32_e32 vcc, v84, v206
	s_nop 1
	v_cndmask_b32_e32 v84, v85, v84, vcc
	v_div_scale_f32 v85, s[2:3], v84, v84, 1.0
	v_rcp_f32_e32 v86, v85
	v_div_scale_f32 v87, vcc, 1.0, v84, 1.0
	v_fma_f32 v88, -v85, v86, 1.0
	v_fmac_f32_e32 v86, v88, v86
	v_mul_f32_e32 v88, v87, v86
	v_fma_f32 v89, -v85, v88, v87
	v_fmac_f32_e32 v88, v89, v86
	v_fma_f32 v85, -v85, v88, v87
	v_div_fmas_f32 v85, v85, v86, v88
	v_div_fixup_f32 v84, v85, v84, 1.0
	s_and_b64 vcc, exec, s[36:37]
	v_pk_mul_f32 v[82:83], v[82:83], v[84:85] op_sel_hi:[1,0]
	v_pk_mul_f32 v[86:87], v[80:81], v[84:85] op_sel_hi:[1,0]
	v_pk_mul_f32 v[78:79], v[78:79], v[84:85] op_sel_hi:[1,0]
	v_pk_mul_f32 v[80:81], v[76:77], v[84:85] op_sel_hi:[1,0]
	s_cbranch_vccnz .LBB0_191
	v_and_b32_e32 v77, 0x7fffffff, v87
	v_and_b32_e32 v76, 0x7fffffff, v86
	v_pk_fma_f32 v[76:77], v[76:77], s[90:91], 1.0 op_sel_hi:[1,0,0]
	s_mov_b32 s2, 0xbf3a00e3
	v_rcp_f32_e32 v88, v76
	v_rcp_f32_e32 v89, v77
	v_mov_b64_e32 v[76:77], s[2:3]
	v_pk_mul_f32 v[92:93], v[86:87], v[86:87]
	s_mov_b32 s2, 0xbf38aa3b
	v_pk_fma_f32 v[90:91], v[88:89], s[92:93], v[76:77] op_sel_hi:[1,0,0]
	v_pk_mul_f32 v[92:93], v[92:93], s[2:3] op_sel_hi:[1,0]
	v_pk_fma_f32 v[90:91], v[88:89], v[90:91], s[94:95] op_sel_hi:[1,1,0]
	v_exp_f32_e32 v92, v92
	v_exp_f32_e32 v93, v93
	v_pk_fma_f32 v[90:91], v[88:89], v[90:91], s[96:97] op_sel_hi:[1,1,0]
	v_cmp_gt_f32_e32 vcc, 0, v86
	v_pk_fma_f32 v[90:91], v[88:89], v[90:91], s[30:31] op_sel_hi:[1,1,0]
	s_nop 0
	v_pk_mul_f32 v[88:89], v[88:89], v[90:91]
	v_pk_mul_f32 v[90:91], v[82:83], v[82:83]
	v_pk_mul_f32 v[88:89], v[92:93], v[88:89]
	v_pk_mul_f32 v[90:91], v[90:91], s[2:3] op_sel_hi:[1,0]
	v_pk_mul_f32 v[92:93], v[86:87], v[88:89]
	v_pk_fma_f32 v[88:89], v[86:87], v[88:89], v[86:87] neg_lo:[1,0,0] neg_hi:[1,0,0]
	v_exp_f32_e32 v90, v90
	v_cndmask_b32_e32 v86, v88, v92, vcc
	v_cmp_gt_f32_e32 vcc, 0, v87
	v_and_b32_e32 v88, 0x7fffffff, v82
	v_exp_f32_e32 v91, v91
	v_cndmask_b32_e32 v87, v89, v93, vcc
	v_and_b32_e32 v89, 0x7fffffff, v83
	v_pk_fma_f32 v[88:89], v[88:89], s[90:91], 1.0 op_sel_hi:[1,0,0]
	v_cmp_gt_f32_e32 vcc, 0, v82
	v_rcp_f32_e32 v88, v88
	v_rcp_f32_e32 v89, v89
	s_nop 0
	v_pk_fma_f32 v[92:93], v[88:89], s[92:93], v[76:77] op_sel_hi:[1,0,0]
	s_nop 0
	v_pk_fma_f32 v[92:93], v[88:89], v[92:93], s[94:95] op_sel_hi:[1,1,0]
	s_nop 0
	v_pk_fma_f32 v[92:93], v[88:89], v[92:93], s[96:97] op_sel_hi:[1,1,0]
	s_nop 0
	v_pk_fma_f32 v[92:93], v[88:89], v[92:93], s[30:31] op_sel_hi:[1,1,0]
	s_nop 0
	v_pk_mul_f32 v[88:89], v[88:89], v[92:93]
	v_pk_mul_f32 v[92:93], v[80:81], v[80:81]
	v_pk_mul_f32 v[88:89], v[90:91], v[88:89]
	v_pk_mul_f32 v[92:93], v[92:93], s[2:3] op_sel_hi:[1,0]
	v_pk_mul_f32 v[90:91], v[82:83], v[88:89]
	v_pk_fma_f32 v[88:89], v[82:83], v[88:89], v[82:83] neg_lo:[1,0,0] neg_hi:[1,0,0]
	v_exp_f32_e32 v92, v92
	v_cndmask_b32_e32 v82, v88, v90, vcc
	v_cmp_gt_f32_e32 vcc, 0, v83
	v_and_b32_e32 v88, 0x7fffffff, v80
	v_exp_f32_e32 v93, v93
	v_cndmask_b32_e32 v83, v89, v91, vcc
	v_and_b32_e32 v89, 0x7fffffff, v81
	v_pk_fma_f32 v[88:89], v[88:89], s[90:91], 1.0 op_sel_hi:[1,0,0]
	v_cmp_gt_f32_e32 vcc, 0, v80
	v_rcp_f32_e32 v88, v88
	v_rcp_f32_e32 v89, v89
	s_nop 0
	v_pk_fma_f32 v[90:91], v[88:89], s[92:93], v[76:77] op_sel_hi:[1,0,0]
	s_nop 0
	v_pk_fma_f32 v[90:91], v[88:89], v[90:91], s[94:95] op_sel_hi:[1,1,0]
	s_nop 0
	v_pk_fma_f32 v[90:91], v[88:89], v[90:91], s[96:97] op_sel_hi:[1,1,0]
	s_nop 0
	v_pk_fma_f32 v[90:91], v[88:89], v[90:91], s[30:31] op_sel_hi:[1,1,0]
	s_nop 0
	v_pk_mul_f32 v[88:89], v[88:89], v[90:91]
	v_pk_mul_f32 v[90:91], v[78:79], v[78:79]
	v_pk_mul_f32 v[88:89], v[92:93], v[88:89]
	s_nop 0
	v_pk_mul_f32 v[92:93], v[80:81], v[88:89]
	v_pk_fma_f32 v[88:89], v[80:81], v[88:89], v[80:81] neg_lo:[1,0,0] neg_hi:[1,0,0]
	s_nop 0
	v_cndmask_b32_e32 v80, v88, v92, vcc
	v_cmp_gt_f32_e32 vcc, 0, v81
	v_and_b32_e32 v88, 0x7fffffff, v78
	s_nop 0
	v_cndmask_b32_e32 v81, v89, v93, vcc
	v_and_b32_e32 v89, 0x7fffffff, v79
	v_pk_fma_f32 v[88:89], v[88:89], s[90:91], 1.0 op_sel_hi:[1,0,0]
	v_cmp_gt_f32_e32 vcc, 0, v78
	v_rcp_f32_e32 v88, v88
	v_rcp_f32_e32 v89, v89
	s_nop 0
	v_pk_fma_f32 v[76:77], v[88:89], s[92:93], v[76:77] op_sel_hi:[1,0,0]
	s_nop 0
	v_pk_fma_f32 v[76:77], v[88:89], v[76:77], s[94:95] op_sel_hi:[1,1,0]
	s_nop 0
	v_pk_fma_f32 v[76:77], v[88:89], v[76:77], s[96:97] op_sel_hi:[1,1,0]
	s_nop 0
	v_pk_fma_f32 v[76:77], v[88:89], v[76:77], s[30:31] op_sel_hi:[1,1,0]
	s_nop 0
	v_pk_mul_f32 v[76:77], v[88:89], v[76:77]
	v_pk_mul_f32 v[88:89], v[90:91], s[2:3] op_sel_hi:[1,0]
	s_nop 0
	v_exp_f32_e32 v88, v88
	v_exp_f32_e32 v89, v89
	s_nop 0
	v_pk_mul_f32 v[76:77], v[88:89], v[76:77]
	s_nop 0
	v_pk_mul_f32 v[88:89], v[78:79], v[76:77]
	v_pk_fma_f32 v[76:77], v[78:79], v[76:77], v[78:79] neg_lo:[1,0,0] neg_hi:[1,0,0]
	s_nop 0
	v_cndmask_b32_e32 v78, v76, v88, vcc
	v_cmp_gt_f32_e32 vcc, 0, v79
	s_nop 1
	v_cndmask_b32_e32 v79, v77, v89, vcc

; __device__ __forceinline__ float ss_get(const ss_t* p) { const ss_t v = *p; return (float)(unsigned)(v >> 32) + (float)(unsigned)v * 2.3283064365386963e-10f; }
; __device__ __forceinline__ unsigned pkbf(float lo, float hi) { typedef float f2_t __attribute__((ext_vector_type(2))); typedef __bf16 b2_t __attribute__((ext_vector_type(2))); f2_t v = {lo, hi}; b2_t b = __builtin_convertvector(v, b2_t); return __builtin_bit_cast(unsigned, b); }
; __device__ __forceinline__ f32x2 gelu_pk(f32x2 v) {
;     const f32x2 av = __builtin_elementwise_abs(v), d = av * 0.2316418882f + 1.0f;
;     f32x2 t; t.x = __builtin_amdgcn_rcpf(d.x); t.y = __builtin_amdgcn_rcpf(d.y);
;     f32x2 q = t * 0.5307027145f + (-0.7265760135f); q = q * t + 0.7107068705f; q = q * t + (-0.142248368f); q = q * t + 0.127414796f; q = q * t;
;     const f32x2 s = (v * v) * (-0.72134752044f);
;     f32x2 e; e.x = __builtin_amdgcn_exp2f(s.x); e.y = __builtin_amdgcn_exp2f(s.y);
;     const f32x2 m = v * (q * e), r = v - m;
;     f32x2 o; o.x = v.x < 0.f ? m.x : r.x; o.y = v.y < 0.f ? m.y : r.y; return o;
; }
;     __device__ __forceinline__ void operator()(const f32x4 (&acc)[2][2][4][2], const Unit& u, int wr, int wc, int fr, int fq) const {
;         int row0 = u.pm * BM + wr * 64 + fr; asm volatile("" : "+v"(row0));     const int col0 = u.pn * BM + wc * 32 + 8 * fq; const bool act = u.pn < gelu_tiles;
; #pragma unroll
;         for (int ai = 0; ai < 2; ++ai)
; #pragma unroll
;             for (int m = 0; m < 4; ++m) { const int row = row0 + ai * HALF + m * 16; bf16_t* rowp = O + (size_t)row * ldc + col0;
;                 const float rs = 1.0f / sqrtf(ss_get(ssq + row) * (1.0f / 2048.f) + 1e-6f);
; #pragma unroll
;                 for (int bj = 0; bj < 2; ++bj) { f32x4 v0 = acc[ai][bj][m][0] * rs, v1 = acc[ai][bj][m][1] * rs;
;                     if (act) { f32x2 a = gelu_pk((f32x2){v0[0], v0[1]}), b = gelu_pk((f32x2){v0[2], v0[3]}), c = gelu_pk((f32x2){v1[0], v1[1]}), d = gelu_pk((f32x2){v1[2], v1[3]});
;                         v0 = (f32x4){a.x, a.y, b.x, b.y}; v1 = (f32x4){c.x, c.y, d.x, d.y}; }
;                     u32x4 w; w.x = pkbf(v0[0], v0[1]); w.y = pkbf(v0[2], v0[3]); w.z = pkbf(v1[0], v1[1]); w.w = pkbf(v1[2], v1[3]);
;                     *(u32x4*)(rowp + bj * HALF) = w; } }
.LBB0_193:
	v_cvt_pk_bf16_f32 v72, v72, v73
	v_cvt_pk_bf16_f32 v73, v74, v75
	v_cvt_pk_bf16_f32 v74, v68, v69
	v_cvt_pk_bf16_f32 v75, v70, v71
	global_store_dwordx4 v[76:77], v[72:75], off offset:256
	s_nop 1
	v_mov_b32_e32 v68, v178
	v_mov_b32_e32 v69, v179
	v_mov_b32_e32 v71, v2
	v_mov_b32_e32 v70, v69
	v_lshlrev_b64 v[70:71], s15, v[70:71]
	v_min_u32_e32 v69, 1, v70
	v_or_b32_e32 v69, v71, v69
	v_cvt_f32_u32_e32 v69, v69
	v_cvt_f32_u32_e32 v68, v68
	v_ldexp_f32 v69, v69, s52
	v_fmac_f32_e32 v69, 0x2f800000, v68
	v_fmamk_f32 v68, v69, 0x3a000000, v205
	v_mul_f32_e32 v69, 0x4f800000, v68
	v_cmp_gt_f32_e32 vcc, s97, v68
	s_nop 1
	v_cndmask_b32_e32 v68, v68, v69, vcc
	v_sqrt_f32_e32 v69, v68
	s_nop 0
	v_add_u32_e32 v70, -1, v69
	v_add_u32_e32 v71, 1, v69
	v_fma_f32 v72, -v70, v69, v68
	v_fma_f32 v73, -v71, v69, v68
	v_cmp_ge_f32_e64 s[2:3], 0, v72
	s_nop 1
	v_cndmask_b32_e64 v69, v69, v70, s[2:3]
	v_cmp_lt_f32_e64 s[2:3], 0, v73
	s_nop 1
	v_cndmask_b32_e64 v69, v69, v71, s[2:3]
	v_mul_f32_e32 v70, 0x37800000, v69
	v_cndmask_b32_e32 v69, v69, v70, vcc
	v_cmp_class_f32_e32 vcc, v68, v206
	s_nop 1
	v_cndmask_b32_e32 v68, v69, v68, vcc
	v_div_scale_f32 v69, s[2:3], v68, v68, 1.0
	v_rcp_f32_e32 v70, v69
	v_div_scale_f32 v71, vcc, 1.0, v68, 1.0
	v_fma_f32 v72, -v69, v70, 1.0
	v_fmac_f32_e32 v70, v72, v70
	v_mul_f32_e32 v72, v71, v70
	v_fma_f32 v73, -v69, v72, v71
	v_fmac_f32_e32 v72, v73, v70
	v_fma_f32 v69, -v69, v72, v71
	v_div_fmas_f32 v69, v69, v70, v72
	v_div_fixup_f32 v68, v69, v68, 1.0
	s_and_b64 vcc, exec, s[36:37]
	v_pk_mul_f32 v[66:67], v[66:67], v[68:69] op_sel_hi:[1,0]
	v_pk_mul_f32 v[70:71], v[64:65], v[68:69] op_sel_hi:[1,0]
	v_pk_mul_f32 v[62:63], v[62:63], v[68:69] op_sel_hi:[1,0]
	v_pk_mul_f32 v[64:65], v[60:61], v[68:69] op_sel_hi:[1,0]
	s_cbranch_vccnz .LBB0_195
	v_and_b32_e32 v61, 0x7fffffff, v71
	v_and_b32_e32 v60, 0x7fffffff, v70
	v_pk_fma_f32 v[60:61], v[60:61], s[90:91], 1.0 op_sel_hi:[1,0,0]
	s_mov_b32 s2, 0xbf3a00e3
	v_rcp_f32_e32 v72, v60
	v_rcp_f32_e32 v73, v61
	v_mov_b64_e32 v[60:61], s[2:3]
	v_pk_mul_f32 v[76:77], v[70:71], v[70:71]
	s_mov_b32 s2, 0xbf38aa3b
	v_pk_fma_f32 v[74:75], v[72:73], s[92:93], v[60:61] op_sel_hi:[1,0,0]
	v_pk_mul_f32 v[76:77], v[76:77], s[2:3] op_sel_hi:[1,0]
	v_pk_fma_f32 v[74:75], v[72:73], v[74:75], s[94:95] op_sel_hi:[1,1,0]
	v_exp_f32_e32 v76, v76
	v_exp_f32_e32 v77, v77
	v_pk_fma_f32 v[74:75], v[72:73], v[74:75], s[96:97] op_sel_hi:[1,1,0]
	v_cmp_gt_f32_e32 vcc, 0, v70
	v_pk_fma_f32 v[74:75], v[72:73], v[74:75], s[30:31] op_sel_hi:[1,1,0]
	s_nop 0
	v_pk_mul_f32 v[72:73], v[72:73], v[74:75]
	v_pk_mul_f32 v[74:75], v[66:67], v[66:67]
	v_pk_mul_f32 v[72:73], v[76:77], v[72:73]
	v_pk_mul_f32 v[74:75], v[74:75], s[2:3] op_sel_hi:[1,0]
	v_pk_mul_f32 v[76:77], v[70:71], v[72:73]
	v_pk_fma_f32 v[72:73], v[70:71], v[72:73], v[70:71] neg_lo:[1,0,0] neg_hi:[1,0,0]
	v_exp_f32_e32 v74, v74
	v_cndmask_b32_e32 v70, v72, v76, vcc
	v_cmp_gt_f32_e32 vcc, 0, v71
	v_and_b32_e32 v72, 0x7fffffff, v66
	v_exp_f32_e32 v75, v75
	v_cndmask_b32_e32 v71, v73, v77, vcc
	v_and_b32_e32 v73, 0x7fffffff, v67
	v_pk_fma_f32 v[72:73], v[72:73], s[90:91], 1.0 op_sel_hi:[1,0,0]
	v_cmp_gt_f32_e32 vcc, 0, v66
	v_rcp_f32_e32 v72, v72
	v_rcp_f32_e32 v73, v73
	s_nop 0
	v_pk_fma_f32 v[76:77], v[72:73], s[92:93], v[60:61] op_sel_hi:[1,0,0]
	s_nop 0
	v_pk_fma_f32 v[76:77], v[72:73], v[76:77], s[94:95] op_sel_hi:[1,1,0]
	s_nop 0
	v_pk_fma_f32 v[76:77], v[72:73], v[76:77], s[96:97] op_sel_hi:[1,1,0]
	s_nop 0
	v_pk_fma_f32 v[76:77], v[72:73], v[76:77], s[30:31] op_sel_hi:[1,1,0]
	s_nop 0
	v_pk_mul_f32 v[72:73], v[72:73], v[76:77]
	v_pk_mul_f32 v[76:77], v[64:65], v[64:65]
	v_pk_mul_f32 v[72:73], v[74:75], v[72:73]
	v_pk_mul_f32 v[76:77], v[76:77], s[2:3] op_sel_hi:[1,0]
	v_pk_mul_f32 v[74:75], v[66:67], v[72:73]
	v_pk_fma_f32 v[72:73], v[66:67], v[72:73], v[66:67] neg_lo:[1,0,0] neg_hi:[1,0,0]
	v_exp_f32_e32 v76, v76
	v_cndmask_b32_e32 v66, v72, v74, vcc
	v_cmp_gt_f32_e32 vcc, 0, v67
	v_and_b32_e32 v72, 0x7fffffff, v64
	v_exp_f32_e32 v77, v77
	v_cndmask_b32_e32 v67, v73, v75, vcc
	v_and_b32_e32 v73, 0x7fffffff, v65
	v_pk_fma_f32 v[72:73], v[72:73], s[90:91], 1.0 op_sel_hi:[1,0,0]
	v_cmp_gt_f32_e32 vcc, 0, v64
	v_rcp_f32_e32 v72, v72
	v_rcp_f32_e32 v73, v73
	s_nop 0
	v_pk_fma_f32 v[74:75], v[72:73], s[92:93], v[60:61] op_sel_hi:[1,0,0]
	s_nop 0
	v_pk_fma_f32 v[74:75], v[72:73], v[74:75], s[94:95] op_sel_hi:[1,1,0]
	s_nop 0
	v_pk_fma_f32 v[74:75], v[72:73], v[74:75], s[96:97] op_sel_hi:[1,1,0]
	s_nop 0
	v_pk_fma_f32 v[74:75], v[72:73], v[74:75], s[30:31] op_sel_hi:[1,1,0]
	s_nop 0
	v_pk_mul_f32 v[72:73], v[72:73], v[74:75]
	v_pk_mul_f32 v[74:75], v[62:63], v[62:63]
	v_pk_mul_f32 v[72:73], v[76:77], v[72:73]
	s_nop 0
	v_pk_mul_f32 v[76:77], v[64:65], v[72:73]
	v_pk_fma_f32 v[72:73], v[64:65], v[72:73], v[64:65] neg_lo:[1,0,0] neg_hi:[1,0,0]
	s_nop 0
	v_cndmask_b32_e32 v64, v72, v76, vcc
	v_cmp_gt_f32_e32 vcc, 0, v65
	v_and_b32_e32 v72, 0x7fffffff, v62
	s_nop 0
	v_cndmask_b32_e32 v65, v73, v77, vcc
	v_and_b32_e32 v73, 0x7fffffff, v63
	v_pk_fma_f32 v[72:73], v[72:73], s[90:91], 1.0 op_sel_hi:[1,0,0]
	v_cmp_gt_f32_e32 vcc, 0, v62
	v_rcp_f32_e32 v72, v72
	v_rcp_f32_e32 v73, v73
	s_nop 0
	v_pk_fma_f32 v[60:61], v[72:73], s[92:93], v[60:61] op_sel_hi:[1,0,0]
	s_nop 0
	v_pk_fma_f32 v[60:61], v[72:73], v[60:61], s[94:95] op_sel_hi:[1,1,0]
	s_nop 0
	v_pk_fma_f32 v[60:61], v[72:73], v[60:61], s[96:97] op_sel_hi:[1,1,0]
	s_nop 0
	v_pk_fma_f32 v[60:61], v[72:73], v[60:61], s[30:31] op_sel_hi:[1,1,0]
	s_nop 0
	v_pk_mul_f32 v[60:61], v[72:73], v[60:61]
	v_pk_mul_f32 v[72:73], v[74:75], s[2:3] op_sel_hi:[1,0]
	s_nop 0
	v_exp_f32_e32 v72, v72
	v_exp_f32_e32 v73, v73
	s_nop 0
	v_pk_mul_f32 v[60:61], v[72:73], v[60:61]
	s_nop 0
	v_pk_mul_f32 v[72:73], v[62:63], v[60:61]
	v_pk_fma_f32 v[60:61], v[62:63], v[60:61], v[62:63] neg_lo:[1,0,0] neg_hi:[1,0,0]
	s_nop 0
	v_cndmask_b32_e32 v62, v60, v72, vcc
	v_cmp_gt_f32_e32 vcc, 0, v63
	s_nop 1
	v_cndmask_b32_e32 v63, v61, v73, vcc

; __device__ __forceinline__ float ss_get(const ss_t* p) { const ss_t v = *p; return (float)(unsigned)(v >> 32) + (float)(unsigned)v * 2.3283064365386963e-10f; }
; __device__ __forceinline__ unsigned pkbf(float lo, float hi) { typedef float f2_t __attribute__((ext_vector_type(2))); typedef __bf16 b2_t __attribute__((ext_vector_type(2))); f2_t v = {lo, hi}; b2_t b = __builtin_convertvector(v, b2_t); return __builtin_bit_cast(unsigned, b); }
; __device__ __forceinline__ f32x2 gelu_pk(f32x2 v) {
;     const f32x2 av = __builtin_elementwise_abs(v), d = av * 0.2316418882f + 1.0f;
;     f32x2 t; t.x = __builtin_amdgcn_rcpf(d.x); t.y = __builtin_amdgcn_rcpf(d.y);
;     f32x2 q = t * 0.5307027145f + (-0.7265760135f); q = q * t + 0.7107068705f; q = q * t + (-0.142248368f); q = q * t + 0.127414796f; q = q * t;
;     const f32x2 s = (v * v) * (-0.72134752044f);
;     f32x2 e; e.x = __builtin_amdgcn_exp2f(s.x); e.y = __builtin_amdgcn_exp2f(s.y);
;     const f32x2 m = v * (q * e), r = v - m;
;     f32x2 o; o.x = v.x < 0.f ? m.x : r.x; o.y = v.y < 0.f ? m.y : r.y; return o;
; }
;     __device__ __forceinline__ void operator()(const f32x4 (&acc)[2][2][4][2], const Unit& u, int wr, int wc, int fr, int fq) const {
;         int row0 = u.pm * BM + wr * 64 + fr; asm volatile("" : "+v"(row0));     const int col0 = u.pn * BM + wc * 32 + 8 * fq; const bool act = u.pn < gelu_tiles;
; #pragma unroll
;         for (int ai = 0; ai < 2; ++ai)
; #pragma unroll
;             for (int m = 0; m < 4; ++m) { const int row = row0 + ai * HALF + m * 16; bf16_t* rowp = O + (size_t)row * ldc + col0;
;                 const float rs = 1.0f / sqrtf(ss_get(ssq + row) * (1.0f / 2048.f) + 1e-6f);
; #pragma unroll
;                 for (int bj = 0; bj < 2; ++bj) { f32x4 v0 = acc[ai][bj][m][0] * rs, v1 = acc[ai][bj][m][1] * rs;
;                     if (act) { f32x2 a = gelu_pk((f32x2){v0[0], v0[1]}), b = gelu_pk((f32x2){v0[2], v0[3]}), c = gelu_pk((f32x2){v1[0], v1[1]}), d = gelu_pk((f32x2){v1[2], v1[3]});
;                         v0 = (f32x4){a.x, a.y, b.x, b.y}; v1 = (f32x4){c.x, c.y, d.x, d.y}; }
;                     u32x4 w; w.x = pkbf(v0[0], v0[1]); w.y = pkbf(v0[2], v0[3]); w.z = pkbf(v1[0], v1[1]); w.w = pkbf(v1[2], v1[3]);
;                     *(u32x4*)(rowp + bj * HALF) = w; } }
.LBB0_197:
	v_cvt_pk_bf16_f32 v56, v56, v57
	v_cvt_pk_bf16_f32 v57, v58, v59
	v_cvt_pk_bf16_f32 v58, v52, v53
	v_cvt_pk_bf16_f32 v59, v54, v55
	global_store_dwordx4 v[60:61], v[56:59], off offset:256
	s_nop 1
	v_mov_b32_e32 v52, v180
	v_mov_b32_e32 v53, v181
	v_mov_b32_e32 v55, v2
	v_mov_b32_e32 v54, v53
	v_lshlrev_b64 v[54:55], s15, v[54:55]
	v_min_u32_e32 v53, 1, v54
	v_or_b32_e32 v53, v55, v53
	v_cvt_f32_u32_e32 v53, v53
	v_cvt_f32_u32_e32 v52, v52
	v_ldexp_f32 v53, v53, s52
	v_fmac_f32_e32 v53, 0x2f800000, v52
	v_fmamk_f32 v52, v53, 0x3a000000, v205
	v_mul_f32_e32 v53, 0x4f800000, v52
	v_cmp_gt_f32_e32 vcc, s97, v52
	s_nop 1
	v_cndmask_b32_e32 v52, v52, v53, vcc
	v_sqrt_f32_e32 v53, v52
	s_nop 0
	v_add_u32_e32 v54, -1, v53
	v_add_u32_e32 v55, 1, v53
	v_fma_f32 v56, -v54, v53, v52
	v_fma_f32 v57, -v55, v53, v52
	v_cmp_ge_f32_e64 s[2:3], 0, v56
	s_nop 1
	v_cndmask_b32_e64 v53, v53, v54, s[2:3]
	v_cmp_lt_f32_e64 s[2:3], 0, v57
	s_nop 1
	v_cndmask_b32_e64 v53, v53, v55, s[2:3]
	v_mul_f32_e32 v54, 0x37800000, v53
	v_cndmask_b32_e32 v53, v53, v54, vcc
	v_cmp_class_f32_e32 vcc, v52, v206
	s_nop 1
	v_cndmask_b32_e32 v52, v53, v52, vcc
	v_div_scale_f32 v53, s[2:3], v52, v52, 1.0
	v_rcp_f32_e32 v54, v53
	v_div_scale_f32 v55, vcc, 1.0, v52, 1.0
	v_fma_f32 v56, -v53, v54, 1.0
	v_fmac_f32_e32 v54, v56, v54
	v_mul_f32_e32 v56, v55, v54
	v_fma_f32 v57, -v53, v56, v55
	v_fmac_f32_e32 v56, v57, v54
	v_fma_f32 v53, -v53, v56, v55
	v_div_fmas_f32 v53, v53, v54, v56
	v_div_fixup_f32 v52, v53, v52, 1.0
	s_and_b64 vcc, exec, s[36:37]
	v_pk_mul_f32 v[50:51], v[50:51], v[52:53] op_sel_hi:[1,0]
	v_pk_mul_f32 v[54:55], v[48:49], v[52:53] op_sel_hi:[1,0]
	v_pk_mul_f32 v[46:47], v[46:47], v[52:53] op_sel_hi:[1,0]
	v_pk_mul_f32 v[48:49], v[44:45], v[52:53] op_sel_hi:[1,0]
	s_cbranch_vccnz .LBB0_199
	v_and_b32_e32 v45, 0x7fffffff, v55
	v_and_b32_e32 v44, 0x7fffffff, v54
	v_pk_fma_f32 v[44:45], v[44:45], s[90:91], 1.0 op_sel_hi:[1,0,0]
	s_mov_b32 s2, 0xbf3a00e3
	v_rcp_f32_e32 v56, v44
	v_rcp_f32_e32 v57, v45
	v_mov_b64_e32 v[44:45], s[2:3]
	v_pk_mul_f32 v[60:61], v[54:55], v[54:55]
	s_mov_b32 s2, 0xbf38aa3b
	v_pk_fma_f32 v[58:59], v[56:57], s[92:93], v[44:45] op_sel_hi:[1,0,0]
	v_pk_mul_f32 v[60:61], v[60:61], s[2:3] op_sel_hi:[1,0]
	v_pk_fma_f32 v[58:59], v[56:57], v[58:59], s[94:95] op_sel_hi:[1,1,0]
	v_exp_f32_e32 v60, v60
	v_exp_f32_e32 v61, v61
	v_pk_fma_f32 v[58:59], v[56:57], v[58:59], s[96:97] op_sel_hi:[1,1,0]
	v_cmp_gt_f32_e32 vcc, 0, v54
	v_pk_fma_f32 v[58:59], v[56:57], v[58:59], s[30:31] op_sel_hi:[1,1,0]
	s_nop 0
	v_pk_mul_f32 v[56:57], v[56:57], v[58:59]
	v_pk_mul_f32 v[58:59], v[50:51], v[50:51]
	v_pk_mul_f32 v[56:57], v[60:61], v[56:57]
	v_pk_mul_f32 v[58:59], v[58:59], s[2:3] op_sel_hi:[1,0]
	v_pk_mul_f32 v[60:61], v[54:55], v[56:57]
	v_pk_fma_f32 v[56:57], v[54:55], v[56:57], v[54:55] neg_lo:[1,0,0] neg_hi:[1,0,0]
	v_exp_f32_e32 v58, v58
	v_cndmask_b32_e32 v54, v56, v60, vcc
	v_cmp_gt_f32_e32 vcc, 0, v55
	v_and_b32_e32 v56, 0x7fffffff, v50
	v_exp_f32_e32 v59, v59
	v_cndmask_b32_e32 v55, v57, v61, vcc
	v_and_b32_e32 v57, 0x7fffffff, v51
	v_pk_fma_f32 v[56:57], v[56:57], s[90:91], 1.0 op_sel_hi:[1,0,0]
	v_cmp_gt_f32_e32 vcc, 0, v50
	v_rcp_f32_e32 v56, v56
	v_rcp_f32_e32 v57, v57
	s_nop 0
	v_pk_fma_f32 v[60:61], v[56:57], s[92:93], v[44:45] op_sel_hi:[1,0,0]
	s_nop 0
	v_pk_fma_f32 v[60:61], v[56:57], v[60:61], s[94:95] op_sel_hi:[1,1,0]
	s_nop 0
	v_pk_fma_f32 v[60:61], v[56:57], v[60:61], s[96:97] op_sel_hi:[1,1,0]
	s_nop 0
	v_pk_fma_f32 v[60:61], v[56:57], v[60:61], s[30:31] op_sel_hi:[1,1,0]
	s_nop 0
	v_pk_mul_f32 v[56:57], v[56:57], v[60:61]
	v_pk_mul_f32 v[60:61], v[48:49], v[48:49]
	v_pk_mul_f32 v[56:57], v[58:59], v[56:57]
	v_pk_mul_f32 v[60:61], v[60:61], s[2:3] op_sel_hi:[1,0]
	v_pk_mul_f32 v[58:59], v[50:51], v[56:57]
	v_pk_fma_f32 v[56:57], v[50:51], v[56:57], v[50:51] neg_lo:[1,0,0] neg_hi:[1,0,0]
	v_exp_f32_e32 v60, v60
	v_cndmask_b32_e32 v50, v56, v58, vcc
	v_cmp_gt_f32_e32 vcc, 0, v51
	v_and_b32_e32 v56, 0x7fffffff, v48
	v_exp_f32_e32 v61, v61
	v_cndmask_b32_e32 v51, v57, v59, vcc
	v_and_b32_e32 v57, 0x7fffffff, v49
	v_pk_fma_f32 v[56:57], v[56:57], s[90:91], 1.0 op_sel_hi:[1,0,0]
	v_cmp_gt_f32_e32 vcc, 0, v48
	v_rcp_f32_e32 v56, v56
	v_rcp_f32_e32 v57, v57
	s_nop 0
	v_pk_fma_f32 v[58:59], v[56:57], s[92:93], v[44:45] op_sel_hi:[1,0,0]
	s_nop 0
	v_pk_fma_f32 v[58:59], v[56:57], v[58:59], s[94:95] op_sel_hi:[1,1,0]
	s_nop 0
	v_pk_fma_f32 v[58:59], v[56:57], v[58:59], s[96:97] op_sel_hi:[1,1,0]
	s_nop 0
	v_pk_fma_f32 v[58:59], v[56:57], v[58:59], s[30:31] op_sel_hi:[1,1,0]
	s_nop 0
	v_pk_mul_f32 v[56:57], v[56:57], v[58:59]
	v_pk_mul_f32 v[58:59], v[46:47], v[46:47]
	v_pk_mul_f32 v[56:57], v[60:61], v[56:57]
	s_nop 0
	v_pk_mul_f32 v[60:61], v[48:49], v[56:57]
	v_pk_fma_f32 v[56:57], v[48:49], v[56:57], v[48:49] neg_lo:[1,0,0] neg_hi:[1,0,0]
	s_nop 0
	v_cndmask_b32_e32 v48, v56, v60, vcc
	v_cmp_gt_f32_e32 vcc, 0, v49
	v_and_b32_e32 v56, 0x7fffffff, v46
	s_nop 0
	v_cndmask_b32_e32 v49, v57, v61, vcc
	v_and_b32_e32 v57, 0x7fffffff, v47
	v_pk_fma_f32 v[56:57], v[56:57], s[90:91], 1.0 op_sel_hi:[1,0,0]
	v_cmp_gt_f32_e32 vcc, 0, v46
	v_rcp_f32_e32 v56, v56
	v_rcp_f32_e32 v57, v57
	s_nop 0
	v_pk_fma_f32 v[44:45], v[56:57], s[92:93], v[44:45] op_sel_hi:[1,0,0]
	s_nop 0
	v_pk_fma_f32 v[44:45], v[56:57], v[44:45], s[94:95] op_sel_hi:[1,1,0]
	s_nop 0
	v_pk_fma_f32 v[44:45], v[56:57], v[44:45], s[96:97] op_sel_hi:[1,1,0]
	s_nop 0
	v_pk_fma_f32 v[44:45], v[56:57], v[44:45], s[30:31] op_sel_hi:[1,1,0]
	s_nop 0
	v_pk_mul_f32 v[44:45], v[56:57], v[44:45]
	v_pk_mul_f32 v[56:57], v[58:59], s[2:3] op_sel_hi:[1,0]
	s_nop 0
	v_exp_f32_e32 v56, v56
	v_exp_f32_e32 v57, v57
	s_nop 0
	v_pk_mul_f32 v[44:45], v[56:57], v[44:45]
	s_nop 0
	v_pk_mul_f32 v[56:57], v[46:47], v[44:45]
	v_pk_fma_f32 v[44:45], v[46:47], v[44:45], v[46:47] neg_lo:[1,0,0] neg_hi:[1,0,0]
	s_nop 0
	v_cndmask_b32_e32 v46, v44, v56, vcc
	v_cmp_gt_f32_e32 vcc, 0, v47
	s_nop 1
	v_cndmask_b32_e32 v47, v45, v57, vcc

; __device__ __forceinline__ float ss_get(const ss_t* p) { const ss_t v = *p; return (float)(unsigned)(v >> 32) + (float)(unsigned)v * 2.3283064365386963e-10f; }
; __device__ __forceinline__ unsigned pkbf(float lo, float hi) { typedef float f2_t __attribute__((ext_vector_type(2))); typedef __bf16 b2_t __attribute__((ext_vector_type(2))); f2_t v = {lo, hi}; b2_t b = __builtin_convertvector(v, b2_t); return __builtin_bit_cast(unsigned, b); }
; __device__ __forceinline__ f32x2 gelu_pk(f32x2 v) {
;     const f32x2 av = __builtin_elementwise_abs(v), d = av * 0.2316418882f + 1.0f;
;     f32x2 t; t.x = __builtin_amdgcn_rcpf(d.x); t.y = __builtin_amdgcn_rcpf(d.y);
;     f32x2 q = t * 0.5307027145f + (-0.7265760135f); q = q * t + 0.7107068705f; q = q * t + (-0.142248368f); q = q * t + 0.127414796f; q = q * t;
;     const f32x2 s = (v * v) * (-0.72134752044f);
;     f32x2 e; e.x = __builtin_amdgcn_exp2f(s.x); e.y = __builtin_amdgcn_exp2f(s.y);
;     const f32x2 m = v * (q * e), r = v - m;
;     f32x2 o; o.x = v.x < 0.f ? m.x : r.x; o.y = v.y < 0.f ? m.y : r.y; return o;
; }
;     __device__ __forceinline__ void operator()(const f32x4 (&acc)[2][2][4][2], const Unit& u, int wr, int wc, int fr, int fq) const {
;         int row0 = u.pm * BM + wr * 64 + fr; asm volatile("" : "+v"(row0));     const int col0 = u.pn * BM + wc * 32 + 8 * fq; const bool act = u.pn < gelu_tiles;
; #pragma unroll
;         for (int ai = 0; ai < 2; ++ai)
; #pragma unroll
;             for (int m = 0; m < 4; ++m) { const int row = row0 + ai * HALF + m * 16; bf16_t* rowp = O + (size_t)row * ldc + col0;
;                 const float rs = 1.0f / sqrtf(ss_get(ssq + row) * (1.0f / 2048.f) + 1e-6f);
; #pragma unroll
;                 for (int bj = 0; bj < 2; ++bj) { f32x4 v0 = acc[ai][bj][m][0] * rs, v1 = acc[ai][bj][m][1] * rs;
;                     if (act) { f32x2 a = gelu_pk((f32x2){v0[0], v0[1]}), b = gelu_pk((f32x2){v0[2], v0[3]}), c = gelu_pk((f32x2){v1[0], v1[1]}), d = gelu_pk((f32x2){v1[2], v1[3]});
;                         v0 = (f32x4){a.x, a.y, b.x, b.y}; v1 = (f32x4){c.x, c.y, d.x, d.y}; }
;                     u32x4 w; w.x = pkbf(v0[0], v0[1]); w.y = pkbf(v0[2], v0[3]); w.z = pkbf(v1[0], v1[1]); w.w = pkbf(v1[2], v1[3]);
;                     *(u32x4*)(rowp + bj * HALF) = w; } }
.LBB0_201:
	v_cvt_pk_bf16_f32 v40, v40, v41
	v_cvt_pk_bf16_f32 v41, v42, v43
	v_cvt_pk_bf16_f32 v42, v36, v37
	v_cvt_pk_bf16_f32 v43, v38, v39
	global_store_dwordx4 v[44:45], v[40:43], off offset:256
	s_nop 1
	v_mov_b32_e32 v36, v182
	v_mov_b32_e32 v37, v183
	v_mov_b32_e32 v39, v2
	v_mov_b32_e32 v38, v37
	v_lshlrev_b64 v[38:39], s15, v[38:39]
	v_min_u32_e32 v37, 1, v38
	v_or_b32_e32 v37, v39, v37
	v_cvt_f32_u32_e32 v37, v37
	v_cvt_f32_u32_e32 v36, v36
	v_ldexp_f32 v37, v37, s52
	v_fmac_f32_e32 v37, 0x2f800000, v36
	v_fmamk_f32 v36, v37, 0x3a000000, v205
	v_mul_f32_e32 v37, 0x4f800000, v36
	v_cmp_gt_f32_e32 vcc, s97, v36
	s_nop 1
	v_cndmask_b32_e32 v36, v36, v37, vcc
	v_sqrt_f32_e32 v37, v36
	s_nop 0
	v_add_u32_e32 v38, -1, v37
	v_add_u32_e32 v39, 1, v37
	v_fma_f32 v40, -v38, v37, v36
	v_fma_f32 v41, -v39, v37, v36
	v_cmp_ge_f32_e64 s[2:3], 0, v40
	s_nop 1
	v_cndmask_b32_e64 v37, v37, v38, s[2:3]
	v_cmp_lt_f32_e64 s[2:3], 0, v41
	s_nop 1
	v_cndmask_b32_e64 v37, v37, v39, s[2:3]
	v_mul_f32_e32 v38, 0x37800000, v37
	v_cndmask_b32_e32 v37, v37, v38, vcc
	v_cmp_class_f32_e32 vcc, v36, v206
	s_nop 1
	v_cndmask_b32_e32 v36, v37, v36, vcc
	v_div_scale_f32 v37, s[2:3], v36, v36, 1.0
	v_rcp_f32_e32 v38, v37
	v_div_scale_f32 v39, vcc, 1.0, v36, 1.0
	v_fma_f32 v40, -v37, v38, 1.0
	v_fmac_f32_e32 v38, v40, v38
	v_mul_f32_e32 v40, v39, v38
	v_fma_f32 v41, -v37, v40, v39
	v_fmac_f32_e32 v40, v41, v38
	v_fma_f32 v37, -v37, v40, v39
	v_div_fmas_f32 v37, v37, v38, v40
	v_div_fixup_f32 v36, v37, v36, 1.0
	s_and_b64 vcc, exec, s[36:37]
	v_pk_mul_f32 v[34:35], v[34:35], v[36:37] op_sel_hi:[1,0]
	v_pk_mul_f32 v[38:39], v[32:33], v[36:37] op_sel_hi:[1,0]
	v_pk_mul_f32 v[30:31], v[30:31], v[36:37] op_sel_hi:[1,0]
	v_pk_mul_f32 v[32:33], v[28:29], v[36:37] op_sel_hi:[1,0]
	s_cbranch_vccnz .LBB0_203
	v_and_b32_e32 v29, 0x7fffffff, v39
	v_and_b32_e32 v28, 0x7fffffff, v38
	v_pk_fma_f32 v[28:29], v[28:29], s[90:91], 1.0 op_sel_hi:[1,0,0]
	s_mov_b32 s2, 0xbf3a00e3
	v_rcp_f32_e32 v40, v28
	v_rcp_f32_e32 v41, v29
	v_mov_b64_e32 v[28:29], s[2:3]
	v_pk_mul_f32 v[44:45], v[38:39], v[38:39]
	s_mov_b32 s2, 0xbf38aa3b
	v_pk_fma_f32 v[42:43], v[40:41], s[92:93], v[28:29] op_sel_hi:[1,0,0]
	v_pk_mul_f32 v[44:45], v[44:45], s[2:3] op_sel_hi:[1,0]
	v_pk_fma_f32 v[42:43], v[40:41], v[42:43], s[94:95] op_sel_hi:[1,1,0]
	v_exp_f32_e32 v44, v44
	v_exp_f32_e32 v45, v45
	v_pk_fma_f32 v[42:43], v[40:41], v[42:43], s[96:97] op_sel_hi:[1,1,0]
	v_cmp_gt_f32_e32 vcc, 0, v38
	v_pk_fma_f32 v[42:43], v[40:41], v[42:43], s[30:31] op_sel_hi:[1,1,0]
	s_nop 0
	v_pk_mul_f32 v[40:41], v[40:41], v[42:43]
	v_pk_mul_f32 v[42:43], v[34:35], v[34:35]
	v_pk_mul_f32 v[40:41], v[44:45], v[40:41]
	v_pk_mul_f32 v[42:43], v[42:43], s[2:3] op_sel_hi:[1,0]
	v_pk_mul_f32 v[44:45], v[38:39], v[40:41]
	v_pk_fma_f32 v[40:41], v[38:39], v[40:41], v[38:39] neg_lo:[1,0,0] neg_hi:[1,0,0]
	v_exp_f32_e32 v42, v42
	v_cndmask_b32_e32 v38, v40, v44, vcc
	v_cmp_gt_f32_e32 vcc, 0, v39
	v_and_b32_e32 v40, 0x7fffffff, v34
	v_exp_f32_e32 v43, v43
	v_cndmask_b32_e32 v39, v41, v45, vcc
	v_and_b32_e32 v41, 0x7fffffff, v35
	v_pk_fma_f32 v[40:41], v[40:41], s[90:91], 1.0 op_sel_hi:[1,0,0]
	v_cmp_gt_f32_e32 vcc, 0, v34
	v_rcp_f32_e32 v40, v40
	v_rcp_f32_e32 v41, v41
	s_nop 0
	v_pk_fma_f32 v[44:45], v[40:41], s[92:93], v[28:29] op_sel_hi:[1,0,0]
	s_nop 0
	v_pk_fma_f32 v[44:45], v[40:41], v[44:45], s[94:95] op_sel_hi:[1,1,0]
	s_nop 0
	v_pk_fma_f32 v[44:45], v[40:41], v[44:45], s[96:97] op_sel_hi:[1,1,0]
	s_nop 0
	v_pk_fma_f32 v[44:45], v[40:41], v[44:45], s[30:31] op_sel_hi:[1,1,0]
	s_nop 0
	v_pk_mul_f32 v[40:41], v[40:41], v[44:45]
	v_pk_mul_f32 v[44:45], v[32:33], v[32:33]
	v_pk_mul_f32 v[40:41], v[42:43], v[40:41]
	v_pk_mul_f32 v[44:45], v[44:45], s[2:3] op_sel_hi:[1,0]
	v_pk_mul_f32 v[42:43], v[34:35], v[40:41]
	v_pk_fma_f32 v[40:41], v[34:35], v[40:41], v[34:35] neg_lo:[1,0,0] neg_hi:[1,0,0]
	v_exp_f32_e32 v44, v44
	v_cndmask_b32_e32 v34, v40, v42, vcc
	v_cmp_gt_f32_e32 vcc, 0, v35
	v_and_b32_e32 v40, 0x7fffffff, v32
	v_exp_f32_e32 v45, v45
	v_cndmask_b32_e32 v35, v41, v43, vcc
	v_and_b32_e32 v41, 0x7fffffff, v33
	v_pk_fma_f32 v[40:41], v[40:41], s[90:91], 1.0 op_sel_hi:[1,0,0]
	v_cmp_gt_f32_e32 vcc, 0, v32
	v_rcp_f32_e32 v40, v40
	v_rcp_f32_e32 v41, v41
	s_nop 0
	v_pk_fma_f32 v[42:43], v[40:41], s[92:93], v[28:29] op_sel_hi:[1,0,0]
	s_nop 0
	v_pk_fma_f32 v[42:43], v[40:41], v[42:43], s[94:95] op_sel_hi:[1,1,0]
	s_nop 0
	v_pk_fma_f32 v[42:43], v[40:41], v[42:43], s[96:97] op_sel_hi:[1,1,0]
	s_nop 0
	v_pk_fma_f32 v[42:43], v[40:41], v[42:43], s[30:31] op_sel_hi:[1,1,0]
	s_nop 0
	v_pk_mul_f32 v[40:41], v[40:41], v[42:43]
	v_pk_mul_f32 v[42:43], v[30:31], v[30:31]
	v_pk_mul_f32 v[40:41], v[44:45], v[40:41]
	s_nop 0
	v_pk_mul_f32 v[44:45], v[32:33], v[40:41]
	v_pk_fma_f32 v[40:41], v[32:33], v[40:41], v[32:33] neg_lo:[1,0,0] neg_hi:[1,0,0]
	s_nop 0
	v_cndmask_b32_e32 v32, v40, v44, vcc
	v_cmp_gt_f32_e32 vcc, 0, v33
	v_and_b32_e32 v40, 0x7fffffff, v30
	s_nop 0
	v_cndmask_b32_e32 v33, v41, v45, vcc
	v_and_b32_e32 v41, 0x7fffffff, v31
	v_pk_fma_f32 v[40:41], v[40:41], s[90:91], 1.0 op_sel_hi:[1,0,0]
	v_cmp_gt_f32_e32 vcc, 0, v30
	v_rcp_f32_e32 v40, v40
	v_rcp_f32_e32 v41, v41
	s_nop 0
	v_pk_fma_f32 v[28:29], v[40:41], s[92:93], v[28:29] op_sel_hi:[1,0,0]
	s_nop 0
	v_pk_fma_f32 v[28:29], v[40:41], v[28:29], s[94:95] op_sel_hi:[1,1,0]
	s_nop 0
	v_pk_fma_f32 v[28:29], v[40:41], v[28:29], s[96:97] op_sel_hi:[1,1,0]
	s_nop 0
	v_pk_fma_f32 v[28:29], v[40:41], v[28:29], s[30:31] op_sel_hi:[1,1,0]
	s_nop 0
	v_pk_mul_f32 v[28:29], v[40:41], v[28:29]
	v_pk_mul_f32 v[40:41], v[42:43], s[2:3] op_sel_hi:[1,0]
	s_nop 0
	v_exp_f32_e32 v40, v40
	v_exp_f32_e32 v41, v41
	s_nop 0
	v_pk_mul_f32 v[28:29], v[40:41], v[28:29]
	s_nop 0
	v_pk_mul_f32 v[40:41], v[30:31], v[28:29]
	v_pk_fma_f32 v[28:29], v[30:31], v[28:29], v[30:31] neg_lo:[1,0,0] neg_hi:[1,0,0]
	s_nop 0
	v_cndmask_b32_e32 v30, v28, v40, vcc
	v_cmp_gt_f32_e32 vcc, 0, v31
	s_nop 1
	v_cndmask_b32_e32 v31, v29, v41, vcc

; __device__ __forceinline__ float ss_get(const ss_t* p) { const ss_t v = *p; return (float)(unsigned)(v >> 32) + (float)(unsigned)v * 2.3283064365386963e-10f; }
; __device__ __forceinline__ unsigned pkbf(float lo, float hi) { typedef float f2_t __attribute__((ext_vector_type(2))); typedef __bf16 b2_t __attribute__((ext_vector_type(2))); f2_t v = {lo, hi}; b2_t b = __builtin_convertvector(v, b2_t); return __builtin_bit_cast(unsigned, b); }
; __device__ __forceinline__ f32x2 gelu_pk(f32x2 v) {
;     const f32x2 av = __builtin_elementwise_abs(v), d = av * 0.2316418882f + 1.0f;
;     f32x2 t; t.x = __builtin_amdgcn_rcpf(d.x); t.y = __builtin_amdgcn_rcpf(d.y);
;     f32x2 q = t * 0.5307027145f + (-0.7265760135f); q = q * t + 0.7107068705f; q = q * t + (-0.142248368f); q = q * t + 0.127414796f; q = q * t;
;     const f32x2 s = (v * v) * (-0.72134752044f);
;     f32x2 e; e.x = __builtin_amdgcn_exp2f(s.x); e.y = __builtin_amdgcn_exp2f(s.y);
;     const f32x2 m = v * (q * e), r = v - m;
;     f32x2 o; o.x = v.x < 0.f ? m.x : r.x; o.y = v.y < 0.f ? m.y : r.y; return o;
; }
;     __device__ __forceinline__ void operator()(const f32x4 (&acc)[2][2][4][2], const Unit& u, int wr, int wc, int fr, int fq) const {
;         int row0 = u.pm * BM + wr * 64 + fr; asm volatile("" : "+v"(row0));     const int col0 = u.pn * BM + wc * 32 + 8 * fq; const bool act = u.pn < gelu_tiles;
; #pragma unroll
;         for (int ai = 0; ai < 2; ++ai)
; #pragma unroll
;             for (int m = 0; m < 4; ++m) { const int row = row0 + ai * HALF + m * 16; bf16_t* rowp = O + (size_t)row * ldc + col0;
;                 const float rs = 1.0f / sqrtf(ss_get(ssq + row) * (1.0f / 2048.f) + 1e-6f);
; #pragma unroll
;                 for (int bj = 0; bj < 2; ++bj) { f32x4 v0 = acc[ai][bj][m][0] * rs, v1 = acc[ai][bj][m][1] * rs;
;                     if (act) { f32x2 a = gelu_pk((f32x2){v0[0], v0[1]}), b = gelu_pk((f32x2){v0[2], v0[3]}), c = gelu_pk((f32x2){v1[0], v1[1]}), d = gelu_pk((f32x2){v1[2], v1[3]});
;                         v0 = (f32x4){a.x, a.y, b.x, b.y}; v1 = (f32x4){c.x, c.y, d.x, d.y}; }
;                     u32x4 w; w.x = pkbf(v0[0], v0[1]); w.y = pkbf(v0[2], v0[3]); w.z = pkbf(v1[0], v1[1]); w.w = pkbf(v1[2], v1[3]);
;                     *(u32x4*)(rowp + bj * HALF) = w; } }
.LBB0_205:
	v_cvt_pk_bf16_f32 v24, v24, v25
	v_cvt_pk_bf16_f32 v25, v26, v27
	v_cvt_pk_bf16_f32 v26, v20, v21
	v_cvt_pk_bf16_f32 v27, v22, v23
	global_store_dwordx4 v[28:29], v[24:27], off offset:256
	s_nop 1
	v_mov_b32_e32 v20, v184
	v_mov_b32_e32 v21, v185
	v_mov_b32_e32 v23, v2
	v_mov_b32_e32 v22, v21
	v_lshlrev_b64 v[22:23], s15, v[22:23]
	v_min_u32_e32 v21, 1, v22
	v_or_b32_e32 v21, v23, v21
	v_cvt_f32_u32_e32 v21, v21
	v_cvt_f32_u32_e32 v20, v20
	v_ldexp_f32 v21, v21, s52
	v_fmac_f32_e32 v21, 0x2f800000, v20
	v_fmamk_f32 v20, v21, 0x3a000000, v205
	v_mul_f32_e32 v21, 0x4f800000, v20
	v_cmp_gt_f32_e32 vcc, s97, v20
	s_nop 1
	v_cndmask_b32_e32 v20, v20, v21, vcc
	v_sqrt_f32_e32 v21, v20
	s_nop 0
	v_add_u32_e32 v22, -1, v21
	v_add_u32_e32 v23, 1, v21
	v_fma_f32 v24, -v22, v21, v20
	v_fma_f32 v25, -v23, v21, v20
	v_cmp_ge_f32_e64 s[2:3], 0, v24
	s_nop 1
	v_cndmask_b32_e64 v21, v21, v22, s[2:3]
	v_cmp_lt_f32_e64 s[2:3], 0, v25
	s_nop 1
	v_cndmask_b32_e64 v21, v21, v23, s[2:3]
	v_mul_f32_e32 v22, 0x37800000, v21
	v_cndmask_b32_e32 v21, v21, v22, vcc
	v_cmp_class_f32_e32 vcc, v20, v206
	s_nop 1
	v_cndmask_b32_e32 v20, v21, v20, vcc
	v_div_scale_f32 v21, s[2:3], v20, v20, 1.0
	v_rcp_f32_e32 v22, v21
	v_div_scale_f32 v23, vcc, 1.0, v20, 1.0
	v_fma_f32 v24, -v21, v22, 1.0
	v_fmac_f32_e32 v22, v24, v22
	v_mul_f32_e32 v24, v23, v22
	v_fma_f32 v25, -v21, v24, v23
	v_fmac_f32_e32 v24, v25, v22
	v_fma_f32 v21, -v21, v24, v23
	v_div_fmas_f32 v21, v21, v22, v24
	v_div_fixup_f32 v20, v21, v20, 1.0
	s_and_b64 vcc, exec, s[36:37]
	v_pk_mul_f32 v[18:19], v[18:19], v[20:21] op_sel_hi:[1,0]
	v_pk_mul_f32 v[22:23], v[16:17], v[20:21] op_sel_hi:[1,0]
	v_pk_mul_f32 v[14:15], v[14:15], v[20:21] op_sel_hi:[1,0]
	v_pk_mul_f32 v[16:17], v[12:13], v[20:21] op_sel_hi:[1,0]
	s_cbranch_vccnz .LBB0_207
	v_and_b32_e32 v13, 0x7fffffff, v23
	v_and_b32_e32 v12, 0x7fffffff, v22
	v_pk_fma_f32 v[12:13], v[12:13], s[90:91], 1.0 op_sel_hi:[1,0,0]
	s_mov_b32 s2, 0xbf3a00e3
	v_rcp_f32_e32 v24, v12
	v_rcp_f32_e32 v25, v13
	v_mov_b64_e32 v[12:13], s[2:3]
	v_pk_mul_f32 v[28:29], v[22:23], v[22:23]
	s_mov_b32 s2, 0xbf38aa3b
	v_pk_fma_f32 v[26:27], v[24:25], s[92:93], v[12:13] op_sel_hi:[1,0,0]
	v_pk_mul_f32 v[28:29], v[28:29], s[2:3] op_sel_hi:[1,0]
	v_pk_fma_f32 v[26:27], v[24:25], v[26:27], s[94:95] op_sel_hi:[1,1,0]
	v_exp_f32_e32 v28, v28
	v_exp_f32_e32 v29, v29
	v_pk_fma_f32 v[26:27], v[24:25], v[26:27], s[96:97] op_sel_hi:[1,1,0]
	v_cmp_gt_f32_e32 vcc, 0, v22
	v_pk_fma_f32 v[26:27], v[24:25], v[26:27], s[30:31] op_sel_hi:[1,1,0]
	s_nop 0
	v_pk_mul_f32 v[24:25], v[24:25], v[26:27]
	v_pk_mul_f32 v[26:27], v[18:19], v[18:19]
	v_pk_mul_f32 v[24:25], v[28:29], v[24:25]
	v_pk_mul_f32 v[26:27], v[26:27], s[2:3] op_sel_hi:[1,0]
	v_pk_mul_f32 v[28:29], v[22:23], v[24:25]
	v_pk_fma_f32 v[24:25], v[22:23], v[24:25], v[22:23] neg_lo:[1,0,0] neg_hi:[1,0,0]
	v_exp_f32_e32 v26, v26
	v_cndmask_b32_e32 v22, v24, v28, vcc
	v_cmp_gt_f32_e32 vcc, 0, v23
	v_and_b32_e32 v24, 0x7fffffff, v18
	v_exp_f32_e32 v27, v27
	v_cndmask_b32_e32 v23, v25, v29, vcc
	v_and_b32_e32 v25, 0x7fffffff, v19
	v_pk_fma_f32 v[24:25], v[24:25], s[90:91], 1.0 op_sel_hi:[1,0,0]
	v_cmp_gt_f32_e32 vcc, 0, v18
	v_rcp_f32_e32 v24, v24
	v_rcp_f32_e32 v25, v25
	s_nop 0
	v_pk_fma_f32 v[28:29], v[24:25], s[92:93], v[12:13] op_sel_hi:[1,0,0]
	s_nop 0
	v_pk_fma_f32 v[28:29], v[24:25], v[28:29], s[94:95] op_sel_hi:[1,1,0]
	s_nop 0
	v_pk_fma_f32 v[28:29], v[24:25], v[28:29], s[96:97] op_sel_hi:[1,1,0]
	s_nop 0
	v_pk_fma_f32 v[28:29], v[24:25], v[28:29], s[30:31] op_sel_hi:[1,1,0]
	s_nop 0
	v_pk_mul_f32 v[24:25], v[24:25], v[28:29]
	v_pk_mul_f32 v[28:29], v[16:17], v[16:17]
	v_pk_mul_f32 v[24:25], v[26:27], v[24:25]
	v_pk_mul_f32 v[28:29], v[28:29], s[2:3] op_sel_hi:[1,0]
	v_pk_mul_f32 v[26:27], v[18:19], v[24:25]
	v_pk_fma_f32 v[24:25], v[18:19], v[24:25], v[18:19] neg_lo:[1,0,0] neg_hi:[1,0,0]
	v_exp_f32_e32 v28, v28
	v_cndmask_b32_e32 v18, v24, v26, vcc
	v_cmp_gt_f32_e32 vcc, 0, v19
	v_and_b32_e32 v24, 0x7fffffff, v16
	v_exp_f32_e32 v29, v29
	v_cndmask_b32_e32 v19, v25, v27, vcc
	v_and_b32_e32 v25, 0x7fffffff, v17
	v_pk_fma_f32 v[24:25], v[24:25], s[90:91], 1.0 op_sel_hi:[1,0,0]
	v_cmp_gt_f32_e32 vcc, 0, v16
	v_rcp_f32_e32 v24, v24
	v_rcp_f32_e32 v25, v25
	s_nop 0
	v_pk_fma_f32 v[26:27], v[24:25], s[92:93], v[12:13] op_sel_hi:[1,0,0]
	s_nop 0
	v_pk_fma_f32 v[26:27], v[24:25], v[26:27], s[94:95] op_sel_hi:[1,1,0]
	s_nop 0
	v_pk_fma_f32 v[26:27], v[24:25], v[26:27], s[96:97] op_sel_hi:[1,1,0]
	s_nop 0
	v_pk_fma_f32 v[26:27], v[24:25], v[26:27], s[30:31] op_sel_hi:[1,1,0]
	s_nop 0
	v_pk_mul_f32 v[24:25], v[24:25], v[26:27]
	v_pk_mul_f32 v[26:27], v[14:15], v[14:15]
	v_pk_mul_f32 v[24:25], v[28:29], v[24:25]
	s_nop 0
	v_pk_mul_f32 v[28:29], v[16:17], v[24:25]
	v_pk_fma_f32 v[24:25], v[16:17], v[24:25], v[16:17] neg_lo:[1,0,0] neg_hi:[1,0,0]
	s_nop 0
	v_cndmask_b32_e32 v16, v24, v28, vcc
	v_cmp_gt_f32_e32 vcc, 0, v17
	v_and_b32_e32 v24, 0x7fffffff, v14
	s_nop 0
	v_cndmask_b32_e32 v17, v25, v29, vcc
	v_and_b32_e32 v25, 0x7fffffff, v15
	v_pk_fma_f32 v[24:25], v[24:25], s[90:91], 1.0 op_sel_hi:[1,0,0]
	v_cmp_gt_f32_e32 vcc, 0, v14
	v_rcp_f32_e32 v24, v24
	v_rcp_f32_e32 v25, v25
	s_nop 0
	v_pk_fma_f32 v[12:13], v[24:25], s[92:93], v[12:13] op_sel_hi:[1,0,0]
	s_nop 0
	v_pk_fma_f32 v[12:13], v[24:25], v[12:13], s[94:95] op_sel_hi:[1,1,0]
	s_nop 0
	v_pk_fma_f32 v[12:13], v[24:25], v[12:13], s[96:97] op_sel_hi:[1,1,0]
	s_nop 0
	v_pk_fma_f32 v[12:13], v[24:25], v[12:13], s[30:31] op_sel_hi:[1,1,0]
	s_nop 0
	v_pk_mul_f32 v[12:13], v[24:25], v[12:13]
	v_pk_mul_f32 v[24:25], v[26:27], s[2:3] op_sel_hi:[1,0]
	s_nop 0
	v_exp_f32_e32 v24, v24
	v_exp_f32_e32 v25, v25
	s_nop 0
	v_pk_mul_f32 v[12:13], v[24:25], v[12:13]
	s_nop 0
	v_pk_mul_f32 v[24:25], v[14:15], v[12:13]
	v_pk_fma_f32 v[12:13], v[14:15], v[12:13], v[14:15] neg_lo:[1,0,0] neg_hi:[1,0,0]
	s_nop 0
	v_cndmask_b32_e32 v14, v12, v24, vcc
	v_cmp_gt_f32_e32 vcc, 0, v15
	s_nop 1
	v_cndmask_b32_e32 v15, v13, v25, vcc

; #define PHASE_IDS() int tid = threadIdx.x; asm volatile("" : "+v"(tid)); const int lane = tid & 63, wid = __builtin_amdgcn_readfirstlane(tid >> 6), gw = bx * NWAVES + wid; (void)lane; (void)gw
; __device__ __forceinline__ void convert_items(const Args& A, unsigned char* ws, int g0, int g1, int w, int nw, float* scr, int lane) {
;     for (int it = g0 + w; it < g1; it += nw) {
;         const int l = it / PER_LAYER; int r = it % PER_LAYER;
;         if (r < I_IN) { const int nb = INW / 64, kb = r / nb, n0 = 64 * (r % nb); transpose_item(A.w_in + (size_t)l * DM * INW, DM, INW, (bf16*)(ws + WS_WIN + l * SZ_WIN), 64 * kb, n0, n0, A.norm1_g + l * DM + 64 * kb, scr, lane); continue; } r -= I_IN;
; __global__ void __launch_bounds__(NWAVES * 64, 2) fwd_kernel(Args A) {
;     ...
;         if (G == 256 && vc >= 192) {
;             PHASE_IDS(); const int g0 = Q_P + l * (Q_G1 + Q_G3), g1 = g0 + Q_G1;
;             convert_items(A, ws, g0 < N_ALL ? g0 : N_ALL, g1 < N_ALL ? g1 : N_ALL, (vc - 192) * NWAVES + wid, 64 * NWAVES, (float*)(lds + wid * TSCR), lane); }
.LBB0_213:
	v_readlane_b32 s2, v250, 60
	v_readlane_b32 s3, v250, 61
	v_readlane_b32 s40, v250, 12
	s_andn2_b64 vcc, exec, s[2:3]
	s_mul_i32 s81, s78, 0x2cec
	v_readlane_b32 s42, v250, 14
	v_readlane_b32 s43, v250, 15
	v_readlane_b32 s44, v250, 16
	v_readlane_b32 s45, v250, 17
	v_readlane_b32 s46, v250, 18
	v_readlane_b32 s47, v250, 19
	v_readlane_b32 s48, v250, 20
	v_readlane_b32 s49, v250, 21
	v_readlane_b32 s50, v250, 22
	v_readlane_b32 s51, v250, 23
	v_readlane_b32 s52, v250, 24
	v_readlane_b32 s53, v250, 25
	v_readlane_b32 s54, v250, 26
	v_readlane_b32 s55, v250, 27
	v_readlane_b32 s41, v250, 13
	s_cbranch_vccnz .LBB0_249
	v_mov_b32_e32 v4, v204
	v_readlane_b32 s3, v250, 62
	v_readfirstlane_b32 s2, v4
	s_ashr_i32 s2, s2, 6
	s_add_i32 s3, s3, s81
	s_add_i32 s8, s81, 0x251c
	s_add_i32 s9, s3, s2
	s_cmp_ge_i32 s9, s8
	s_cbranch_scc1 .LBB0_249
	v_lshlrev_b32_e32 v0, 2, v4
	s_mulk_i32 s2, 0x4100
	v_bfe_u32 v1, v4, 4, 2
	v_and_b32_e32 v0, 60, v0
	s_add_i32 s2, s2, 0
	v_lshlrev_b32_e32 v3, 2, v0
	s_waitcnt lgkmcnt(0)
	v_mul_u32_u24_e32 v5, 0x104, v1
	v_add3_u32 v3, s2, v3, v5
	v_and_b32_e32 v5, 7, v4
	v_bfe_u32 v13, v4, 3, 3
	v_lshlrev_b32_e32 v12, 3, v5
	v_mul_u32_u24_e32 v4, 0x820, v5
	v_lshlrev_b32_e32 v5, 2, v13
	v_add3_u32 v16, s2, v4, v5
	v_or_b32_e32 v17, 8, v13
	v_or_b32_e32 v18, 16, v13
	v_or_b32_e32 v19, 24, v13
	v_or_b32_e32 v20, 32, v13
	v_or_b32_e32 v21, 40, v13
	v_or_b32_e32 v22, 48, v13
	v_or_b32_e32 v23, 56, v13
	s_lshl_b32 s10, s9, 6
	s_lshl_b32 s11, s9, 1
	s_branch .LBB0_219

; __device__ __forceinline__ float ss_get(const ss_t* p) { const ss_t v = *p; return (float)(unsigned)(v >> 32) + (float)(unsigned)v * 2.3283064365386963e-10f; }
; __device__ __forceinline__ unsigned pkbf(float lo, float hi) { typedef float f2_t __attribute__((ext_vector_type(2))); typedef __bf16 b2_t __attribute__((ext_vector_type(2))); f2_t v = {lo, hi}; b2_t b = __builtin_convertvector(v, b2_t); return __builtin_bit_cast(unsigned, b); }
; __device__ __forceinline__ f32x2 swiglu_pk(f32x2 g, f32x2 u, float c1, float rs2) {
;     const f32x2 z = g * c1; f32x2 e; e.x = __builtin_amdgcn_exp2f(z.x); e.y = __builtin_amdgcn_exp2f(z.y);
;     const f32x2 d = e + 1.0f; f32x2 r; r.x = __builtin_amdgcn_rcpf(d.x); r.y = __builtin_amdgcn_rcpf(d.y);
;     return (g * u) * (r * rs2);
; }
;     __device__ __forceinline__ void operator()(const f32x4 (&acc)[2][2][4][2], const Unit& u, int wr, int wc, int fr, int fq) const {
;         int row0 = u.pm * BM + wr * 64 + fr; asm volatile("" : "+v"(row0));     const int col0 = u.pn * HALF + wc * 32 + 8 * fq;
; #pragma unroll
;         for (int ai = 0; ai < 2; ++ai)
; #pragma unroll
;             for (int m = 0; m < 4; ++m) { const int row = row0 + ai * HALF + m * 16; bf16_t* rowp = O + (size_t)row * ldc + col0;
;                 const float rs = 1.0f / sqrtf(ss_get(ssq + row) * (1.0f / 2048.f) + 1e-6f);
;                 const float c1 = -1.4426950408889634f * rs, rs2 = rs * rs;
;                 const f32x4 ga = acc[ai][0][m][0], gb = acc[ai][0][m][1], ua = acc[ai][1][m][0], ub = acc[ai][1][m][1];
;                 u32x4 w;
;                 { const f32x2 o = swiglu_pk((f32x2){ga[0], ga[1]}, (f32x2){ua[0], ua[1]}, c1, rs2); w.x = pkbf(o.x, o.y); }
;                 { const f32x2 o = swiglu_pk((f32x2){ga[2], ga[3]}, (f32x2){ua[2], ua[3]}, c1, rs2); w.y = pkbf(o.x, o.y); }
;                 { const f32x2 o = swiglu_pk((f32x2){gb[0], gb[1]}, (f32x2){ub[0], ub[1]}, c1, rs2); w.z = pkbf(o.x, o.y); }
;                 { const f32x2 o = swiglu_pk((f32x2){gb[2], gb[3]}, (f32x2){ub[2], ub[3]}, c1, rs2); w.w = pkbf(o.x, o.y); }
;                 *(u32x4*)rowp = w; }
.LBB0_1054:
	v_mov_b32_e32 v142, v148
	v_readlane_b32 s2, v247, 4
	v_ashrrev_i32_e32 v143, 31, v142
	v_lshl_add_u64 v[146:147], v[142:143], 3, s[4:5]
	global_load_dwordx2 v[152:153], v[146:147], off
	global_load_dwordx2 v[172:173], v[146:147], off offset:128
	global_load_dwordx2 v[174:175], v[146:147], off offset:256
	global_load_dwordx2 v[176:177], v[146:147], off offset:384
	global_load_dwordx2 v[178:179], v[146:147], off offset:1024
	global_load_dwordx2 v[180:181], v[146:147], off offset:1152
	global_load_dwordx2 v[182:183], v[146:147], off offset:1280
	global_load_dwordx2 v[184:185], v[146:147], off offset:1408
	v_readlane_b32 s3, v247, 5
	v_mov_b32_e32 v157, v2
	v_pk_mul_f32 v[158:159], v[116:117], v[124:125]
	v_mov_b64_e32 v[144:145], s[2:3]
	s_flbit_i32_b32 s2, 0
	s_min_u32 s13, s2, 32
	s_sub_i32 s36, 32, s13
	v_lshl_or_b32 v154, s52, 7, v149
	v_ashrrev_i32_e32 v155, 31, v154
	s_movk_i32 s16, 0x2c00
	v_pk_mul_f32 v[130:131], v[122:123], v[130:131]
	v_pk_mul_f32 v[128:129], v[120:121], v[128:129]
	v_pk_mul_f32 v[126:127], v[118:119], v[126:127]
	v_pk_mul_f32 v[114:115], v[106:107], v[114:115]
	v_pk_mul_f32 v[112:113], v[104:105], v[112:113]
	v_pk_mul_f32 v[110:111], v[102:103], v[110:111]
	v_pk_mul_f32 v[108:109], v[100:101], v[108:109]
	v_pk_mul_f32 v[98:99], v[90:91], v[98:99]
	v_pk_mul_f32 v[96:97], v[88:89], v[96:97]
	v_pk_mul_f32 v[94:95], v[86:87], v[94:95]
	v_pk_mul_f32 v[92:93], v[84:85], v[92:93]
	v_pk_mul_f32 v[82:83], v[74:75], v[82:83]
	v_pk_mul_f32 v[80:81], v[72:73], v[80:81]
	v_pk_mul_f32 v[78:79], v[70:71], v[78:79]
	v_pk_mul_f32 v[76:77], v[68:69], v[76:77]
	v_pk_mul_f32 v[66:67], v[58:59], v[66:67]
	v_pk_mul_f32 v[64:65], v[56:57], v[64:65]
	v_pk_mul_f32 v[62:63], v[54:55], v[62:63]
	v_pk_mul_f32 v[60:61], v[52:53], v[60:61]
	v_pk_mul_f32 v[50:51], v[42:43], v[50:51]
	v_pk_mul_f32 v[48:49], v[40:41], v[48:49]
	v_pk_mul_f32 v[46:47], v[38:39], v[46:47]
	v_pk_mul_f32 v[44:45], v[36:37], v[44:45]
	v_pk_mul_f32 v[34:35], v[26:27], v[34:35]
	v_pk_mul_f32 v[32:33], v[24:25], v[32:33]
	v_pk_mul_f32 v[30:31], v[22:23], v[30:31]
	v_pk_mul_f32 v[28:29], v[20:21], v[28:29]
	v_pk_mul_f32 v[18:19], v[10:11], v[18:19]
	v_pk_mul_f32 v[16:17], v[8:9], v[16:17]
	v_pk_mul_f32 v[14:15], v[6:7], v[14:15]
	v_pk_mul_f32 v[12:13], v[4:5], v[12:13]
	s_waitcnt vmcnt(0)
	v_mov_b32_e32 v156, v153
	v_lshlrev_b64 v[124:125], s13, v[156:157]
	v_min_u32_e32 v124, 1, v124
	v_or_b32_e32 v124, v125, v124
	v_cvt_f32_u32_e32 v124, v124
	v_cvt_f32_u32_e32 v125, v152
	v_mad_i64_i32 v[152:153], s[2:3], v142, s16, v[144:145]
	v_ldexp_f32 v124, v124, s36
	v_fmac_f32_e32 v124, 0x2f800000, v125
	v_fmamk_f32 v124, v124, 0x3a000000, v205
	v_mul_f32_e32 v125, 0x4f800000, v124
	v_cmp_gt_f32_e32 vcc, s97, v124
	s_nop 1
	v_cndmask_b32_e32 v143, v124, v125, vcc
	v_sqrt_f32_e32 v151, v143
	v_lshlrev_b64 v[124:125], 1, v[154:155]
	v_lshl_add_u64 v[152:153], v[152:153], 0, v[124:125]
	v_add_u32_e32 v154, -1, v151
	v_add_u32_e32 v155, 1, v151
	v_fma_f32 v156, -v154, v151, v143
	v_fma_f32 v157, -v155, v151, v143
	v_cmp_ge_f32_e64 s[2:3], 0, v156
	s_nop 1
	v_cndmask_b32_e64 v151, v151, v154, s[2:3]
	v_cmp_lt_f32_e64 s[2:3], 0, v157
	s_nop 1
	v_cndmask_b32_e64 v151, v151, v155, s[2:3]
	v_mul_f32_e32 v154, 0x37800000, v151
	v_cndmask_b32_e32 v151, v151, v154, vcc
	v_cmp_class_f32_e32 vcc, v143, v206
	s_nop 1
	v_cndmask_b32_e32 v143, v151, v143, vcc
	v_div_scale_f32 v151, s[2:3], v143, v143, 1.0
	v_rcp_f32_e32 v154, v151
	v_div_scale_f32 v155, vcc, 1.0, v143, 1.0
	v_fma_f32 v156, -v151, v154, 1.0
	v_fmac_f32_e32 v154, v156, v154
	v_mul_f32_e32 v156, v155, v154
	v_fma_f32 v157, -v151, v156, v155
	v_fmac_f32_e32 v156, v157, v154
	v_fma_f32 v151, -v151, v156, v155
	v_div_fmas_f32 v151, v151, v154, v156
	v_div_fixup_f32 v143, v151, v143, 1.0
	v_mul_f32_e32 v154, 0xbfb8aa3b, v143
	v_pk_mul_f32 v[120:121], v[120:121], v[154:155] op_sel_hi:[1,0]
	v_pk_mul_f32 v[122:123], v[122:123], v[154:155] op_sel_hi:[1,0]
	v_pk_mul_f32 v[116:117], v[116:117], v[154:155] op_sel_hi:[1,0]
	v_pk_mul_f32 v[118:119], v[118:119], v[154:155] op_sel_hi:[1,0]
	v_exp_f32_e32 v120, v120
	v_exp_f32_e32 v121, v121
	v_exp_f32_e32 v122, v122
	v_exp_f32_e32 v123, v123
	v_exp_f32_e32 v116, v116
	v_exp_f32_e32 v117, v117
	v_exp_f32_e32 v118, v118
	v_exp_f32_e32 v119, v119
	v_pk_add_f32 v[120:121], v[120:121], 1.0 op_sel_hi:[1,0]
	v_pk_add_f32 v[122:123], v[122:123], 1.0 op_sel_hi:[1,0]
	v_pk_add_f32 v[116:117], v[116:117], 1.0 op_sel_hi:[1,0]
	v_pk_add_f32 v[118:119], v[118:119], 1.0 op_sel_hi:[1,0]
	v_rcp_f32_e32 v120, v120
	v_rcp_f32_e32 v121, v121
	v_rcp_f32_e32 v122, v122
	v_rcp_f32_e32 v123, v123
	v_rcp_f32_e32 v116, v116
	v_rcp_f32_e32 v117, v117
	v_rcp_f32_e32 v118, v118
	v_rcp_f32_e32 v119, v119
	v_mul_f32_e32 v156, v143, v143
	v_pk_mul_f32 v[120:121], v[156:157], v[120:121] op_sel_hi:[0,1]
	v_pk_mul_f32 v[122:123], v[156:157], v[122:123] op_sel_hi:[0,1]
	v_pk_mul_f32 v[116:117], v[156:157], v[116:117] op_sel_hi:[0,1]
	v_pk_mul_f32 v[118:119], v[156:157], v[118:119] op_sel_hi:[0,1]
	v_pk_mul_f32 v[120:121], v[128:129], v[120:121]
	v_pk_mul_f32 v[122:123], v[130:131], v[122:123]
	v_pk_mul_f32 v[128:129], v[158:159], v[116:117]
	v_pk_mul_f32 v[126:127], v[126:127], v[118:119]
	v_cvt_pk_bf16_f32 v116, v120, v121
	v_cvt_pk_bf16_f32 v117, v122, v123
	v_cvt_pk_bf16_f32 v118, v128, v129
	v_cvt_pk_bf16_f32 v119, v126, v127
	global_store_dwordx4 v[152:153], v[116:119], off
	s_nop 1
	v_mov_b32_e32 v116, v172
	v_mov_b32_e32 v117, v173
	s_nop 0
	v_mov_b32_e32 v119, v2
	v_mov_b32_e32 v118, v117
	v_lshlrev_b64 v[118:119], s13, v[118:119]
	v_min_u32_e32 v117, 1, v118
	v_or_b32_e32 v117, v119, v117
	v_cvt_f32_u32_e32 v117, v117
; __device__ __forceinline__ float ss_get(const ss_t* p) { const ss_t v = *p; return (float)(unsigned)(v >> 32) + (float)(unsigned)v * 2.3283064365386963e-10f; }
; __device__ __forceinline__ unsigned pkbf(float lo, float hi) { typedef float f2_t __attribute__((ext_vector_type(2))); typedef __bf16 b2_t __attribute__((ext_vector_type(2))); f2_t v = {lo, hi}; b2_t b = __builtin_convertvector(v, b2_t); return __builtin_bit_cast(unsigned, b); }
; __device__ __forceinline__ f32x2 swiglu_pk(f32x2 g, f32x2 u, float c1, float rs2) {
;     const f32x2 z = g * c1; f32x2 e; e.x = __builtin_amdgcn_exp2f(z.x); e.y = __builtin_amdgcn_exp2f(z.y);
;     const f32x2 d = e + 1.0f; f32x2 r; r.x = __builtin_amdgcn_rcpf(d.x); r.y = __builtin_amdgcn_rcpf(d.y);
;     return (g * u) * (r * rs2);
; }
;     __device__ __forceinline__ void operator()(const f32x4 (&acc)[2][2][4][2], const Unit& u, int wr, int wc, int fr, int fq) const {
;         int row0 = u.pm * BM + wr * 64 + fr; asm volatile("" : "+v"(row0));     const int col0 = u.pn * HALF + wc * 32 + 8 * fq;
; #pragma unroll
;         for (int ai = 0; ai < 2; ++ai)
; #pragma unroll
;             for (int m = 0; m < 4; ++m) { const int row = row0 + ai * HALF + m * 16; bf16_t* rowp = O + (size_t)row * ldc + col0;
;                 const float rs = 1.0f / sqrtf(ss_get(ssq + row) * (1.0f / 2048.f) + 1e-6f);
;                 const float c1 = -1.4426950408889634f * rs, rs2 = rs * rs;
;                 const f32x4 ga = acc[ai][0][m][0], gb = acc[ai][0][m][1], ua = acc[ai][1][m][0], ub = acc[ai][1][m][1];
;                 u32x4 w;
;                 { const f32x2 o = swiglu_pk((f32x2){ga[0], ga[1]}, (f32x2){ua[0], ua[1]}, c1, rs2); w.x = pkbf(o.x, o.y); }
;                 { const f32x2 o = swiglu_pk((f32x2){ga[2], ga[3]}, (f32x2){ua[2], ua[3]}, c1, rs2); w.y = pkbf(o.x, o.y); }
;                 { const f32x2 o = swiglu_pk((f32x2){gb[0], gb[1]}, (f32x2){ub[0], ub[1]}, c1, rs2); w.z = pkbf(o.x, o.y); }
;                 { const f32x2 o = swiglu_pk((f32x2){gb[2], gb[3]}, (f32x2){ub[2], ub[3]}, c1, rs2); w.w = pkbf(o.x, o.y); }
;                 *(u32x4*)rowp = w; }
	v_cvt_f32_u32_e32 v116, v116
	v_ldexp_f32 v117, v117, s36
	v_fmac_f32_e32 v117, 0x2f800000, v116
	v_fmamk_f32 v116, v117, 0x3a000000, v205
	v_mul_f32_e32 v117, 0x4f800000, v116
	v_cmp_gt_f32_e32 vcc, s97, v116
	s_nop 1
	v_cndmask_b32_e32 v118, v116, v117, vcc
	v_sqrt_f32_e32 v119, v118
	v_add_u32_e32 v116, 16, v142
	v_mad_i64_i32 v[116:117], s[2:3], v116, s16, v[144:145]
	v_add_u32_e32 v120, -1, v119
	v_add_u32_e32 v121, 1, v119
	v_fma_f32 v122, -v120, v119, v118
	v_fma_f32 v123, -v121, v119, v118
	v_cmp_ge_f32_e64 s[2:3], 0, v122
	v_lshl_add_u64 v[116:117], v[116:117], 0, v[124:125]
	s_nop 0
	v_cndmask_b32_e64 v119, v119, v120, s[2:3]
	v_cmp_lt_f32_e64 s[2:3], 0, v123
	s_nop 1
	v_cndmask_b32_e64 v119, v119, v121, s[2:3]
	v_mul_f32_e32 v120, 0x37800000, v119
	v_cndmask_b32_e32 v119, v119, v120, vcc
	v_cmp_class_f32_e32 vcc, v118, v206
	s_nop 1
	v_cndmask_b32_e32 v118, v119, v118, vcc
	v_div_scale_f32 v119, s[2:3], v118, v118, 1.0
	v_rcp_f32_e32 v120, v119
	v_div_scale_f32 v121, vcc, 1.0, v118, 1.0
	v_fma_f32 v122, -v119, v120, 1.0
	v_fmac_f32_e32 v120, v122, v120
	v_mul_f32_e32 v122, v121, v120
	v_fma_f32 v123, -v119, v122, v121
	v_fmac_f32_e32 v122, v123, v120
	v_fma_f32 v119, -v119, v122, v121
	v_div_fmas_f32 v119, v119, v120, v122
	v_div_fixup_f32 v119, v119, v118, 1.0
	v_mul_f32_e32 v118, 0xbfb8aa3b, v119
	v_pk_mul_f32 v[104:105], v[104:105], v[118:119] op_sel_hi:[1,0]
	v_pk_mul_f32 v[106:107], v[106:107], v[118:119] op_sel_hi:[1,0]
	v_pk_mul_f32 v[100:101], v[100:101], v[118:119] op_sel_hi:[1,0]
	v_pk_mul_f32 v[102:103], v[102:103], v[118:119] op_sel_hi:[1,0]
	v_exp_f32_e32 v104, v104
	v_exp_f32_e32 v105, v105
	v_exp_f32_e32 v106, v106
	v_exp_f32_e32 v107, v107
	v_exp_f32_e32 v100, v100
	v_exp_f32_e32 v101, v101
	v_exp_f32_e32 v102, v102
	v_exp_f32_e32 v103, v103
	v_pk_add_f32 v[104:105], v[104:105], 1.0 op_sel_hi:[1,0]
	v_pk_add_f32 v[106:107], v[106:107], 1.0 op_sel_hi:[1,0]
	v_pk_add_f32 v[100:101], v[100:101], 1.0 op_sel_hi:[1,0]
	v_pk_add_f32 v[102:103], v[102:103], 1.0 op_sel_hi:[1,0]
	v_rcp_f32_e32 v104, v104
	v_rcp_f32_e32 v105, v105
	v_rcp_f32_e32 v106, v106
	v_rcp_f32_e32 v107, v107
	v_rcp_f32_e32 v100, v100
	v_rcp_f32_e32 v101, v101
	v_rcp_f32_e32 v102, v102
	v_rcp_f32_e32 v103, v103
	v_mul_f32_e32 v120, v119, v119
	v_pk_mul_f32 v[104:105], v[120:121], v[104:105] op_sel_hi:[0,1]
	v_pk_mul_f32 v[106:107], v[120:121], v[106:107] op_sel_hi:[0,1]
	v_pk_mul_f32 v[100:101], v[120:121], v[100:101] op_sel_hi:[0,1]
	v_pk_mul_f32 v[102:103], v[120:121], v[102:103] op_sel_hi:[0,1]
	v_pk_mul_f32 v[104:105], v[112:113], v[104:105]
	v_pk_mul_f32 v[106:107], v[114:115], v[106:107]
	v_pk_mul_f32 v[108:109], v[108:109], v[100:101]
	v_pk_mul_f32 v[110:111], v[110:111], v[102:103]
	v_cvt_pk_bf16_f32 v100, v104, v105
	v_cvt_pk_bf16_f32 v101, v106, v107
	v_cvt_pk_bf16_f32 v102, v108, v109
	v_cvt_pk_bf16_f32 v103, v110, v111
	global_store_dwordx4 v[116:117], v[100:103], off
	s_nop 1
	v_mov_b32_e32 v100, v174
	v_mov_b32_e32 v101, v175
	s_nop 0
	v_mov_b32_e32 v103, v2
	v_mov_b32_e32 v102, v101
	v_lshlrev_b64 v[102:103], s13, v[102:103]
	v_min_u32_e32 v101, 1, v102
	v_or_b32_e32 v101, v103, v101
	v_cvt_f32_u32_e32 v101, v101
	v_cvt_f32_u32_e32 v100, v100
	v_ldexp_f32 v101, v101, s36
	v_fmac_f32_e32 v101, 0x2f800000, v100
	v_fmamk_f32 v100, v101, 0x3a000000, v205
	v_mul_f32_e32 v101, 0x4f800000, v100
	v_cmp_gt_f32_e32 vcc, s97, v100
	s_nop 1
	v_cndmask_b32_e32 v102, v100, v101, vcc
	v_sqrt_f32_e32 v103, v102
	v_add_u32_e32 v100, 32, v142
	v_mad_i64_i32 v[100:101], s[2:3], v100, s16, v[144:145]
	v_add_u32_e32 v104, -1, v103
	v_add_u32_e32 v105, 1, v103
	v_fma_f32 v106, -v104, v103, v102
	v_fma_f32 v107, -v105, v103, v102
	v_cmp_ge_f32_e64 s[2:3], 0, v106
	v_lshl_add_u64 v[100:101], v[100:101], 0, v[124:125]
	s_nop 0
	v_cndmask_b32_e64 v103, v103, v104, s[2:3]
	v_cmp_lt_f32_e64 s[2:3], 0, v107
	s_nop 1
	v_cndmask_b32_e64 v103, v103, v105, s[2:3]
	v_mul_f32_e32 v104, 0x37800000, v103
	v_cndmask_b32_e32 v103, v103, v104, vcc
	v_cmp_class_f32_e32 vcc, v102, v206
	s_nop 1
	v_cndmask_b32_e32 v102, v103, v102, vcc
	v_div_scale_f32 v103, s[2:3], v102, v102, 1.0
	v_rcp_f32_e32 v104, v103
	v_div_scale_f32 v105, vcc, 1.0, v102, 1.0
	v_fma_f32 v106, -v103, v104, 1.0
	v_fmac_f32_e32 v104, v106, v104
	v_mul_f32_e32 v106, v105, v104
	v_fma_f32 v107, -v103, v106, v105
	v_fmac_f32_e32 v106, v107, v104
	v_fma_f32 v103, -v103, v106, v105
	v_div_fmas_f32 v103, v103, v104, v106
	v_div_fixup_f32 v103, v103, v102, 1.0
	v_mul_f32_e32 v102, 0xbfb8aa3b, v103
	v_pk_mul_f32 v[88:89], v[88:89], v[102:103] op_sel_hi:[1,0]
	v_pk_mul_f32 v[90:91], v[90:91], v[102:103] op_sel_hi:[1,0]
	v_pk_mul_f32 v[84:85], v[84:85], v[102:103] op_sel_hi:[1,0]
	v_pk_mul_f32 v[86:87], v[86:87], v[102:103] op_sel_hi:[1,0]
	v_exp_f32_e32 v88, v88
	v_exp_f32_e32 v89, v89
	v_exp_f32_e32 v90, v90
	v_exp_f32_e32 v91, v91
	v_exp_f32_e32 v84, v84
	v_exp_f32_e32 v85, v85
	v_exp_f32_e32 v86, v86
	v_exp_f32_e32 v87, v87
	v_pk_add_f32 v[88:89], v[88:89], 1.0 op_sel_hi:[1,0]
	v_pk_add_f32 v[90:91], v[90:91], 1.0 op_sel_hi:[1,0]
	v_pk_add_f32 v[84:85], v[84:85], 1.0 op_sel_hi:[1,0]
	v_pk_add_f32 v[86:87], v[86:87], 1.0 op_sel_hi:[1,0]
	v_rcp_f32_e32 v88, v88
	v_rcp_f32_e32 v89, v89
	v_rcp_f32_e32 v90, v90
	v_rcp_f32_e32 v91, v91
	v_rcp_f32_e32 v84, v84
	v_rcp_f32_e32 v85, v85
	v_rcp_f32_e32 v86, v86
	v_rcp_f32_e32 v87, v87
	v_mul_f32_e32 v104, v103, v103
	v_pk_mul_f32 v[88:89], v[104:105], v[88:89] op_sel_hi:[0,1]
	v_pk_mul_f32 v[90:91], v[104:105], v[90:91] op_sel_hi:[0,1]
	v_pk_mul_f32 v[84:85], v[104:105], v[84:85] op_sel_hi:[0,1]
	v_pk_mul_f32 v[86:87], v[104:105], v[86:87] op_sel_hi:[0,1]
; __device__ __forceinline__ float ss_get(const ss_t* p) { const ss_t v = *p; return (float)(unsigned)(v >> 32) + (float)(unsigned)v * 2.3283064365386963e-10f; }
; __device__ __forceinline__ unsigned pkbf(float lo, float hi) { typedef float f2_t __attribute__((ext_vector_type(2))); typedef __bf16 b2_t __attribute__((ext_vector_type(2))); f2_t v = {lo, hi}; b2_t b = __builtin_convertvector(v, b2_t); return __builtin_bit_cast(unsigned, b); }
; __device__ __forceinline__ f32x2 swiglu_pk(f32x2 g, f32x2 u, float c1, float rs2) {
;     const f32x2 z = g * c1; f32x2 e; e.x = __builtin_amdgcn_exp2f(z.x); e.y = __builtin_amdgcn_exp2f(z.y);
;     const f32x2 d = e + 1.0f; f32x2 r; r.x = __builtin_amdgcn_rcpf(d.x); r.y = __builtin_amdgcn_rcpf(d.y);
;     return (g * u) * (r * rs2);
; }
;     __device__ __forceinline__ void operator()(const f32x4 (&acc)[2][2][4][2], const Unit& u, int wr, int wc, int fr, int fq) const {
;         int row0 = u.pm * BM + wr * 64 + fr; asm volatile("" : "+v"(row0));     const int col0 = u.pn * HALF + wc * 32 + 8 * fq;
; #pragma unroll
;         for (int ai = 0; ai < 2; ++ai)
; #pragma unroll
;             for (int m = 0; m < 4; ++m) { const int row = row0 + ai * HALF + m * 16; bf16_t* rowp = O + (size_t)row * ldc + col0;
;                 const float rs = 1.0f / sqrtf(ss_get(ssq + row) * (1.0f / 2048.f) + 1e-6f);
;                 const float c1 = -1.4426950408889634f * rs, rs2 = rs * rs;
;                 const f32x4 ga = acc[ai][0][m][0], gb = acc[ai][0][m][1], ua = acc[ai][1][m][0], ub = acc[ai][1][m][1];
;                 u32x4 w;
;                 { const f32x2 o = swiglu_pk((f32x2){ga[0], ga[1]}, (f32x2){ua[0], ua[1]}, c1, rs2); w.x = pkbf(o.x, o.y); }
;                 { const f32x2 o = swiglu_pk((f32x2){ga[2], ga[3]}, (f32x2){ua[2], ua[3]}, c1, rs2); w.y = pkbf(o.x, o.y); }
;                 { const f32x2 o = swiglu_pk((f32x2){gb[0], gb[1]}, (f32x2){ub[0], ub[1]}, c1, rs2); w.z = pkbf(o.x, o.y); }
;                 { const f32x2 o = swiglu_pk((f32x2){gb[2], gb[3]}, (f32x2){ub[2], ub[3]}, c1, rs2); w.w = pkbf(o.x, o.y); }
;                 *(u32x4*)rowp = w; }
	v_pk_mul_f32 v[88:89], v[96:97], v[88:89]
	v_pk_mul_f32 v[90:91], v[98:99], v[90:91]
	v_pk_mul_f32 v[92:93], v[92:93], v[84:85]
	v_pk_mul_f32 v[94:95], v[94:95], v[86:87]
	v_cvt_pk_bf16_f32 v84, v88, v89
	v_cvt_pk_bf16_f32 v85, v90, v91
	v_cvt_pk_bf16_f32 v86, v92, v93
	v_cvt_pk_bf16_f32 v87, v94, v95
	global_store_dwordx4 v[100:101], v[84:87], off
	s_nop 1
	v_mov_b32_e32 v84, v176
	v_mov_b32_e32 v85, v177
	s_nop 0
	v_mov_b32_e32 v87, v2
	v_mov_b32_e32 v86, v85
	v_lshlrev_b64 v[86:87], s13, v[86:87]
	v_min_u32_e32 v85, 1, v86
	v_or_b32_e32 v85, v87, v85
	v_cvt_f32_u32_e32 v85, v85
	v_cvt_f32_u32_e32 v84, v84
	v_ldexp_f32 v85, v85, s36
	v_fmac_f32_e32 v85, 0x2f800000, v84
	v_fmamk_f32 v84, v85, 0x3a000000, v205
	v_mul_f32_e32 v85, 0x4f800000, v84
	v_cmp_gt_f32_e32 vcc, s97, v84
	s_nop 1
	v_cndmask_b32_e32 v86, v84, v85, vcc
	v_sqrt_f32_e32 v87, v86
	v_add_u32_e32 v84, 48, v142
	v_mad_i64_i32 v[84:85], s[2:3], v84, s16, v[144:145]
	v_add_u32_e32 v88, -1, v87
	v_add_u32_e32 v89, 1, v87
	v_fma_f32 v90, -v88, v87, v86
	v_fma_f32 v91, -v89, v87, v86
	v_cmp_ge_f32_e64 s[2:3], 0, v90
	v_lshl_add_u64 v[84:85], v[84:85], 0, v[124:125]
	s_nop 0
	v_cndmask_b32_e64 v87, v87, v88, s[2:3]
	v_cmp_lt_f32_e64 s[2:3], 0, v91
	s_nop 1
	v_cndmask_b32_e64 v87, v87, v89, s[2:3]
	v_mul_f32_e32 v88, 0x37800000, v87
	v_cndmask_b32_e32 v87, v87, v88, vcc
	v_cmp_class_f32_e32 vcc, v86, v206
	s_nop 1
	v_cndmask_b32_e32 v86, v87, v86, vcc
	v_div_scale_f32 v87, s[2:3], v86, v86, 1.0
	v_rcp_f32_e32 v88, v87
	v_div_scale_f32 v89, vcc, 1.0, v86, 1.0
	v_fma_f32 v90, -v87, v88, 1.0
	v_fmac_f32_e32 v88, v90, v88
	v_mul_f32_e32 v90, v89, v88
	v_fma_f32 v91, -v87, v90, v89
	v_fmac_f32_e32 v90, v91, v88
	v_fma_f32 v87, -v87, v90, v89
	v_div_fmas_f32 v87, v87, v88, v90
	v_div_fixup_f32 v87, v87, v86, 1.0
	v_mul_f32_e32 v86, 0xbfb8aa3b, v87
	v_pk_mul_f32 v[72:73], v[72:73], v[86:87] op_sel_hi:[1,0]
	v_pk_mul_f32 v[74:75], v[74:75], v[86:87] op_sel_hi:[1,0]
	v_pk_mul_f32 v[68:69], v[68:69], v[86:87] op_sel_hi:[1,0]
	v_pk_mul_f32 v[70:71], v[70:71], v[86:87] op_sel_hi:[1,0]
	v_exp_f32_e32 v72, v72
	v_exp_f32_e32 v73, v73
	v_exp_f32_e32 v74, v74
	v_exp_f32_e32 v75, v75
	v_exp_f32_e32 v68, v68
	v_exp_f32_e32 v69, v69
	v_exp_f32_e32 v70, v70
	v_exp_f32_e32 v71, v71
	v_pk_add_f32 v[72:73], v[72:73], 1.0 op_sel_hi:[1,0]
	v_pk_add_f32 v[74:75], v[74:75], 1.0 op_sel_hi:[1,0]
	v_pk_add_f32 v[68:69], v[68:69], 1.0 op_sel_hi:[1,0]
	v_pk_add_f32 v[70:71], v[70:71], 1.0 op_sel_hi:[1,0]
	v_rcp_f32_e32 v72, v72
	v_rcp_f32_e32 v73, v73
	v_rcp_f32_e32 v74, v74
	v_rcp_f32_e32 v75, v75
	v_rcp_f32_e32 v68, v68
	v_rcp_f32_e32 v69, v69
	v_rcp_f32_e32 v70, v70
	v_rcp_f32_e32 v71, v71
	v_mul_f32_e32 v88, v87, v87
	v_pk_mul_f32 v[72:73], v[88:89], v[72:73] op_sel_hi:[0,1]
	v_pk_mul_f32 v[74:75], v[88:89], v[74:75] op_sel_hi:[0,1]
	v_pk_mul_f32 v[68:69], v[88:89], v[68:69] op_sel_hi:[0,1]
	v_pk_mul_f32 v[70:71], v[88:89], v[70:71] op_sel_hi:[0,1]
	v_pk_mul_f32 v[72:73], v[80:81], v[72:73]
	v_pk_mul_f32 v[74:75], v[82:83], v[74:75]
	v_pk_mul_f32 v[76:77], v[76:77], v[68:69]
	v_pk_mul_f32 v[78:79], v[78:79], v[70:71]
	v_cvt_pk_bf16_f32 v68, v72, v73
	v_cvt_pk_bf16_f32 v69, v74, v75
	v_cvt_pk_bf16_f32 v70, v76, v77
	v_cvt_pk_bf16_f32 v71, v78, v79
	global_store_dwordx4 v[84:85], v[68:71], off
	s_nop 1
	v_mov_b32_e32 v68, v178
	v_mov_b32_e32 v69, v179
	s_nop 0
	v_mov_b32_e32 v71, v2
	v_mov_b32_e32 v70, v69
	v_lshlrev_b64 v[70:71], s13, v[70:71]
	v_min_u32_e32 v69, 1, v70
	v_or_b32_e32 v69, v71, v69
	v_cvt_f32_u32_e32 v69, v69
	v_cvt_f32_u32_e32 v68, v68
	v_ldexp_f32 v69, v69, s36
	v_fmac_f32_e32 v69, 0x2f800000, v68
	v_fmamk_f32 v68, v69, 0x3a000000, v205
	v_mul_f32_e32 v69, 0x4f800000, v68
	v_cmp_gt_f32_e32 vcc, s97, v68
	s_nop 1
	v_cndmask_b32_e32 v70, v68, v69, vcc
	v_sqrt_f32_e32 v71, v70
	v_add_u32_e32 v68, 0x80, v142
	v_mad_i64_i32 v[68:69], s[2:3], v68, s16, v[144:145]
	v_add_u32_e32 v72, -1, v71
	v_add_u32_e32 v73, 1, v71
	v_fma_f32 v74, -v72, v71, v70
	v_fma_f32 v75, -v73, v71, v70
	v_cmp_ge_f32_e64 s[2:3], 0, v74
	v_lshl_add_u64 v[68:69], v[68:69], 0, v[124:125]
	s_nop 0
	v_cndmask_b32_e64 v71, v71, v72, s[2:3]
	v_cmp_lt_f32_e64 s[2:3], 0, v75
	s_nop 1
	v_cndmask_b32_e64 v71, v71, v73, s[2:3]
	v_mul_f32_e32 v72, 0x37800000, v71
	v_cndmask_b32_e32 v71, v71, v72, vcc
	v_cmp_class_f32_e32 vcc, v70, v206
	s_nop 1
	v_cndmask_b32_e32 v70, v71, v70, vcc
	v_div_scale_f32 v71, s[2:3], v70, v70, 1.0
	v_rcp_f32_e32 v72, v71
	v_div_scale_f32 v73, vcc, 1.0, v70, 1.0
	v_fma_f32 v74, -v71, v72, 1.0
	v_fmac_f32_e32 v72, v74, v72
	v_mul_f32_e32 v74, v73, v72
	v_fma_f32 v75, -v71, v74, v73
	v_fmac_f32_e32 v74, v75, v72
	v_fma_f32 v71, -v71, v74, v73
	v_div_fmas_f32 v71, v71, v72, v74
	v_div_fixup_f32 v71, v71, v70, 1.0
	v_mul_f32_e32 v70, 0xbfb8aa3b, v71
	v_pk_mul_f32 v[56:57], v[56:57], v[70:71] op_sel_hi:[1,0]
	v_pk_mul_f32 v[58:59], v[58:59], v[70:71] op_sel_hi:[1,0]
	v_pk_mul_f32 v[52:53], v[52:53], v[70:71] op_sel_hi:[1,0]
	v_pk_mul_f32 v[54:55], v[54:55], v[70:71] op_sel_hi:[1,0]
	v_exp_f32_e32 v56, v56
	v_exp_f32_e32 v57, v57
	v_exp_f32_e32 v58, v58
	v_exp_f32_e32 v59, v59
	v_exp_f32_e32 v52, v52
	v_exp_f32_e32 v53, v53
	v_exp_f32_e32 v54, v54
	v_exp_f32_e32 v55, v55
	v_pk_add_f32 v[56:57], v[56:57], 1.0 op_sel_hi:[1,0]
	v_pk_add_f32 v[58:59], v[58:59], 1.0 op_sel_hi:[1,0]
	v_pk_add_f32 v[52:53], v[52:53], 1.0 op_sel_hi:[1,0]
	v_pk_add_f32 v[54:55], v[54:55], 1.0 op_sel_hi:[1,0]
	v_rcp_f32_e32 v56, v56
	v_rcp_f32_e32 v57, v57
	v_rcp_f32_e32 v58, v58
	v_rcp_f32_e32 v59, v59
	v_rcp_f32_e32 v52, v52
	v_rcp_f32_e32 v53, v53
	v_rcp_f32_e32 v54, v54
	v_rcp_f32_e32 v55, v55
	v_mul_f32_e32 v72, v71, v71
; __device__ __forceinline__ float ss_get(const ss_t* p) { const ss_t v = *p; return (float)(unsigned)(v >> 32) + (float)(unsigned)v * 2.3283064365386963e-10f; }
; __device__ __forceinline__ unsigned pkbf(float lo, float hi) { typedef float f2_t __attribute__((ext_vector_type(2))); typedef __bf16 b2_t __attribute__((ext_vector_type(2))); f2_t v = {lo, hi}; b2_t b = __builtin_convertvector(v, b2_t); return __builtin_bit_cast(unsigned, b); }
; __device__ __forceinline__ f32x2 swiglu_pk(f32x2 g, f32x2 u, float c1, float rs2) {
;     const f32x2 z = g * c1; f32x2 e; e.x = __builtin_amdgcn_exp2f(z.x); e.y = __builtin_amdgcn_exp2f(z.y);
;     const f32x2 d = e + 1.0f; f32x2 r; r.x = __builtin_amdgcn_rcpf(d.x); r.y = __builtin_amdgcn_rcpf(d.y);
;     return (g * u) * (r * rs2);
; }
;     __device__ __forceinline__ void operator()(const f32x4 (&acc)[2][2][4][2], const Unit& u, int wr, int wc, int fr, int fq) const {
;         int row0 = u.pm * BM + wr * 64 + fr; asm volatile("" : "+v"(row0));     const int col0 = u.pn * HALF + wc * 32 + 8 * fq;
; #pragma unroll
;         for (int ai = 0; ai < 2; ++ai)
; #pragma unroll
;             for (int m = 0; m < 4; ++m) { const int row = row0 + ai * HALF + m * 16; bf16_t* rowp = O + (size_t)row * ldc + col0;
;                 const float rs = 1.0f / sqrtf(ss_get(ssq + row) * (1.0f / 2048.f) + 1e-6f);
;                 const float c1 = -1.4426950408889634f * rs, rs2 = rs * rs;
;                 const f32x4 ga = acc[ai][0][m][0], gb = acc[ai][0][m][1], ua = acc[ai][1][m][0], ub = acc[ai][1][m][1];
;                 u32x4 w;
;                 { const f32x2 o = swiglu_pk((f32x2){ga[0], ga[1]}, (f32x2){ua[0], ua[1]}, c1, rs2); w.x = pkbf(o.x, o.y); }
;                 { const f32x2 o = swiglu_pk((f32x2){ga[2], ga[3]}, (f32x2){ua[2], ua[3]}, c1, rs2); w.y = pkbf(o.x, o.y); }
;                 { const f32x2 o = swiglu_pk((f32x2){gb[0], gb[1]}, (f32x2){ub[0], ub[1]}, c1, rs2); w.z = pkbf(o.x, o.y); }
;                 { const f32x2 o = swiglu_pk((f32x2){gb[2], gb[3]}, (f32x2){ub[2], ub[3]}, c1, rs2); w.w = pkbf(o.x, o.y); }
;                 *(u32x4*)rowp = w; }
	v_pk_mul_f32 v[56:57], v[72:73], v[56:57] op_sel_hi:[0,1]
	v_pk_mul_f32 v[58:59], v[72:73], v[58:59] op_sel_hi:[0,1]
	v_pk_mul_f32 v[52:53], v[72:73], v[52:53] op_sel_hi:[0,1]
	v_pk_mul_f32 v[54:55], v[72:73], v[54:55] op_sel_hi:[0,1]
	v_pk_mul_f32 v[56:57], v[64:65], v[56:57]
	v_pk_mul_f32 v[58:59], v[66:67], v[58:59]
	v_pk_mul_f32 v[60:61], v[60:61], v[52:53]
	v_pk_mul_f32 v[62:63], v[62:63], v[54:55]
	v_cvt_pk_bf16_f32 v52, v56, v57
	v_cvt_pk_bf16_f32 v53, v58, v59
	v_cvt_pk_bf16_f32 v54, v60, v61
	v_cvt_pk_bf16_f32 v55, v62, v63
	global_store_dwordx4 v[68:69], v[52:55], off
	s_nop 1
	v_mov_b32_e32 v52, v180
	v_mov_b32_e32 v53, v181
	s_nop 0
	v_mov_b32_e32 v55, v2
	v_mov_b32_e32 v54, v53
	v_lshlrev_b64 v[54:55], s13, v[54:55]
	v_min_u32_e32 v53, 1, v54
	v_or_b32_e32 v53, v55, v53
	v_cvt_f32_u32_e32 v53, v53
	v_cvt_f32_u32_e32 v52, v52
	v_ldexp_f32 v53, v53, s36
	v_fmac_f32_e32 v53, 0x2f800000, v52
	v_fmamk_f32 v52, v53, 0x3a000000, v205
	v_mul_f32_e32 v53, 0x4f800000, v52
	v_cmp_gt_f32_e32 vcc, s97, v52
	s_nop 1
	v_cndmask_b32_e32 v54, v52, v53, vcc
	v_sqrt_f32_e32 v55, v54
	v_add_u32_e32 v52, 0x90, v142
	v_mad_i64_i32 v[52:53], s[2:3], v52, s16, v[144:145]
	v_add_u32_e32 v56, -1, v55
	v_add_u32_e32 v57, 1, v55
	v_fma_f32 v58, -v56, v55, v54
	v_fma_f32 v59, -v57, v55, v54
	v_cmp_ge_f32_e64 s[2:3], 0, v58
	v_lshl_add_u64 v[52:53], v[52:53], 0, v[124:125]
	s_nop 0
	v_cndmask_b32_e64 v55, v55, v56, s[2:3]
	v_cmp_lt_f32_e64 s[2:3], 0, v59
	s_nop 1
	v_cndmask_b32_e64 v55, v55, v57, s[2:3]
	v_mul_f32_e32 v56, 0x37800000, v55
	v_cndmask_b32_e32 v55, v55, v56, vcc
	v_cmp_class_f32_e32 vcc, v54, v206
	s_nop 1
	v_cndmask_b32_e32 v54, v55, v54, vcc
	v_div_scale_f32 v55, s[2:3], v54, v54, 1.0
	v_rcp_f32_e32 v56, v55
	v_div_scale_f32 v57, vcc, 1.0, v54, 1.0
	v_fma_f32 v58, -v55, v56, 1.0
	v_fmac_f32_e32 v56, v58, v56
	v_mul_f32_e32 v58, v57, v56
	v_fma_f32 v59, -v55, v58, v57
	v_fmac_f32_e32 v58, v59, v56
	v_fma_f32 v55, -v55, v58, v57
	v_div_fmas_f32 v55, v55, v56, v58
	v_div_fixup_f32 v55, v55, v54, 1.0
	v_mul_f32_e32 v54, 0xbfb8aa3b, v55
	v_pk_mul_f32 v[40:41], v[40:41], v[54:55] op_sel_hi:[1,0]
	v_pk_mul_f32 v[42:43], v[42:43], v[54:55] op_sel_hi:[1,0]
	v_pk_mul_f32 v[36:37], v[36:37], v[54:55] op_sel_hi:[1,0]
	v_pk_mul_f32 v[38:39], v[38:39], v[54:55] op_sel_hi:[1,0]
	v_exp_f32_e32 v40, v40
	v_exp_f32_e32 v41, v41
	v_exp_f32_e32 v42, v42
	v_exp_f32_e32 v43, v43
	v_exp_f32_e32 v36, v36
	v_exp_f32_e32 v37, v37
	v_exp_f32_e32 v38, v38
	v_exp_f32_e32 v39, v39
	v_pk_add_f32 v[40:41], v[40:41], 1.0 op_sel_hi:[1,0]
	v_pk_add_f32 v[42:43], v[42:43], 1.0 op_sel_hi:[1,0]
	v_pk_add_f32 v[36:37], v[36:37], 1.0 op_sel_hi:[1,0]
	v_pk_add_f32 v[38:39], v[38:39], 1.0 op_sel_hi:[1,0]
	v_rcp_f32_e32 v40, v40
	v_rcp_f32_e32 v41, v41
	v_rcp_f32_e32 v42, v42
	v_rcp_f32_e32 v43, v43
	v_rcp_f32_e32 v36, v36
	v_rcp_f32_e32 v37, v37
	v_rcp_f32_e32 v38, v38
	v_rcp_f32_e32 v39, v39
	v_mul_f32_e32 v56, v55, v55
	v_pk_mul_f32 v[40:41], v[56:57], v[40:41] op_sel_hi:[0,1]
	v_pk_mul_f32 v[42:43], v[56:57], v[42:43] op_sel_hi:[0,1]
	v_pk_mul_f32 v[36:37], v[56:57], v[36:37] op_sel_hi:[0,1]
	v_pk_mul_f32 v[38:39], v[56:57], v[38:39] op_sel_hi:[0,1]
	v_pk_mul_f32 v[40:41], v[48:49], v[40:41]
	v_pk_mul_f32 v[42:43], v[50:51], v[42:43]
	v_pk_mul_f32 v[44:45], v[44:45], v[36:37]
	v_pk_mul_f32 v[46:47], v[46:47], v[38:39]
	v_cvt_pk_bf16_f32 v36, v40, v41
	v_cvt_pk_bf16_f32 v37, v42, v43
	v_cvt_pk_bf16_f32 v38, v44, v45
	v_cvt_pk_bf16_f32 v39, v46, v47
	global_store_dwordx4 v[52:53], v[36:39], off
	s_nop 1
	v_mov_b32_e32 v36, v182
	v_mov_b32_e32 v37, v183
	s_nop 0
	v_mov_b32_e32 v39, v2
	v_mov_b32_e32 v38, v37
	v_lshlrev_b64 v[38:39], s13, v[38:39]
	v_min_u32_e32 v37, 1, v38
	v_or_b32_e32 v37, v39, v37
	v_cvt_f32_u32_e32 v37, v37
	v_cvt_f32_u32_e32 v36, v36
	v_ldexp_f32 v37, v37, s36
	v_fmac_f32_e32 v37, 0x2f800000, v36
	v_fmamk_f32 v36, v37, 0x3a000000, v205
	v_mul_f32_e32 v37, 0x4f800000, v36
	v_cmp_gt_f32_e32 vcc, s97, v36
	s_nop 1
	v_cndmask_b32_e32 v38, v36, v37, vcc
	v_sqrt_f32_e32 v39, v38
	v_add_u32_e32 v36, 0xa0, v142
	v_mad_i64_i32 v[36:37], s[2:3], v36, s16, v[144:145]
	v_add_u32_e32 v40, -1, v39
	v_add_u32_e32 v41, 1, v39
	v_fma_f32 v42, -v40, v39, v38
	v_fma_f32 v43, -v41, v39, v38
	v_cmp_ge_f32_e64 s[2:3], 0, v42
	v_lshl_add_u64 v[36:37], v[36:37], 0, v[124:125]
	s_nop 0
	v_cndmask_b32_e64 v39, v39, v40, s[2:3]
	v_cmp_lt_f32_e64 s[2:3], 0, v43
	s_nop 1
	v_cndmask_b32_e64 v39, v39, v41, s[2:3]
	v_mul_f32_e32 v40, 0x37800000, v39
	v_cndmask_b32_e32 v39, v39, v40, vcc
	v_cmp_class_f32_e32 vcc, v38, v206
	s_nop 1
	v_cndmask_b32_e32 v38, v39, v38, vcc
	v_div_scale_f32 v39, s[2:3], v38, v38, 1.0
	v_rcp_f32_e32 v40, v39
	v_div_scale_f32 v41, vcc, 1.0, v38, 1.0
	v_fma_f32 v42, -v39, v40, 1.0
; __device__ __forceinline__ f32x2 swiglu_pk(f32x2 g, f32x2 u, float c1, float rs2) {
;     const f32x2 z = g * c1; f32x2 e; e.x = __builtin_amdgcn_exp2f(z.x); e.y = __builtin_amdgcn_exp2f(z.y);
;     const f32x2 d = e + 1.0f; f32x2 r; r.x = __builtin_amdgcn_rcpf(d.x); r.y = __builtin_amdgcn_rcpf(d.y);
;     return (g * u) * (r * rs2);
; }
;     __device__ __forceinline__ void operator()(const f32x4 (&acc)[2][2][4][2], const Unit& u, int wr, int wc, int fr, int fq) const {
;         int row0 = u.pm * BM + wr * 64 + fr; asm volatile("" : "+v"(row0));     const int col0 = u.pn * HALF + wc * 32 + 8 * fq;
; #pragma unroll
;         for (int ai = 0; ai < 2; ++ai)
; #pragma unroll
;             for (int m = 0; m < 4; ++m) { const int row = row0 + ai * HALF + m * 16; bf16_t* rowp = O + (size_t)row * ldc + col0;
;                 const float rs = 1.0f / sqrtf(ss_get(ssq + row) * (1.0f / 2048.f) + 1e-6f);
;                 const float c1 = -1.4426950408889634f * rs, rs2 = rs * rs;
;                 const f32x4 ga = acc[ai][0][m][0], gb = acc[ai][0][m][1], ua = acc[ai][1][m][0], ub = acc[ai][1][m][1];
;                 u32x4 w;
;                 { const f32x2 o = swiglu_pk((f32x2){ga[0], ga[1]}, (f32x2){ua[0], ua[1]}, c1, rs2); w.x = pkbf(o.x, o.y); }
;                 { const f32x2 o = swiglu_pk((f32x2){ga[2], ga[3]}, (f32x2){ua[2], ua[3]}, c1, rs2); w.y = pkbf(o.x, o.y); }
;                 { const f32x2 o = swiglu_pk((f32x2){gb[0], gb[1]}, (f32x2){ub[0], ub[1]}, c1, rs2); w.z = pkbf(o.x, o.y); }
;                 { const f32x2 o = swiglu_pk((f32x2){gb[2], gb[3]}, (f32x2){ub[2], ub[3]}, c1, rs2); w.w = pkbf(o.x, o.y); }
;                 *(u32x4*)rowp = w; }
; template <class Epi, class Sched, bool ALIGN_EPI = false, bool SP2 = false>
; __device__ __forceinline__ void gemm_phase(PG8_LAS unsigned char* lds, const Gemm g, const Sched& S, const Epi& E) {
;     ...
;         if constexpr (!Epi::AFTER_DRAIN) { E(acc, cur, wr, wc, fr, fq); S.done(cur); }
;         if (!has_next) break;
; #pragma unroll
;         for (int a = 0; a < 2; ++a)
; #pragma unroll
;             for (int b = 0; b < 2; ++b)
; #pragma unroll
;                 for (int m = 0; m < 4; ++m)
; #pragma unroll
;                     for (int n = 0; n < 2; ++n) acc[a][b][m][n] = (f32x4){0.f, 0.f, 0.f, 0.f};
;         cur = nxt; cA = nA; cB = nB; ++ui;
;         if constexpr (ALIGN_EPI) { if (wr == 1) PG8_BAR; }
	v_fmac_f32_e32 v40, v42, v40
	v_mul_f32_e32 v42, v41, v40
	v_fma_f32 v43, -v39, v42, v41
	v_fmac_f32_e32 v42, v43, v40
	v_fma_f32 v39, -v39, v42, v41
	v_div_fmas_f32 v39, v39, v40, v42
	v_div_fixup_f32 v39, v39, v38, 1.0
	v_mul_f32_e32 v38, 0xbfb8aa3b, v39
	v_pk_mul_f32 v[24:25], v[24:25], v[38:39] op_sel_hi:[1,0]
	v_pk_mul_f32 v[26:27], v[26:27], v[38:39] op_sel_hi:[1,0]
	v_pk_mul_f32 v[20:21], v[20:21], v[38:39] op_sel_hi:[1,0]
	v_pk_mul_f32 v[22:23], v[22:23], v[38:39] op_sel_hi:[1,0]
	v_exp_f32_e32 v24, v24
	v_exp_f32_e32 v25, v25
	v_exp_f32_e32 v26, v26
	v_exp_f32_e32 v27, v27
	v_exp_f32_e32 v20, v20
	v_exp_f32_e32 v21, v21
	v_exp_f32_e32 v22, v22
	v_exp_f32_e32 v23, v23
	v_pk_add_f32 v[24:25], v[24:25], 1.0 op_sel_hi:[1,0]
	v_pk_add_f32 v[26:27], v[26:27], 1.0 op_sel_hi:[1,0]
	v_pk_add_f32 v[20:21], v[20:21], 1.0 op_sel_hi:[1,0]
	v_pk_add_f32 v[22:23], v[22:23], 1.0 op_sel_hi:[1,0]
	v_rcp_f32_e32 v24, v24
	v_rcp_f32_e32 v25, v25
	v_rcp_f32_e32 v26, v26
	v_rcp_f32_e32 v27, v27
	v_rcp_f32_e32 v20, v20
	v_rcp_f32_e32 v21, v21
	v_rcp_f32_e32 v22, v22
	v_rcp_f32_e32 v23, v23
	v_mul_f32_e32 v40, v39, v39
	v_pk_mul_f32 v[24:25], v[40:41], v[24:25] op_sel_hi:[0,1]
	v_pk_mul_f32 v[26:27], v[40:41], v[26:27] op_sel_hi:[0,1]
	v_pk_mul_f32 v[20:21], v[40:41], v[20:21] op_sel_hi:[0,1]
	v_pk_mul_f32 v[22:23], v[40:41], v[22:23] op_sel_hi:[0,1]
	v_pk_mul_f32 v[24:25], v[32:33], v[24:25]
	v_pk_mul_f32 v[26:27], v[34:35], v[26:27]
	v_pk_mul_f32 v[28:29], v[28:29], v[20:21]
	v_pk_mul_f32 v[30:31], v[30:31], v[22:23]
	v_cvt_pk_bf16_f32 v20, v24, v25
	v_cvt_pk_bf16_f32 v21, v26, v27
	v_cvt_pk_bf16_f32 v22, v28, v29
	v_cvt_pk_bf16_f32 v23, v30, v31
	global_store_dwordx4 v[36:37], v[20:23], off
	s_nop 1
	v_mov_b32_e32 v20, v184
	v_mov_b32_e32 v21, v185
	s_nop 0
	v_mov_b32_e32 v23, v2
	v_mov_b32_e32 v22, v21
	v_lshlrev_b64 v[22:23], s13, v[22:23]
	v_min_u32_e32 v21, 1, v22
	v_or_b32_e32 v21, v23, v21
	v_cvt_f32_u32_e32 v21, v21
	v_cvt_f32_u32_e32 v20, v20
	v_ldexp_f32 v21, v21, s36
	v_fmac_f32_e32 v21, 0x2f800000, v20
	v_fmamk_f32 v20, v21, 0x3a000000, v205
	v_mul_f32_e32 v21, 0x4f800000, v20
	v_cmp_gt_f32_e32 vcc, s97, v20
	s_nop 1
	v_cndmask_b32_e32 v22, v20, v21, vcc
	v_sqrt_f32_e32 v23, v22
	v_add_u32_e32 v20, 0xb0, v142
	v_mad_i64_i32 v[20:21], s[2:3], v20, s16, v[144:145]
	v_add_u32_e32 v24, -1, v23
	v_add_u32_e32 v25, 1, v23
	v_fma_f32 v26, -v24, v23, v22
	v_fma_f32 v27, -v25, v23, v22
	v_cmp_ge_f32_e64 s[2:3], 0, v26
	v_lshl_add_u64 v[20:21], v[20:21], 0, v[124:125]
	s_nop 0
	v_cndmask_b32_e64 v23, v23, v24, s[2:3]
	v_cmp_lt_f32_e64 s[2:3], 0, v27
	s_nop 1
	v_cndmask_b32_e64 v23, v23, v25, s[2:3]
	v_mul_f32_e32 v24, 0x37800000, v23
	v_cndmask_b32_e32 v23, v23, v24, vcc
	v_cmp_class_f32_e32 vcc, v22, v206
	s_nop 1
	v_cndmask_b32_e32 v22, v23, v22, vcc
	v_div_scale_f32 v23, s[2:3], v22, v22, 1.0
	v_rcp_f32_e32 v24, v23
	v_div_scale_f32 v25, vcc, 1.0, v22, 1.0
	s_mov_b64 s[2:3], -1
	v_fma_f32 v26, -v23, v24, 1.0
	v_fmac_f32_e32 v24, v26, v24
	v_mul_f32_e32 v26, v25, v24
	v_fma_f32 v27, -v23, v26, v25
	v_fmac_f32_e32 v26, v27, v24
	v_fma_f32 v23, -v23, v26, v25
	v_div_fmas_f32 v23, v23, v24, v26
	v_div_fixup_f32 v23, v23, v22, 1.0
	v_mul_f32_e32 v22, 0xbfb8aa3b, v23
	v_pk_mul_f32 v[8:9], v[8:9], v[22:23] op_sel_hi:[1,0]
	v_pk_mul_f32 v[10:11], v[10:11], v[22:23] op_sel_hi:[1,0]
	v_pk_mul_f32 v[4:5], v[4:5], v[22:23] op_sel_hi:[1,0]
	v_pk_mul_f32 v[6:7], v[6:7], v[22:23] op_sel_hi:[1,0]
	v_exp_f32_e32 v8, v8
	v_exp_f32_e32 v9, v9
	v_exp_f32_e32 v10, v10
	v_exp_f32_e32 v11, v11
	v_exp_f32_e32 v4, v4
	v_exp_f32_e32 v5, v5
	v_exp_f32_e32 v6, v6
	v_exp_f32_e32 v7, v7
	v_pk_add_f32 v[8:9], v[8:9], 1.0 op_sel_hi:[1,0]
	v_pk_add_f32 v[10:11], v[10:11], 1.0 op_sel_hi:[1,0]
	v_pk_add_f32 v[4:5], v[4:5], 1.0 op_sel_hi:[1,0]
	v_pk_add_f32 v[6:7], v[6:7], 1.0 op_sel_hi:[1,0]
	v_rcp_f32_e32 v8, v8
	v_rcp_f32_e32 v9, v9
	v_rcp_f32_e32 v10, v10
	v_rcp_f32_e32 v11, v11
	v_rcp_f32_e32 v4, v4
	v_rcp_f32_e32 v5, v5
	v_rcp_f32_e32 v6, v6
	v_rcp_f32_e32 v7, v7
	v_mul_f32_e32 v24, v23, v23
	v_pk_mul_f32 v[8:9], v[24:25], v[8:9] op_sel_hi:[0,1]
	v_pk_mul_f32 v[10:11], v[24:25], v[10:11] op_sel_hi:[0,1]
	v_pk_mul_f32 v[4:5], v[24:25], v[4:5] op_sel_hi:[0,1]
	v_pk_mul_f32 v[6:7], v[24:25], v[6:7] op_sel_hi:[0,1]
	v_pk_mul_f32 v[8:9], v[16:17], v[8:9]
	v_pk_mul_f32 v[10:11], v[18:19], v[10:11]
	v_pk_mul_f32 v[12:13], v[12:13], v[4:5]
	v_pk_mul_f32 v[14:15], v[14:15], v[6:7]
	s_andn2_b64 vcc, exec, s[14:15]
	v_cvt_pk_bf16_f32 v4, v8, v9
	v_cvt_pk_bf16_f32 v5, v10, v11
	v_cvt_pk_bf16_f32 v6, v12, v13
	v_cvt_pk_bf16_f32 v7, v14, v15
	global_store_dwordx4 v[20:21], v[4:7], off
	s_cbranch_vccnz .LBB0_1049
	s_andn2_b64 vcc, exec, s[8:9]
	s_cbranch_vccnz .LBB0_1048
	s_barrier
	s_branch .LBB0_1048
